# v72 plus nt hint on the once-read f32 weight loads of the weight-conversion code (P0 parts 0-2)
# speedup vs baseline: 1.0005x; 1.0005x over previous
; __device__ __forceinline__ unsigned pk2(float lo, float hi) { f32x2 v = {lo, hi}; bf16x2_t b = __builtin_convertvector(v, bf16x2_t); return __builtin_bit_cast(unsigned, b); }
; __device__ __forceinline__ void p0_cvt_item(const float* W, int K, int N, bf16_t* WT, int row_off, const float* gain, int item, int lane) {
;     const int nblk = N / 256, kb = item / nblk, nb = item % nblk, k0 = 16 * kb, n0 = 256 * nb + 4 * lane;
; #pragma unroll
;     for (int kk = 0; kk < 16; kk += 8) {
;         f32x4 v[8];
; #pragma unroll
;         for (int j = 0; j < 8; ++j) { const float gk = gain ? gain[k0 + kk + j] : 1.f; v[j] = *(const f32x4*)(W + (size_t)(k0 + kk + j) * N + n0) * gk; }
; #pragma unroll
;         for (int c = 0; c < 4; ++c) { u32x4 o; o.x = pk2(v[0][c], v[1][c]); o.y = pk2(v[2][c], v[3][c]); o.z = pk2(v[4][c], v[5][c]); o.w = pk2(v[6][c], v[7][c]);
;             *(u32x4*)(WT + (size_t)(row_off + n0 + c) * K + k0 + kk) = o; }
;     }
.LBB0_22:
	v_or_b32_e32 v36, 15, v36
	v_ashrrev_i32_e32 v37, 31, v36
	v_lshlrev_b64 v[36:37], 14, v[36:37]
	v_lshl_add_u64 v[36:37], v[38:39], 0, v[36:37]
	global_load_dwordx4 v[36:39], v[36:37], off nt
	s_waitcnt vmcnt(2)
	v_pk_mul_f32 v[22:23], v[22:23], v[58:59] op_sel_hi:[1,0]
	v_pk_mul_f32 v[18:19], v[18:19], v[60:61] op_sel_hi:[1,0]
	v_pk_mul_f32 v[14:15], v[14:15], v[52:53] op_sel_hi:[1,0]
	v_pk_mul_f32 v[12:13], v[12:13], v[52:53] op_sel_hi:[1,0]
	v_pk_mul_f32 v[10:11], v[10:11], v[54:55] op_sel_hi:[1,0]
	v_pk_mul_f32 v[8:9], v[8:9], v[54:55] op_sel_hi:[1,0]
	v_pk_mul_f32 v[4:5], v[4:5], v[32:33] op_sel_hi:[1,0]
	v_pk_mul_f32 v[78:79], v[2:3], v[50:51] op_sel_hi:[1,0]
	v_pk_mul_f32 v[2:3], v[0:1], v[50:51] op_sel_hi:[1,0]
	s_waitcnt vmcnt(1)
	v_pk_mul_f32 v[24:25], v[24:25], v[62:63] op_sel_hi:[1,0]
	v_pk_mul_f32 v[20:21], v[20:21], v[58:59] op_sel_hi:[1,0]
	v_pk_mul_f32 v[16:17], v[16:17], v[60:61] op_sel_hi:[1,0]
	v_cvt_pk_bf16_f32 v0, v2, v4
	v_cvt_pk_bf16_f32 v4, v3, v5
	v_cvt_pk_bf16_f32 v5, v9, v13
	v_cvt_pk_bf16_f32 v9, v10, v14
	v_cvt_pk_bf16_f32 v10, v18, v22
	v_cvt_pk_bf16_f32 v14, v19, v23
	v_pk_mul_f32 v[26:27], v[26:27], v[62:63] op_sel_hi:[1,0]
	v_pk_mul_f32 v[40:41], v[6:7], v[32:33] op_sel_hi:[1,0]
	v_cvt_pk_bf16_f32 v1, v8, v12
	v_cvt_pk_bf16_f32 v2, v16, v20
	v_cvt_pk_bf16_f32 v6, v17, v21
	v_cvt_pk_bf16_f32 v8, v78, v40
	v_cvt_pk_bf16_f32 v12, v79, v41
	v_cvt_pk_bf16_f32 v13, v11, v15
	s_waitcnt vmcnt(0)
	v_pk_mul_f32 v[18:19], v[36:37], v[56:57] op_sel_hi:[1,0]
	v_pk_mul_f32 v[16:17], v[38:39], v[56:57] op_sel_hi:[1,0]
	v_cvt_pk_bf16_f32 v3, v24, v18
	v_cvt_pk_bf16_f32 v7, v25, v19
	v_cvt_pk_bf16_f32 v11, v26, v16
	v_cvt_pk_bf16_f32 v15, v27, v17
	global_store_dwordx4 v[44:45], v[0:3], off offset:16
	global_store_dwordx4 v[46:47], v[4:7], off offset:16
	global_store_dwordx4 v[48:49], v[8:11], off offset:16
	global_store_dwordx4 v[42:43], v[12:15], off offset:16

; __device__ __forceinline__ void p0_cvt_item(const float* W, int K, int N, bf16_t* WT, int row_off, const float* gain, int item, int lane) {
;     const int nblk = N / 256, kb = item / nblk, nb = item % nblk, k0 = 16 * kb, n0 = 256 * nb + 4 * lane;
; #pragma unroll
;     for (int kk = 0; kk < 16; kk += 8) {
;         f32x4 v[8];
; #pragma unroll
; __device__ __forceinline__ void p0_phase(const Args& a, LAS unsigned char* lds, int G, int wg, int part, bool split) {
;     ...
;     for (int it = it_lo + gw; it < it_hi; it += NGW) {
;         int r = it;
;         if (r < 2 * I_AIN) { const int j = r / I_AIN; r -= j * I_AIN;
;             p0_cvt_item(a.in[4] + (size_t)j * DM * 4096, DM, 4096, (bf16_t*)(ws + WS_AWIN) + (size_t)j * 4096 * DM, 0, norm_mix + (3 * j) * DM, r, lane); continue; } r -= 2 * I_AIN;
;         if (r < I_SQ) { p0_cvt_item(a.in[7], DM, DM, (bf16_t*)(ws + WS_AWOUT), 0, nullptr, r, lane); continue; } r -= I_SQ;
;         if (r < I_QKV) { p0_cvt_item(a.in[8], DM, 3072, (bf16_t*)(ws + WS_BQKV), 0, norm_mix + 1 * DM, r, lane); continue; } r -= I_QKV;
;         if (r < I_SQ) { p0_cvt_item(a.in[9], DM, DM, (bf16_t*)(ws + WS_BOUT), 0, nullptr, r, lane); continue; } r -= I_SQ;
;         if (r < 4 * I_CW) { const int g = r / I_CW; r -= g * I_CW;
;             p0_cvt_item(a.in[11] + (size_t)g * 256 * 256, 256, 256, (bf16_t*)(ws + WS_CW), g * 256, nullptr, r, lane); continue; } r -= 4 * I_CW;
;         if (r < 3 * I_W1) { const int j = r / I_W1; r -= j * I_W1;
;             p0_cvt_item(a.in[13] + (size_t)j * DM * FF, DM, FF, (bf16_t*)(ws + WS_W1) + (size_t)j * FF * DM, 0, norm_mlp + j * DM, r, lane); continue; } r -= 3 * I_W1;
;         if (r < 3 * I_W2) { const int j = r / I_W2; r -= j * I_W2;
;             p0_cvt_item(a.in[14] + (size_t)j * FF * DM, FF, DM, (bf16_t*)(ws + WS_W2) + (size_t)j * DM * FF, 0, nullptr, r, lane); continue; } r -= 3 * I_W2;
;         if (r < I_SQ) { p0_cvt_item(a.in[7] + (size_t)DM * DM, DM, DM, (bf16_t*)(ws + WS_AWOUT) + (size_t)DM * DM, 0, nullptr, r, lane); continue; } r -= I_SQ;
;         if (r < I_W1) { p0_cvt_item(a.in[13] + (size_t)3 * DM * FF, DM, FF, (bf16_t*)(ws + WS_W1) + (size_t)3 * FF * DM, 0, norm_mlp + 3 * DM, r, lane); continue; } r -= I_W1;
;         p0_cvt_item(a.in[14] + (size_t)3 * FF * DM, FF, DM, (bf16_t*)(ws + WS_W2) + (size_t)3 * DM * FF, 0, nullptr, r, lane);
.LBB0_24:
	v_add_u32_e32 v0, 0xffff2640, v57
	s_movk_i32 s4, 0x7ff
	v_cmp_lt_i32_e32 vcc, s4, v0
	s_and_saveexec_b64 s[4:5], vcc
	s_xor_b64 s[52:53], exec, s[4:5]
	s_cbranch_execz .LBB0_90
	s_movk_i32 s4, 0x8ff
	v_cmp_lt_u32_e32 vcc, s4, v0
	s_and_saveexec_b64 s[4:5], vcc
	s_xor_b64 s[54:55], exec, s[4:5]
	s_cbranch_execz .LBB0_87
	s_movk_i32 s4, 0xbff
	v_cmp_lt_u32_e32 vcc, s4, v0
	s_and_saveexec_b64 s[4:5], vcc
	s_xor_b64 s[56:57], exec, s[4:5]
	s_cbranch_execz .LBB0_84
	s_movk_i32 s4, 0xcff
	v_cmp_lt_u32_e32 vcc, s4, v0
	s_and_saveexec_b64 s[4:5], vcc
	s_xor_b64 s[58:59], exec, s[4:5]
	s_cbranch_execz .LBB0_81
	s_movk_i32 s4, 0xd3f
	v_cmp_lt_u32_e32 vcc, s4, v0
	s_and_saveexec_b64 s[4:5], vcc
	s_xor_b64 s[60:61], exec, s[4:5]
	s_cbranch_execz .LBB0_78
	s_movk_i32 s4, 0x193f
	v_cmp_lt_u32_e32 vcc, s4, v0
	s_and_saveexec_b64 s[4:5], vcc
	s_xor_b64 s[4:5], exec, s[4:5]
	s_cbranch_execz .LBB0_43
	v_writelane_b32 v252, s64, 34
	s_movk_i32 s62, 0x253f
	v_cmp_lt_u32_e32 vcc, s62, v0
	v_writelane_b32 v252, s65, 35
	s_and_saveexec_b64 s[62:63], vcc
	s_xor_b64 s[62:63], exec, s[62:63]
	s_cbranch_execz .LBB0_40
	s_movk_i32 s64, 0x263f
	s_mov_b64 s[10:11], s[66:67]
	v_cmp_lt_u32_e32 vcc, s64, v0
	s_and_saveexec_b64 s[64:65], vcc
	s_xor_b64 s[64:65], exec, s[64:65]
	s_cbranch_execz .LBB0_37
	s_movk_i32 s66, 0x2a3f
	s_mov_b64 s[8:9], s[82:83]
	v_cmp_lt_u32_e32 vcc, s66, v0
	s_and_saveexec_b64 s[66:67], vcc
	s_xor_b64 s[66:67], exec, s[66:67]
	s_cbranch_execz .LBB0_34
	v_and_or_b32 v52, v31, s72, v28
	v_and_b32_e32 v50, 0x7ffffff0, v29
	v_lshlrev_b32_e32 v32, 2, v52
	v_lshl_add_u64 v[48:49], s[44:45], 0, v[32:33]
	v_add_u32_e32 v32, 0xffff5701, v50
	v_lshlrev_b64 v[2:3], 12, v[32:33]
	v_add_u32_e32 v32, 0xffff5702, v50
	v_lshlrev_b64 v[8:9], 12, v[32:33]
	v_add_u32_e32 v32, 0xffff5703, v50
	v_lshlrev_b64 v[10:11], 12, v[32:33]
	v_add_u32_e32 v32, 0xffff5704, v50
	v_lshlrev_b64 v[16:17], 12, v[32:33]
	v_add_u32_e32 v32, 0xffff5705, v50
	v_lshlrev_b64 v[18:19], 12, v[32:33]
	v_add_u32_e32 v32, 0xffff5706, v50
	v_add_u32_e32 v40, 0xffff5700, v50
	v_mov_b32_e32 v41, v33
	v_lshlrev_b64 v[24:25], 12, v[32:33]
	v_add_u32_e32 v32, 0xffff5707, v50
	v_lshlrev_b64 v[0:1], 12, v[40:41]
	v_lshlrev_b64 v[26:27], 12, v[32:33]
	v_lshl_add_u64 v[0:1], v[48:49], 0, v[0:1]
	v_lshl_add_u64 v[4:5], v[48:49], 0, v[2:3]
	v_lshl_add_u64 v[8:9], v[48:49], 0, v[8:9]
	v_lshl_add_u64 v[12:13], v[48:49], 0, v[10:11]
	v_lshl_add_u64 v[16:17], v[48:49], 0, v[16:17]
	v_lshl_add_u64 v[20:21], v[48:49], 0, v[18:19]
	v_lshl_add_u64 v[24:25], v[48:49], 0, v[24:25]
	v_lshl_add_u64 v[36:37], v[48:49], 0, v[26:27]
	global_load_dwordx4 v[0:3], v[0:1], off nt
	s_nop 0
	global_load_dwordx4 v[4:7], v[4:5], off nt
	s_nop 0
	global_load_dwordx4 v[8:11], v[8:9], off nt
	s_nop 0
	global_load_dwordx4 v[12:15], v[12:13], off nt
	s_nop 0
	global_load_dwordx4 v[16:19], v[16:17], off nt
	s_nop 0
	global_load_dwordx4 v[20:23], v[20:21], off nt
	s_nop 0
	global_load_dwordx4 v[24:27], v[24:25], off nt
	s_nop 0
	global_load_dwordx4 v[36:39], v[36:37], off nt
	v_mov_b32_e32 v43, v33
	v_mov_b32_e32 v45, v33
	v_mov_b32_e32 v47, v33
	v_mov_b32_e32 v83, v33
	v_add_u32_e32 v42, 0xffff5708, v50
	v_add_u32_e32 v44, 0xffff5709, v50
	v_add_u32_e32 v46, 0xffff570a, v50
	v_add_u32_e32 v82, 0xffff570b, v50
	v_lshl_add_u64 v[88:89], v[40:41], 1, s[8:9]
	v_lshlrev_b64 v[40:41], 12, v[42:43]
	v_lshlrev_b64 v[42:43], 12, v[44:45]
	v_lshlrev_b64 v[44:45], 12, v[46:47]
	v_lshlrev_b64 v[46:47], 12, v[82:83]
	v_mov_b32_e32 v85, v33
	v_mov_b32_e32 v87, v33
	v_add_u32_e32 v84, 0xffff570c, v50
	v_add_u32_e32 v86, 0xffff570d, v50
	v_lshl_add_u64 v[90:91], v[48:49], 0, v[42:43]
	v_lshl_add_u64 v[92:93], v[48:49], 0, v[44:45]
	v_lshl_add_u64 v[94:95], v[48:49], 0, v[46:47]
	v_lshlrev_b32_e32 v32, 13, v52
	v_mov_b32_e32 v79, v33
	v_mov_b32_e32 v81, v33
	v_lshlrev_b64 v[82:83], 12, v[84:85]
	v_lshl_add_u64 v[84:85], v[48:49], 0, v[40:41]
	v_lshl_add_u64 v[96:97], v[88:89], 0, v[32:33]
	v_or_b32_e32 v78, 0x2000, v32
	v_or_b32_e32 v80, 0x4000, v32
	v_or_b32_e32 v32, 0x6000, v32
	v_lshl_add_u64 v[82:83], v[48:49], 0, v[82:83]
	v_lshl_add_u64 v[98:99], v[88:89], 0, v[78:79]
	v_lshl_add_u64 v[100:101], v[88:89], 0, v[80:81]
	v_lshl_add_u64 v[102:103], v[88:89], 0, v[32:33]
	s_waitcnt vmcnt(6)
	v_cvt_pk_bf16_f32 v44, v3, v7
	v_cvt_pk_bf16_f32 v0, v0, v4
	v_cvt_pk_bf16_f32 v4, v1, v5
	s_waitcnt vmcnt(0)
	v_cvt_pk_bf16_f32 v3, v24, v36
	v_cvt_pk_bf16_f32 v7, v25, v37
	v_cvt_pk_bf16_f32 v43, v26, v38
	v_cvt_pk_bf16_f32 v47, v27, v39
	v_add_u32_e32 v24, 0xffff570e, v50
	v_mov_b32_e32 v25, v33
	v_add_u32_e32 v26, 0xffff570f, v50
	v_mov_b32_e32 v27, v33
	v_cvt_pk_bf16_f32 v40, v2, v6
	v_cvt_pk_bf16_f32 v1, v8, v12
	v_cvt_pk_bf16_f32 v2, v16, v20
	v_cvt_pk_bf16_f32 v6, v17, v21
	v_lshlrev_b64 v[16:17], 12, v[86:87]
	v_lshlrev_b64 v[24:25], 12, v[24:25]
	v_lshlrev_b64 v[26:27], 12, v[26:27]
	v_cvt_pk_bf16_f32 v5, v9, v13
	v_cvt_pk_bf16_f32 v41, v10, v14
	v_cvt_pk_bf16_f32 v45, v11, v15
	v_cvt_pk_bf16_f32 v42, v18, v22
	v_cvt_pk_bf16_f32 v46, v19, v23
	global_store_dwordx4 v[96:97], v[0:3], off
	global_store_dwordx4 v[98:99], v[4:7], off
	global_store_dwordx4 v[100:101], v[40:43], off
	global_store_dwordx4 v[102:103], v[44:47], off
	v_lshl_add_u64 v[20:21], v[48:49], 0, v[16:17]
	v_lshl_add_u64 v[24:25], v[48:49], 0, v[24:25]
	v_lshl_add_u64 v[36:37], v[48:49], 0, v[26:27]
	global_load_dwordx4 v[0:3], v[84:85], off nt
	global_load_dwordx4 v[4:7], v[90:91], off nt
	global_load_dwordx4 v[8:11], v[92:93], off nt
	global_load_dwordx4 v[12:15], v[94:95], off nt
	global_load_dwordx4 v[16:19], v[82:83], off nt
	s_nop 0
	global_load_dwordx4 v[20:23], v[20:21], off nt
	s_nop 0
	global_load_dwordx4 v[24:27], v[24:25], off nt
	s_nop 0
	global_load_dwordx4 v[36:39], v[36:37], off nt
	v_lshl_add_u64 v[40:41], v[88:89], 0, 16
	v_lshl_add_u64 v[48:49], v[40:41], 0, v[78:79]
	v_lshl_add_u64 v[82:83], v[40:41], 0, v[80:81]
	v_lshl_add_u64 v[84:85], v[40:41], 0, v[32:33]
	s_waitcnt vmcnt(6)
	v_cvt_pk_bf16_f32 v40, v0, v4
	v_cvt_pk_bf16_f32 v44, v1, v5
	s_waitcnt vmcnt(4)
	v_cvt_pk_bf16_f32 v41, v8, v12
	s_waitcnt vmcnt(2)
	v_cvt_pk_bf16_f32 v42, v16, v20
	s_waitcnt vmcnt(0)
	v_cvt_pk_bf16_f32 v43, v24, v36
	v_cvt_pk_bf16_f32 v45, v9, v13
	v_cvt_pk_bf16_f32 v46, v17, v21
	v_cvt_pk_bf16_f32 v47, v25, v37
	v_cvt_pk_bf16_f32 v78, v2, v6
	v_cvt_pk_bf16_f32 v79, v10, v14
	v_cvt_pk_bf16_f32 v80, v18, v22
	v_cvt_pk_bf16_f32 v81, v26, v38
	v_cvt_pk_bf16_f32 v0, v3, v7
	v_cvt_pk_bf16_f32 v1, v11, v15
	v_cvt_pk_bf16_f32 v2, v19, v23
	v_cvt_pk_bf16_f32 v3, v27, v39
	global_store_dwordx4 v[96:97], v[40:43], off offset:16
	global_store_dwordx4 v[48:49], v[44:47], off
	global_store_dwordx4 v[82:83], v[78:81], off
	global_store_dwordx4 v[84:85], v[0:3], off
; __device__ __forceinline__ unsigned pk2(float lo, float hi) { f32x2 v = {lo, hi}; bf16x2_t b = __builtin_convertvector(v, bf16x2_t); return __builtin_bit_cast(unsigned, b); }
; __device__ __forceinline__ void p0_cvt_item(const float* W, int K, int N, bf16_t* WT, int row_off, const float* gain, int item, int lane) {
;     const int nblk = N / 256, kb = item / nblk, nb = item % nblk, k0 = 16 * kb, n0 = 256 * nb + 4 * lane;
; #pragma unroll
;     for (int kk = 0; kk < 16; kk += 8) {
;         f32x4 v[8];
; #pragma unroll
;         for (int j = 0; j < 8; ++j) { const float gk = gain ? gain[k0 + kk + j] : 1.f; v[j] = *(const f32x4*)(W + (size_t)(k0 + kk + j) * N + n0) * gk; }
; #pragma unroll
;         for (int c = 0; c < 4; ++c) { u32x4 o; o.x = pk2(v[0][c], v[1][c]); o.y = pk2(v[2][c], v[3][c]); o.z = pk2(v[4][c], v[5][c]); o.w = pk2(v[6][c], v[7][c]);
;             *(u32x4*)(WT + (size_t)(row_off + n0 + c) * K + k0 + kk) = o; }
;     }
; __device__ __forceinline__ void p0_phase(const Args& a, LAS unsigned char* lds, int G, int wg, int part, bool split) {
;     ...
;         if (r < I_SQ) { p0_cvt_item(a.in[7] + (size_t)DM * DM, DM, DM, (bf16_t*)(ws + WS_AWOUT) + (size_t)DM * DM, 0, nullptr, r, lane); continue; } r -= I_SQ;
;         if (r < I_W1) { p0_cvt_item(a.in[13] + (size_t)3 * DM * FF, DM, FF, (bf16_t*)(ws + WS_W1) + (size_t)3 * FF * DM, 0, norm_mlp + 3 * DM, r, lane); continue; } r -= I_W1;
;         p0_cvt_item(a.in[14] + (size_t)3 * FF * DM, FF, DM, (bf16_t*)(ws + WS_W2) + (size_t)3 * DM * FF, 0, nullptr, r, lane);
.LBB0_34:
	s_andn2_saveexec_b64 s[66:67], s[66:67]
	s_cbranch_execz .LBB0_36
	v_and_or_b32 v52, v31, s76, v28
	v_and_b32_e32 v50, 0xfff0, v57
	v_lshlrev_b32_e32 v32, 2, v52
	v_lshl_add_u64 v[2:3], s[46:47], 0, v[32:33]
	v_lshlrev_b32_e32 v32, 1, v50
	v_lshl_add_u64 v[0:1], s[10:11], 0, v[32:33]
	v_lshlrev_b32_e32 v32, 14, v50
	v_lshlrev_b32_e32 v8, 2, v50
	v_or_b32_e32 v14, 0x4000, v32
	v_mov_b32_e32 v15, v33
	v_or_b32_e32 v20, 0x8000, v32
	v_mov_b32_e32 v21, v33
	v_or_b32_e32 v22, 0xc000, v32
	v_mov_b32_e32 v23, v33
	v_or_b32_e32 v36, 0x10000, v32
	v_mov_b32_e32 v37, v33
	v_or_b32_e32 v38, 0x14000, v32
	v_mov_b32_e32 v39, v33
	v_or_b32_e32 v44, 0x18000, v32
	v_mov_b32_e32 v45, v33
	v_or_b32_e32 v48, 0x1c000, v32
	v_mov_b32_e32 v49, v33
	global_load_dwordx4 v[4:7], v8, s[90:91] offset:16
	s_nop 0
	global_load_dwordx4 v[8:11], v8, s[90:91]
	v_lshl_add_u64 v[12:13], v[2:3], 0, v[32:33]
	v_lshl_add_u64 v[16:17], v[2:3], 0, v[14:15]
	v_lshl_add_u64 v[20:21], v[2:3], 0, v[20:21]
	v_lshl_add_u64 v[24:25], v[2:3], 0, v[22:23]
	v_lshl_add_u64 v[36:37], v[2:3], 0, v[36:37]
	v_lshl_add_u64 v[40:41], v[2:3], 0, v[38:39]
	v_lshl_add_u64 v[44:45], v[2:3], 0, v[44:45]
	v_lshl_add_u64 v[48:49], v[2:3], 0, v[48:49]
	global_load_dwordx4 v[12:15], v[12:13], off nt
	s_nop 0
	global_load_dwordx4 v[16:19], v[16:17], off nt
	s_nop 0
	global_load_dwordx4 v[20:23], v[20:21], off nt
	s_nop 0
	global_load_dwordx4 v[24:27], v[24:25], off nt
	s_nop 0
	global_load_dwordx4 v[36:39], v[36:37], off nt
	s_nop 0
	global_load_dwordx4 v[40:43], v[40:41], off nt
	v_or_b32_e32 v54, 8, v50
	global_load_dwordx4 v[44:47], v[44:45], off nt
	v_mov_b32_e32 v83, v33
	global_load_dwordx4 v[78:81], v[48:49], off nt
	v_lshlrev_b32_e32 v48, 11, v52
	v_mov_b32_e32 v49, v33
	v_mov_b32_e32 v85, v33
	v_or_b32_e32 v82, 0x1000, v48
	v_or_b32_e32 v84, 0x1800, v48
	v_lshl_add_u64 v[48:49], v[0:1], 0, v[48:49]
	v_lshl_add_u64 v[86:87], v[0:1], 0, v[82:83]
	v_lshl_add_u64 v[88:89], v[0:1], 0, v[84:85]
	v_lshlrev_b32_e32 v56, 2, v54
	v_lshl_add_u64 v[0:1], v[0:1], 0, 16
	v_lshl_add_u64 v[82:83], v[0:1], 0, v[82:83]
	v_lshl_add_u64 v[84:85], v[0:1], 0, v[84:85]
	s_waitcnt vmcnt(9)
	v_mov_b32_e32 v52, v7
	s_waitcnt vmcnt(8)
	v_mov_b32_e32 v50, v11
	s_waitcnt vmcnt(7)
	v_pk_mul_f32 v[90:91], v[14:15], v[8:9] op_sel_hi:[1,0]
	v_pk_mul_f32 v[12:13], v[12:13], v[8:9] op_sel_hi:[1,0]
	s_waitcnt vmcnt(6)
	v_pk_mul_f32 v[18:19], v[18:19], v[8:9] op_sel:[0,1]
	v_pk_mul_f32 v[8:9], v[16:17], v[8:9] op_sel:[0,1]
	s_waitcnt vmcnt(5)
	v_pk_mul_f32 v[16:17], v[22:23], v[10:11] op_sel_hi:[1,0]
	v_pk_mul_f32 v[10:11], v[20:21], v[10:11] op_sel_hi:[1,0]
	s_waitcnt vmcnt(4)
	v_pk_mul_f32 v[20:21], v[26:27], v[50:51] op_sel_hi:[1,0]
	v_pk_mul_f32 v[14:15], v[24:25], v[50:51] op_sel_hi:[1,0]
	s_waitcnt vmcnt(3)
	v_pk_mul_f32 v[24:25], v[36:37], v[4:5] op_sel_hi:[1,0]
	s_waitcnt vmcnt(2)
	v_pk_mul_f32 v[36:37], v[40:41], v[4:5] op_sel:[0,1]
	s_waitcnt vmcnt(1)
	v_pk_mul_f32 v[40:41], v[44:45], v[6:7] op_sel_hi:[1,0]
	s_waitcnt vmcnt(0)
	v_pk_mul_f32 v[44:45], v[78:79], v[52:53] op_sel_hi:[1,0]
	v_pk_mul_f32 v[22:23], v[38:39], v[4:5] op_sel_hi:[1,0]
	v_pk_mul_f32 v[26:27], v[42:43], v[4:5] op_sel:[0,1]
	v_pk_mul_f32 v[38:39], v[46:47], v[6:7] op_sel_hi:[1,0]
	v_pk_mul_f32 v[42:43], v[80:81], v[52:53] op_sel_hi:[1,0]
	v_cvt_pk_bf16_f32 v4, v12, v8
	v_cvt_pk_bf16_f32 v5, v10, v14
	v_cvt_pk_bf16_f32 v6, v24, v36
	v_cvt_pk_bf16_f32 v7, v40, v44
	v_cvt_pk_bf16_f32 v8, v13, v9
	v_cvt_pk_bf16_f32 v12, v90, v18
	v_cvt_pk_bf16_f32 v13, v16, v20
	v_cvt_pk_bf16_f32 v9, v11, v15
	v_cvt_pk_bf16_f32 v10, v25, v37
	v_cvt_pk_bf16_f32 v11, v41, v45
	v_cvt_pk_bf16_f32 v14, v22, v26
	v_cvt_pk_bf16_f32 v15, v38, v42
	v_cvt_pk_bf16_f32 v16, v91, v19
	v_cvt_pk_bf16_f32 v17, v17, v21
	v_cvt_pk_bf16_f32 v18, v23, v27
	v_cvt_pk_bf16_f32 v19, v39, v43
	global_store_dwordx4 v[48:49], v[4:7], off
	global_store_dwordx4 v[48:49], v[8:11], off offset:2048
	global_store_dwordx4 v[86:87], v[12:15], off
	global_store_dwordx4 v[88:89], v[16:19], off
	v_or_b32_e32 v24, 0x24000, v32
	v_lshlrev_b32_e32 v12, 14, v54
	v_mov_b32_e32 v13, v33
	v_lshl_add_u64 v[36:37], v[2:3], 0, v[12:13]
	v_or_b32_e32 v12, 0x30000, v32
	v_mov_b32_e32 v25, v33
	v_lshl_add_u64 v[16:17], v[2:3], 0, v[12:13]
	v_or_b32_e32 v12, 0x34000, v32
	v_lshl_add_u64 v[20:21], v[2:3], 0, v[12:13]
	v_or_b32_e32 v12, 0x38000, v32
	v_lshl_add_u64 v[40:41], v[2:3], 0, v[24:25]
	v_or_b32_e32 v24, 0x28000, v32
	v_or_b32_e32 v44, 0x2c000, v32
	v_mov_b32_e32 v45, v33
	v_or_b32_e32 v32, 0x3c000, v32
	global_load_dwordx4 v[4:7], v56, s[90:91] offset:16
	global_load_dwordx4 v[8:11], v56, s[90:91]
	v_lshl_add_u64 v[12:13], v[2:3], 0, v[12:13]
	v_lshl_add_u64 v[24:25], v[2:3], 0, v[24:25]
	v_lshl_add_u64 v[44:45], v[2:3], 0, v[44:45]
	v_lshl_add_u64 v[2:3], v[2:3], 0, v[32:33]
	global_load_dwordx4 v[12:15], v[12:13], off nt
	s_nop 0
	global_load_dwordx4 v[16:19], v[16:17], off nt
	s_nop 0
	global_load_dwordx4 v[20:23], v[20:21], off nt
	s_nop 0
	global_load_dwordx4 v[24:27], v[24:25], off nt
	s_nop 0
	global_load_dwordx4 v[36:39], v[36:37], off nt
	s_nop 0
	global_load_dwordx4 v[40:43], v[40:41], off nt
	s_waitcnt vmcnt(6)
	v_mov_b32_e32 v0, v11
	global_load_dwordx4 v[44:47], v[44:45], off nt
	s_waitcnt vmcnt(6)
	v_pk_mul_f32 v[86:87], v[14:15], v[6:7] op_sel_hi:[1,0]
	global_load_dwordx4 v[78:81], v[2:3], off nt
	v_pk_mul_f32 v[88:89], v[12:13], v[6:7] op_sel_hi:[1,0]
	v_mov_b32_e32 v6, v7
	s_waitcnt vmcnt(5)
	v_pk_mul_f32 v[12:13], v[22:23], v[4:5] op_sel:[0,1]
	v_pk_mul_f32 v[2:3], v[20:21], v[4:5] op_sel:[0,1]
	v_pk_mul_f32 v[14:15], v[18:19], v[4:5] op_sel_hi:[1,0]
	v_pk_mul_f32 v[4:5], v[16:17], v[4:5] op_sel_hi:[1,0]
	s_waitcnt vmcnt(4)
	v_pk_mul_f32 v[16:17], v[26:27], v[10:11] op_sel_hi:[1,0]
	v_pk_mul_f32 v[18:19], v[24:25], v[10:11] op_sel_hi:[1,0]
	s_waitcnt vmcnt(2)
	v_pk_mul_f32 v[10:11], v[42:43], v[8:9] op_sel:[0,1]
	v_pk_mul_f32 v[20:21], v[40:41], v[8:9] op_sel:[0,1]
	v_pk_mul_f32 v[22:23], v[38:39], v[8:9] op_sel_hi:[1,0]
	v_pk_mul_f32 v[8:9], v[36:37], v[8:9] op_sel_hi:[1,0]
	v_cvt_pk_bf16_f32 v2, v4, v2
	v_cvt_pk_bf16_f32 v4, v9, v21
	s_waitcnt vmcnt(1)
	v_pk_mul_f32 v[26:27], v[44:45], v[0:1] op_sel_hi:[1,0]
	v_pk_mul_f32 v[24:25], v[46:47], v[0:1] op_sel_hi:[1,0]
	v_cvt_pk_bf16_f32 v0, v8, v20
	s_waitcnt vmcnt(0)
	v_pk_mul_f32 v[38:39], v[78:79], v[6:7] op_sel_hi:[1,0]
	v_pk_mul_f32 v[36:37], v[80:81], v[6:7] op_sel_hi:[1,0]
	v_cvt_pk_bf16_f32 v6, v5, v3
	v_cvt_pk_bf16_f32 v1, v18, v26
	v_cvt_pk_bf16_f32 v3, v88, v38
	v_cvt_pk_bf16_f32 v8, v22, v10
	v_cvt_pk_bf16_f32 v10, v14, v12
	v_cvt_pk_bf16_f32 v12, v23, v11
	v_cvt_pk_bf16_f32 v14, v15, v13
	v_cvt_pk_bf16_f32 v5, v19, v27
	v_cvt_pk_bf16_f32 v7, v89, v39
	v_cvt_pk_bf16_f32 v9, v16, v24
	v_cvt_pk_bf16_f32 v11, v86, v36
	v_cvt_pk_bf16_f32 v13, v17, v25
	v_cvt_pk_bf16_f32 v15, v87, v37
	global_store_dwordx4 v[48:49], v[0:3], off offset:16
	global_store_dwordx4 v[48:49], v[4:7], off offset:2064
	global_store_dwordx4 v[82:83], v[8:11], off
	global_store_dwordx4 v[84:85], v[12:15], off

; __device__ __forceinline__ unsigned pk2(float lo, float hi) { f32x2 v = {lo, hi}; bf16x2_t b = __builtin_convertvector(v, bf16x2_t); return __builtin_bit_cast(unsigned, b); }
; __device__ __forceinline__ void p0_cvt_item(const float* W, int K, int N, bf16_t* WT, int row_off, const float* gain, int item, int lane) {
;     const int nblk = N / 256, kb = item / nblk, nb = item % nblk, k0 = 16 * kb, n0 = 256 * nb + 4 * lane;
; #pragma unroll
;     for (int kk = 0; kk < 16; kk += 8) {
;         f32x4 v[8];
; #pragma unroll
;         for (int j = 0; j < 8; ++j) { const float gk = gain ? gain[k0 + kk + j] : 1.f; v[j] = *(const f32x4*)(W + (size_t)(k0 + kk + j) * N + n0) * gk; }
; #pragma unroll
;         for (int c = 0; c < 4; ++c) { u32x4 o; o.x = pk2(v[0][c], v[1][c]); o.y = pk2(v[2][c], v[3][c]); o.z = pk2(v[4][c], v[5][c]); o.w = pk2(v[6][c], v[7][c]);
;             *(u32x4*)(WT + (size_t)(row_off + n0 + c) * K + k0 + kk) = o; }
;     }
; __device__ __forceinline__ void p0_phase(const Args& a, LAS unsigned char* lds, int G, int wg, int part, bool split) {
;     ...
;         if (r < I_SQ) { p0_cvt_item(a.in[7] + (size_t)DM * DM, DM, DM, (bf16_t*)(ws + WS_AWOUT) + (size_t)DM * DM, 0, nullptr, r, lane); continue; } r -= I_SQ;
.LBB0_37:
	s_andn2_saveexec_b64 s[64:65], s[64:65]
	s_cbranch_execz .LBB0_39
	v_add_u32_e32 v0, 0x300, v29
	v_and_or_b32 v40, v31, s72, v28
	v_and_b32_e32 v2, 0x3f0, v0
	v_lshlrev_b32_e32 v32, 2, v40
	v_lshl_add_u64 v[0:1], s[48:49], 0, v[32:33]
	v_lshlrev_b32_e32 v32, 1, v2
	v_lshl_add_u64 v[48:49], s[92:93], 0, v[32:33]
	v_lshlrev_b32_e32 v32, 12, v2
	v_lshl_add_u64 v[78:79], v[0:1], 0, v[32:33]
	v_add_co_u32_e32 v4, vcc, 0x1000, v78
	v_lshlrev_b32_e32 v32, 11, v40
	s_nop 0
	v_addc_co_u32_e32 v5, vcc, 0, v79, vcc
	v_add_co_u32_e32 v8, vcc, s73, v78
	global_load_dwordx4 v[0:3], v[78:79], off nt
	s_nop 0
	global_load_dwordx4 v[4:7], v[4:5], off nt
	v_addc_co_u32_e32 v9, vcc, 0, v79, vcc
	v_add_co_u32_e32 v12, vcc, 0x3000, v78
	v_mov_b32_e32 v81, v33
	s_nop 0
	v_addc_co_u32_e32 v13, vcc, 0, v79, vcc
	v_add_co_u32_e32 v16, vcc, s74, v78
	global_load_dwordx4 v[8:11], v[8:9], off nt
	s_nop 0
	global_load_dwordx4 v[12:15], v[12:13], off nt
	v_addc_co_u32_e32 v17, vcc, 0, v79, vcc
	v_add_co_u32_e32 v20, vcc, 0x5000, v78
	v_lshl_add_u64 v[82:83], v[48:49], 0, v[32:33]
	s_nop 0
	v_addc_co_u32_e32 v21, vcc, 0, v79, vcc
	v_add_co_u32_e32 v24, vcc, s75, v78
	global_load_dwordx4 v[16:19], v[16:17], off nt
	s_nop 0
	global_load_dwordx4 v[20:23], v[20:21], off nt
	v_addc_co_u32_e32 v25, vcc, 0, v79, vcc
	v_add_co_u32_e32 v36, vcc, 0x7000, v78
	v_or_b32_e32 v80, 0x1000, v32
	s_nop 0
	v_addc_co_u32_e32 v37, vcc, 0, v79, vcc
	global_load_dwordx4 v[24:27], v[24:25], off nt
	s_nop 0
	global_load_dwordx4 v[36:39], v[36:37], off nt
	v_add_co_u32_e32 v84, vcc, s78, v78
	v_or_b32_e32 v32, 0x1800, v32
	s_nop 0
	v_addc_co_u32_e32 v85, vcc, 0, v79, vcc
	v_add_co_u32_e32 v86, vcc, s79, v78
	v_lshl_add_u64 v[90:91], v[48:49], 0, v[80:81]
	s_nop 0
	v_addc_co_u32_e32 v87, vcc, 0, v79, vcc
	v_add_co_u32_e32 v88, vcc, s80, v78
	v_lshl_add_u64 v[92:93], v[48:49], 0, v[32:33]
	s_nop 0
	v_addc_co_u32_e32 v89, vcc, 0, v79, vcc
	s_waitcnt vmcnt(6)
	v_cvt_pk_bf16_f32 v0, v0, v4
	v_cvt_pk_bf16_f32 v4, v1, v5
	v_cvt_pk_bf16_f32 v40, v2, v6
	v_cvt_pk_bf16_f32 v44, v3, v7
	s_waitcnt vmcnt(4)
	v_cvt_pk_bf16_f32 v1, v8, v12
	v_cvt_pk_bf16_f32 v5, v9, v13
	v_cvt_pk_bf16_f32 v41, v10, v14
	v_cvt_pk_bf16_f32 v45, v11, v15
	s_waitcnt vmcnt(2)
	v_cvt_pk_bf16_f32 v2, v16, v20
	v_cvt_pk_bf16_f32 v6, v17, v21
	v_cvt_pk_bf16_f32 v42, v18, v22
	v_cvt_pk_bf16_f32 v46, v19, v23
	s_waitcnt vmcnt(0)
	v_cvt_pk_bf16_f32 v3, v24, v36
	v_add_co_u32_e32 v36, vcc, s81, v78
	v_cvt_pk_bf16_f32 v7, v25, v37
	v_cvt_pk_bf16_f32 v43, v26, v38
	v_cvt_pk_bf16_f32 v47, v27, v39
	global_store_dwordx4 v[82:83], v[0:3], off
	global_store_dwordx4 v[82:83], v[4:7], off offset:2048
	global_store_dwordx4 v[90:91], v[40:43], off
	global_store_dwordx4 v[92:93], v[44:47], off
	v_addc_co_u32_e32 v37, vcc, 0, v79, vcc
	global_load_dwordx4 v[0:3], v[84:85], off offset:-4096 nt
	global_load_dwordx4 v[4:7], v[84:85], off nt
	global_load_dwordx4 v[8:11], v[86:87], off offset:-4096 nt
	global_load_dwordx4 v[12:15], v[86:87], off nt
	global_load_dwordx4 v[16:19], v[88:89], off offset:-4096 nt
	global_load_dwordx4 v[20:23], v[88:89], off nt
	global_load_dwordx4 v[24:27], v[36:37], off offset:-4096 nt
	s_nop 0
	global_load_dwordx4 v[36:39], v[36:37], off nt
	v_lshl_add_u64 v[40:41], v[48:49], 0, 16
	v_lshl_add_u64 v[48:49], v[40:41], 0, v[80:81]
	v_lshl_add_u64 v[84:85], v[40:41], 0, v[32:33]
	s_waitcnt vmcnt(6)
	v_cvt_pk_bf16_f32 v40, v0, v4
	v_cvt_pk_bf16_f32 v44, v1, v5
	s_waitcnt vmcnt(4)
	v_cvt_pk_bf16_f32 v41, v8, v12
	v_cvt_pk_bf16_f32 v45, v9, v13
	s_waitcnt vmcnt(2)
	v_cvt_pk_bf16_f32 v42, v16, v20
	s_waitcnt vmcnt(0)
	v_cvt_pk_bf16_f32 v43, v24, v36
	v_cvt_pk_bf16_f32 v46, v17, v21
	v_cvt_pk_bf16_f32 v47, v25, v37
	v_cvt_pk_bf16_f32 v78, v2, v6
	v_cvt_pk_bf16_f32 v79, v10, v14
	v_cvt_pk_bf16_f32 v80, v18, v22
	v_cvt_pk_bf16_f32 v81, v26, v38
	v_cvt_pk_bf16_f32 v0, v3, v7
	v_cvt_pk_bf16_f32 v1, v11, v15
	v_cvt_pk_bf16_f32 v2, v19, v23
	v_cvt_pk_bf16_f32 v3, v27, v39
	global_store_dwordx4 v[82:83], v[40:43], off offset:16
	global_store_dwordx4 v[82:83], v[44:47], off offset:2064
	global_store_dwordx4 v[48:49], v[78:81], off
	global_store_dwordx4 v[84:85], v[0:3], off

; __device__ __forceinline__ unsigned pk2(float lo, float hi) { f32x2 v = {lo, hi}; bf16x2_t b = __builtin_convertvector(v, bf16x2_t); return __builtin_bit_cast(unsigned, b); }
; __device__ __forceinline__ void p0_cvt_item(const float* W, int K, int N, bf16_t* WT, int row_off, const float* gain, int item, int lane) {
;     const int nblk = N / 256, kb = item / nblk, nb = item % nblk, k0 = 16 * kb, n0 = 256 * nb + 4 * lane;
; #pragma unroll
;     for (int kk = 0; kk < 16; kk += 8) {
;         f32x4 v[8];
; #pragma unroll
;         for (int j = 0; j < 8; ++j) { const float gk = gain ? gain[k0 + kk + j] : 1.f; v[j] = *(const f32x4*)(W + (size_t)(k0 + kk + j) * N + n0) * gk; }
; #pragma unroll
;         for (int c = 0; c < 4; ++c) { u32x4 o; o.x = pk2(v[0][c], v[1][c]); o.y = pk2(v[2][c], v[3][c]); o.z = pk2(v[4][c], v[5][c]); o.w = pk2(v[6][c], v[7][c]);
;             *(u32x4*)(WT + (size_t)(row_off + n0 + c) * K + k0 + kk) = o; }
;     }
; __device__ __forceinline__ void p0_phase(const Args& a, LAS unsigned char* lds, int G, int wg, int part, bool split) {
;     ...
;         if (r < 3 * I_W2) { const int j = r / I_W2; r -= j * I_W2;
;             p0_cvt_item(a.in[14] + (size_t)j * FF * DM, FF, DM, (bf16_t*)(ws + WS_W2) + (size_t)j * DM * FF, 0, nullptr, r, lane); continue; } r -= 3 * I_W2;
.LBB0_40:
	s_andn2_saveexec_b64 s[62:63], s[62:63]
	s_cbranch_execz .LBB0_42
	v_add_u32_e32 v0, 0xffff0d00, v57
	v_lshrrev_b32_e32 v32, 10, v0
	v_readlane_b32 s8, v252, 16
	v_lshlrev_b64 v[0:1], 24, v[32:33]
	v_readlane_b32 s20, v252, 28
	v_readlane_b32 s21, v252, 29
	v_add_u32_e32 v4, 0xffff9b00, v29
	v_and_or_b32 v42, v31, s72, v28
	v_lshl_add_u64 v[0:1], s[20:21], 0, v[0:1]
	v_lshlrev_b64 v[2:3], 23, v[32:33]
	v_and_b32_e32 v4, 0xff0, v4
	v_lshlrev_b32_e32 v32, 2, v42
	v_lshl_add_u64 v[2:3], s[94:95], 0, v[2:3]
	v_lshl_add_u64 v[0:1], v[0:1], 0, v[32:33]
	v_lshlrev_b32_e32 v32, 1, v4
	v_lshl_add_u64 v[48:49], v[2:3], 0, v[32:33]
	v_lshlrev_b32_e32 v32, 12, v4
	v_lshl_add_u64 v[40:41], v[0:1], 0, v[32:33]
	v_add_co_u32_e32 v8, vcc, s73, v40
	s_mov_b32 s64, 0x8000
	s_nop 0
	v_addc_co_u32_e32 v9, vcc, 0, v41, vcc
	v_add_co_u32_e32 v16, vcc, s74, v40
	global_load_dwordx4 v[0:3], v[40:41], off nt
	global_load_dwordx4 v[4:7], v[8:9], off offset:-4096 nt
	v_addc_co_u32_e32 v17, vcc, 0, v41, vcc
	v_add_co_u32_e32 v24, vcc, s75, v40
	global_load_dwordx4 v[8:11], v[8:9], off nt
	s_nop 0
	global_load_dwordx4 v[12:15], v[16:17], off offset:-4096 nt
	v_addc_co_u32_e32 v25, vcc, 0, v41, vcc
	v_add_co_u32_e32 v82, vcc, s64, v40
	global_load_dwordx4 v[16:19], v[16:17], off nt
	s_nop 0
	global_load_dwordx4 v[20:23], v[24:25], off offset:-4096 nt
	v_addc_co_u32_e32 v83, vcc, 0, v41, vcc
	global_load_dwordx4 v[24:27], v[24:25], off nt
	s_nop 0
	global_load_dwordx4 v[36:39], v[82:83], off offset:-4096 nt
	s_mov_b32 s64, 0xa000
	v_add_co_u32_e32 v90, vcc, s64, v40
	s_mov_b32 s64, 0xc000
	s_nop 0
	v_addc_co_u32_e32 v91, vcc, 0, v41, vcc
	v_add_co_u32_e32 v92, vcc, s64, v40
	s_mov_b32 s64, 0xe000
	s_nop 0
	v_addc_co_u32_e32 v93, vcc, 0, v41, vcc
	v_add_co_u32_e32 v94, vcc, s64, v40
	v_lshlrev_b32_e32 v32, 13, v42
	s_nop 0
	v_addc_co_u32_e32 v95, vcc, 0, v41, vcc
	v_add_co_u32_e32 v96, vcc, s81, v40
	v_mov_b32_e32 v85, v33
	v_mov_b32_e32 v87, v33
	v_lshl_add_u64 v[88:89], v[48:49], 0, v[32:33]
	v_or_b32_e32 v84, 0x2000, v32
	v_or_b32_e32 v86, 0x4000, v32
	v_or_b32_e32 v32, 0x6000, v32
	v_addc_co_u32_e32 v97, vcc, 0, v41, vcc
	v_lshl_add_u64 v[98:99], v[48:49], 0, v[84:85]
	v_lshl_add_u64 v[100:101], v[48:49], 0, v[86:87]
	v_lshl_add_u64 v[102:103], v[48:49], 0, v[32:33]
	v_readlane_b32 s9, v252, 17
	v_readlane_b32 s10, v252, 18
	v_readlane_b32 s11, v252, 19
	v_readlane_b32 s12, v252, 20
	v_readlane_b32 s13, v252, 21
	v_readlane_b32 s14, v252, 22
	v_readlane_b32 s15, v252, 23
	v_readlane_b32 s16, v252, 24
	v_readlane_b32 s17, v252, 25
	v_readlane_b32 s18, v252, 26
	v_readlane_b32 s19, v252, 27
	v_readlane_b32 s22, v252, 30
	v_readlane_b32 s23, v252, 31
	s_waitcnt vmcnt(6)
	v_cvt_pk_bf16_f32 v40, v0, v4
	v_cvt_pk_bf16_f32 v44, v1, v5
	v_cvt_pk_bf16_f32 v78, v2, v6
	v_cvt_pk_bf16_f32 v0, v3, v7
	s_waitcnt vmcnt(4)
	v_cvt_pk_bf16_f32 v41, v8, v12
	v_cvt_pk_bf16_f32 v45, v9, v13
	v_cvt_pk_bf16_f32 v79, v10, v14
	v_cvt_pk_bf16_f32 v1, v11, v15
	s_waitcnt vmcnt(2)
	v_cvt_pk_bf16_f32 v42, v16, v20
	v_cvt_pk_bf16_f32 v46, v17, v21
	v_cvt_pk_bf16_f32 v80, v18, v22
	s_waitcnt vmcnt(0)
	v_cvt_pk_bf16_f32 v43, v24, v36
	v_cvt_pk_bf16_f32 v47, v25, v37
	v_cvt_pk_bf16_f32 v81, v26, v38
	v_cvt_pk_bf16_f32 v2, v19, v23
	v_cvt_pk_bf16_f32 v3, v27, v39
	global_store_dwordx4 v[88:89], v[40:43], off
	global_store_dwordx4 v[98:99], v[44:47], off
	global_store_dwordx4 v[100:101], v[78:81], off
	global_store_dwordx4 v[102:103], v[0:3], off
	global_load_dwordx4 v[0:3], v[82:83], off nt
	s_nop 0
	global_load_dwordx4 v[4:7], v[90:91], off offset:-4096 nt
	global_load_dwordx4 v[8:11], v[90:91], off nt
	global_load_dwordx4 v[12:15], v[92:93], off offset:-4096 nt
	global_load_dwordx4 v[16:19], v[92:93], off nt
	global_load_dwordx4 v[20:23], v[94:95], off offset:-4096 nt
	global_load_dwordx4 v[24:27], v[94:95], off nt
	global_load_dwordx4 v[36:39], v[96:97], off nt
	v_lshl_add_u64 v[40:41], v[48:49], 0, 16
	v_lshl_add_u64 v[48:49], v[40:41], 0, v[84:85]
	v_lshl_add_u64 v[82:83], v[40:41], 0, v[86:87]
	v_lshl_add_u64 v[84:85], v[40:41], 0, v[32:33]
	s_waitcnt vmcnt(6)
	v_cvt_pk_bf16_f32 v40, v0, v4
	v_cvt_pk_bf16_f32 v44, v1, v5
	s_waitcnt vmcnt(4)
	v_cvt_pk_bf16_f32 v41, v8, v12
	v_cvt_pk_bf16_f32 v45, v9, v13
	s_waitcnt vmcnt(2)
	v_cvt_pk_bf16_f32 v42, v16, v20
	v_cvt_pk_bf16_f32 v46, v17, v21
	s_waitcnt vmcnt(0)
	v_cvt_pk_bf16_f32 v43, v24, v36
	v_cvt_pk_bf16_f32 v47, v25, v37
	v_cvt_pk_bf16_f32 v78, v2, v6
	v_cvt_pk_bf16_f32 v79, v10, v14
	v_cvt_pk_bf16_f32 v80, v18, v22
	v_cvt_pk_bf16_f32 v81, v26, v38
	v_cvt_pk_bf16_f32 v0, v3, v7
	v_cvt_pk_bf16_f32 v1, v11, v15
	v_cvt_pk_bf16_f32 v2, v19, v23
	v_cvt_pk_bf16_f32 v3, v27, v39
	global_store_dwordx4 v[88:89], v[40:43], off offset:16
	global_store_dwordx4 v[48:49], v[44:47], off
	global_store_dwordx4 v[82:83], v[78:81], off
	global_store_dwordx4 v[84:85], v[0:3], off

; __device__ __forceinline__ unsigned pk2(float lo, float hi) { f32x2 v = {lo, hi}; bf16x2_t b = __builtin_convertvector(v, bf16x2_t); return __builtin_bit_cast(unsigned, b); }
; __device__ __forceinline__ void p0_cvt_item(const float* W, int K, int N, bf16_t* WT, int row_off, const float* gain, int item, int lane) {
;     const int nblk = N / 256, kb = item / nblk, nb = item % nblk, k0 = 16 * kb, n0 = 256 * nb + 4 * lane;
; #pragma unroll
;     for (int kk = 0; kk < 16; kk += 8) {
;         f32x4 v[8];
; #pragma unroll
;         for (int j = 0; j < 8; ++j) { const float gk = gain ? gain[k0 + kk + j] : 1.f; v[j] = *(const f32x4*)(W + (size_t)(k0 + kk + j) * N + n0) * gk; }
; #pragma unroll
;         for (int c = 0; c < 4; ++c) { u32x4 o; o.x = pk2(v[0][c], v[1][c]); o.y = pk2(v[2][c], v[3][c]); o.z = pk2(v[4][c], v[5][c]); o.w = pk2(v[6][c], v[7][c]);
;             *(u32x4*)(WT + (size_t)(row_off + n0 + c) * K + k0 + kk) = o; }
;     }
; __device__ __forceinline__ void p0_phase(const Args& a, LAS unsigned char* lds, int G, int wg, int part, bool split) {
;     ...
;         if (r < 2 * I_AIN) { const int j = r / I_AIN; r -= j * I_AIN;
;             p0_cvt_item(a.in[4] + (size_t)j * DM * 4096, DM, 4096, (bf16_t*)(ws + WS_AWIN) + (size_t)j * 4096 * DM, 0, norm_mix + (3 * j) * DM, r, lane); continue; } r -= 2 * I_AIN;
;         if (r < I_SQ) { p0_cvt_item(a.in[7], DM, DM, (bf16_t*)(ws + WS_AWOUT), 0, nullptr, r, lane); continue; } r -= I_SQ;
;         if (r < I_QKV) { p0_cvt_item(a.in[8], DM, 3072, (bf16_t*)(ws + WS_BQKV), 0, norm_mix + 1 * DM, r, lane); continue; } r -= I_QKV;
;         if (r < I_SQ) { p0_cvt_item(a.in[9], DM, DM, (bf16_t*)(ws + WS_BOUT), 0, nullptr, r, lane); continue; } r -= I_SQ;
;         if (r < 4 * I_CW) { const int g = r / I_CW; r -= g * I_CW;
;             p0_cvt_item(a.in[11] + (size_t)g * 256 * 256, 256, 256, (bf16_t*)(ws + WS_CW), g * 256, nullptr, r, lane); continue; } r -= 4 * I_CW;
;         if (r < 3 * I_W1) { const int j = r / I_W1; r -= j * I_W1;
;             p0_cvt_item(a.in[13] + (size_t)j * DM * FF, DM, FF, (bf16_t*)(ws + WS_W1) + (size_t)j * FF * DM, 0, norm_mlp + j * DM, r, lane); continue; } r -= 3 * I_W1;
.LBB0_46:
	v_lshrrev_b32_e32 v32, 10, v0
	v_readlane_b32 s8, v252, 16
	v_lshlrev_b64 v[0:1], 24, v[32:33]
	v_readlane_b32 s18, v252, 26
	v_readlane_b32 s19, v252, 27
	v_and_or_b32 v47, v31, s76, v28
	v_lshlrev_b32_e32 v2, 2, v47
	v_lshl_add_u64 v[0:1], s[18:19], 0, v[0:1]
	v_mov_b32_e32 v3, v33
	v_lshl_add_u64 v[38:39], v[0:1], 0, v[2:3]
	v_lshlrev_b32_e32 v0, 14, v49
	v_mov_b32_e32 v1, v33
	v_lshl_add_u64 v[0:1], v[38:39], 0, v[0:1]
	global_load_dwordx4 v[0:3], v[0:1], off nt
	s_and_b64 vcc, exec, s[4:5]
	v_readlane_b32 s9, v252, 17
	v_readlane_b32 s10, v252, 18
	v_readlane_b32 s11, v252, 19
	v_readlane_b32 s12, v252, 20
	v_readlane_b32 s13, v252, 21
	v_readlane_b32 s14, v252, 22
	v_readlane_b32 s15, v252, 23
	v_readlane_b32 s16, v252, 24
	v_readlane_b32 s17, v252, 25
	v_readlane_b32 s20, v252, 28
	v_readlane_b32 s21, v252, 29
	v_readlane_b32 s22, v252, 30
	v_readlane_b32 s23, v252, 31
	s_cbranch_vccnz .LBB0_48
	v_mov_b32_e32 v41, v33
	v_lshl_add_u64 v[4:5], v[36:37], 0, v[40:41]
	global_load_dword v44, v[4:5], off offset:4
.LBB0_48:
	v_lshl_or_b32 v4, v49, 14, v61
	v_mov_b32_e32 v5, v33
	v_lshl_add_u64 v[4:5], v[38:39], 0, v[4:5]
	global_load_dwordx4 v[4:7], v[4:5], off nt
	v_mov_b32_e32 v48, 1.0
	s_and_b64 vcc, exec, s[4:5]
	v_mov_b32_e32 v52, 1.0
	s_cbranch_vccnz .LBB0_50
	v_mov_b32_e32 v41, v33
	v_lshl_add_u64 v[8:9], v[36:37], 0, v[40:41]
	global_load_dword v52, v[8:9], off offset:8
.LBB0_50:
	v_lshl_or_b32 v8, v49, 14, v63
	v_mov_b32_e32 v9, v33
	v_lshl_add_u64 v[8:9], v[38:39], 0, v[8:9]
	global_load_dwordx4 v[8:11], v[8:9], off nt
	s_and_b64 vcc, exec, s[4:5]
	s_cbranch_vccnz .LBB0_52
	v_mov_b32_e32 v41, v33
	v_lshl_add_u64 v[12:13], v[36:37], 0, v[40:41]
	global_load_dword v48, v[12:13], off offset:12
.LBB0_52:
	v_lshl_or_b32 v12, v49, 14, v64
	v_mov_b32_e32 v13, v33
	v_lshl_add_u64 v[12:13], v[38:39], 0, v[12:13]
	global_load_dwordx4 v[12:15], v[12:13], off nt
	v_mov_b32_e32 v54, 1.0
	s_and_b64 vcc, exec, s[4:5]
	v_mov_b32_e32 v56, 1.0
	s_cbranch_vccnz .LBB0_54
	v_mov_b32_e32 v41, v33
	v_lshl_add_u64 v[16:17], v[36:37], 0, v[40:41]
	global_load_dword v56, v[16:17], off offset:16
.LBB0_54:
	v_lshl_or_b32 v16, v49, 14, v65
	v_mov_b32_e32 v17, v33
	v_lshl_add_u64 v[16:17], v[38:39], 0, v[16:17]
	global_load_dwordx4 v[16:19], v[16:17], off nt
	s_and_b64 vcc, exec, s[4:5]
	s_cbranch_vccnz .LBB0_56
	v_mov_b32_e32 v41, v33
	v_lshl_add_u64 v[20:21], v[36:37], 0, v[40:41]
	global_load_dword v54, v[20:21], off offset:20
.LBB0_56:
	v_lshl_or_b32 v20, v49, 14, v66
	v_mov_b32_e32 v21, v33
	v_lshl_add_u64 v[20:21], v[38:39], 0, v[20:21]
	global_load_dwordx4 v[20:23], v[20:21], off nt
	v_mov_b32_e32 v50, 1.0
	s_and_b64 vcc, exec, s[4:5]
	v_mov_b32_e32 v58, 1.0
	s_cbranch_vccnz .LBB0_58
	v_mov_b32_e32 v41, v33
	v_lshl_add_u64 v[24:25], v[36:37], 0, v[40:41]
	global_load_dword v58, v[24:25], off offset:24
.LBB0_58:
	v_lshl_or_b32 v24, v49, 14, v67
	v_mov_b32_e32 v25, v33
	v_lshl_add_u64 v[24:25], v[38:39], 0, v[24:25]
	global_load_dwordx4 v[24:27], v[24:25], off nt
	s_and_b64 vcc, exec, s[4:5]
	s_cbranch_vccnz .LBB0_60
	v_mov_b32_e32 v41, v33
	v_lshl_add_u64 v[42:43], v[36:37], 0, v[40:41]
	global_load_dword v50, v[42:43], off offset:28
.LBB0_60:
	v_lshlrev_b64 v[42:43], 23, v[32:33]
	v_lshl_add_u64 v[42:43], s[96:97], 0, v[42:43]
	v_lshlrev_b32_e32 v32, 1, v49
	v_lshl_add_u64 v[42:43], v[42:43], 0, v[32:33]
	v_lshl_or_b32 v32, v49, 14, v68
	v_lshl_add_u64 v[78:79], v[38:39], 0, v[32:33]
	global_load_dwordx4 v[78:81], v[78:79], off nt
	s_waitcnt vmcnt(2)
	v_pk_mul_f32 v[22:23], v[22:23], v[54:55] op_sel_hi:[1,0]
	v_pk_mul_f32 v[18:19], v[18:19], v[56:57] op_sel_hi:[1,0]
	v_pk_mul_f32 v[14:15], v[14:15], v[48:49] op_sel_hi:[1,0]
	v_pk_mul_f32 v[12:13], v[12:13], v[48:49] op_sel_hi:[1,0]
	v_pk_mul_f32 v[10:11], v[10:11], v[52:53] op_sel_hi:[1,0]
	v_pk_mul_f32 v[8:9], v[8:9], v[52:53] op_sel_hi:[1,0]
	v_pk_mul_f32 v[82:83], v[6:7], v[44:45] op_sel_hi:[1,0]
	v_pk_mul_f32 v[4:5], v[4:5], v[44:45] op_sel_hi:[1,0]
	v_pk_mul_f32 v[84:85], v[2:3], v[46:47] op_sel_hi:[1,0]
	v_pk_mul_f32 v[2:3], v[0:1], v[46:47] op_sel_hi:[1,0]
	v_lshlrev_b32_e32 v7, 10, v47
	s_waitcnt vmcnt(1)
	v_pk_mul_f32 v[24:25], v[24:25], v[58:59] op_sel_hi:[1,0]
	v_pk_mul_f32 v[20:21], v[20:21], v[54:55] op_sel_hi:[1,0]
	v_pk_mul_f32 v[16:17], v[16:17], v[56:57] op_sel_hi:[1,0]
	v_cvt_pk_bf16_f32 v0, v2, v4
	v_cvt_pk_bf16_f32 v4, v3, v5
	v_cvt_pk_bf16_f32 v5, v9, v13
	v_cvt_pk_bf16_f32 v9, v10, v14
	v_cvt_pk_bf16_f32 v10, v18, v22
	v_or_b32_e32 v3, 0x800, v7
	v_cvt_pk_bf16_f32 v14, v19, v23
	v_or_b32_e32 v7, 0xc00, v7
	v_lshlrev_b32_e32 v32, 11, v47
	v_pk_mul_f32 v[26:27], v[26:27], v[58:59] op_sel_hi:[1,0]
	v_mov_b32_e32 v45, v33
	v_mov_b32_e32 v48, 1.0
	s_and_b64 vcc, exec, s[4:5]
	v_cvt_pk_bf16_f32 v1, v8, v12
	v_cvt_pk_bf16_f32 v2, v16, v20
	v_cvt_pk_bf16_f32 v6, v17, v21
	v_lshlrev_b32_e32 v44, 1, v7
	v_lshl_add_u64 v[46:47], v[42:43], 0, v[32:33]
	v_lshlrev_b32_e32 v32, 1, v3
	v_cvt_pk_bf16_f32 v8, v84, v82
	v_cvt_pk_bf16_f32 v12, v85, v83
	v_cvt_pk_bf16_f32 v13, v11, v15
	v_lshl_add_u64 v[16:17], v[42:43], 0, v[44:45]
	v_lshl_add_u64 v[18:19], v[42:43], 0, v[32:33]
	s_waitcnt vmcnt(0)
	v_pk_mul_f32 v[22:23], v[78:79], v[50:51] op_sel_hi:[1,0]
	v_pk_mul_f32 v[20:21], v[80:81], v[50:51] op_sel_hi:[1,0]
	v_cvt_pk_bf16_f32 v3, v24, v22
	v_mov_b32_e32 v50, 1.0
	v_cvt_pk_bf16_f32 v7, v25, v23
	v_cvt_pk_bf16_f32 v11, v26, v20
	v_cvt_pk_bf16_f32 v15, v27, v21
	global_store_dwordx4 v[46:47], v[0:3], off
	global_store_dwordx4 v[46:47], v[4:7], off offset:2048
	global_store_dwordx4 v[18:19], v[8:11], off
	global_store_dwordx4 v[16:17], v[12:15], off
	s_cbranch_vccnz .LBB0_62
	v_mov_b32_e32 v41, v33
	v_lshl_add_u64 v[0:1], v[36:37], 0, v[40:41]
	global_load_dword v50, v[0:1], off offset:32
; __device__ __forceinline__ unsigned pk2(float lo, float hi) { f32x2 v = {lo, hi}; bf16x2_t b = __builtin_convertvector(v, bf16x2_t); return __builtin_bit_cast(unsigned, b); }
; __device__ __forceinline__ void p0_cvt_item(const float* W, int K, int N, bf16_t* WT, int row_off, const float* gain, int item, int lane) {
;     const int nblk = N / 256, kb = item / nblk, nb = item % nblk, k0 = 16 * kb, n0 = 256 * nb + 4 * lane;
; #pragma unroll
;     for (int kk = 0; kk < 16; kk += 8) {
;         f32x4 v[8];
; #pragma unroll
;         for (int j = 0; j < 8; ++j) { const float gk = gain ? gain[k0 + kk + j] : 1.f; v[j] = *(const f32x4*)(W + (size_t)(k0 + kk + j) * N + n0) * gk; }
; #pragma unroll
;         for (int c = 0; c < 4; ++c) { u32x4 o; o.x = pk2(v[0][c], v[1][c]); o.y = pk2(v[2][c], v[3][c]); o.z = pk2(v[4][c], v[5][c]); o.w = pk2(v[6][c], v[7][c]);
;             *(u32x4*)(WT + (size_t)(row_off + n0 + c) * K + k0 + kk) = o; }
;     }
.LBB0_62:
	v_lshl_or_b32 v0, v49, 14, v69
	v_mov_b32_e32 v1, v33
	v_lshl_add_u64 v[0:1], v[38:39], 0, v[0:1]
	global_load_dwordx4 v[0:3], v[0:1], off nt
	s_and_b64 vcc, exec, s[4:5]
	s_cbranch_vccnz .LBB0_64
	v_mov_b32_e32 v41, v33
	v_lshl_add_u64 v[4:5], v[36:37], 0, v[40:41]
	global_load_dword v48, v[4:5], off offset:36
.LBB0_64:
	v_lshl_or_b32 v4, v49, 14, v70
	v_mov_b32_e32 v5, v33
	v_lshl_add_u64 v[4:5], v[38:39], 0, v[4:5]
	global_load_dwordx4 v[4:7], v[4:5], off nt
	v_mov_b32_e32 v52, 1.0
	s_and_b64 vcc, exec, s[4:5]
	v_mov_b32_e32 v54, 1.0
	s_cbranch_vccnz .LBB0_66
	v_mov_b32_e32 v41, v33
	v_lshl_add_u64 v[8:9], v[36:37], 0, v[40:41]
	global_load_dword v54, v[8:9], off offset:40
.LBB0_66:
	v_lshl_or_b32 v8, v49, 14, v71
	v_mov_b32_e32 v9, v33
	v_lshl_add_u64 v[8:9], v[38:39], 0, v[8:9]
	global_load_dwordx4 v[8:11], v[8:9], off nt
	s_and_b64 vcc, exec, s[4:5]
	s_cbranch_vccnz .LBB0_68
	v_mov_b32_e32 v41, v33
	v_lshl_add_u64 v[12:13], v[36:37], 0, v[40:41]
	global_load_dword v52, v[12:13], off offset:44
.LBB0_68:
	v_lshl_or_b32 v12, v49, 14, v72
	v_mov_b32_e32 v13, v33
	v_lshl_add_u64 v[12:13], v[38:39], 0, v[12:13]
	global_load_dwordx4 v[12:15], v[12:13], off nt
	v_mov_b32_e32 v58, 1.0
	s_and_b64 vcc, exec, s[4:5]
	v_mov_b32_e32 v60, 1.0
	s_cbranch_vccnz .LBB0_70
	v_mov_b32_e32 v41, v33
	v_lshl_add_u64 v[16:17], v[36:37], 0, v[40:41]
	global_load_dword v60, v[16:17], off offset:48
.LBB0_70:
	v_lshl_or_b32 v16, v49, 14, v73
	v_mov_b32_e32 v17, v33
	v_lshl_add_u64 v[16:17], v[38:39], 0, v[16:17]
	global_load_dwordx4 v[16:19], v[16:17], off nt
	s_and_b64 vcc, exec, s[4:5]
	s_cbranch_vccnz .LBB0_72
	v_mov_b32_e32 v41, v33
	v_lshl_add_u64 v[20:21], v[36:37], 0, v[40:41]
	global_load_dword v58, v[20:21], off offset:52
.LBB0_72:
	v_lshl_or_b32 v20, v49, 14, v74
	v_mov_b32_e32 v21, v33
	v_lshl_add_u64 v[20:21], v[38:39], 0, v[20:21]
	global_load_dwordx4 v[20:23], v[20:21], off nt
	v_mov_b32_e32 v56, 1.0
	s_and_b64 vcc, exec, s[4:5]
	v_mov_b32_e32 v62, 1.0
	s_cbranch_vccnz .LBB0_74
	v_mov_b32_e32 v41, v33
	v_lshl_add_u64 v[24:25], v[36:37], 0, v[40:41]
	global_load_dword v62, v[24:25], off offset:56
.LBB0_74:
	v_lshl_or_b32 v24, v49, 14, v75
	v_mov_b32_e32 v25, v33
	v_lshl_add_u64 v[24:25], v[38:39], 0, v[24:25]
	global_load_dwordx4 v[24:27], v[24:25], off nt
	s_and_b64 vcc, exec, s[4:5]
	s_cbranch_vccnz .LBB0_76
	v_mov_b32_e32 v41, v33
	v_lshl_add_u64 v[36:37], v[36:37], 0, v[40:41]
	global_load_dword v56, v[36:37], off offset:60
.LBB0_76:
	v_lshl_or_b32 v36, v49, 14, v76
	v_mov_b32_e32 v37, v33
	v_lshl_add_u64 v[36:37], v[38:39], 0, v[36:37]
	global_load_dwordx4 v[36:39], v[36:37], off nt
	s_waitcnt vmcnt(2)
	v_pk_mul_f32 v[22:23], v[22:23], v[58:59] op_sel_hi:[1,0]
	v_pk_mul_f32 v[18:19], v[18:19], v[60:61] op_sel_hi:[1,0]
	v_pk_mul_f32 v[14:15], v[14:15], v[52:53] op_sel_hi:[1,0]
	v_pk_mul_f32 v[12:13], v[12:13], v[52:53] op_sel_hi:[1,0]
	v_pk_mul_f32 v[10:11], v[10:11], v[54:55] op_sel_hi:[1,0]
	v_pk_mul_f32 v[8:9], v[8:9], v[54:55] op_sel_hi:[1,0]
	v_pk_mul_f32 v[40:41], v[6:7], v[48:49] op_sel_hi:[1,0]
	v_pk_mul_f32 v[4:5], v[4:5], v[48:49] op_sel_hi:[1,0]
	v_pk_mul_f32 v[48:49], v[2:3], v[50:51] op_sel_hi:[1,0]
	v_pk_mul_f32 v[2:3], v[0:1], v[50:51] op_sel_hi:[1,0]
	s_waitcnt vmcnt(1)
	v_pk_mul_f32 v[24:25], v[24:25], v[62:63] op_sel_hi:[1,0]
	v_pk_mul_f32 v[20:21], v[20:21], v[58:59] op_sel_hi:[1,0]
	v_pk_mul_f32 v[16:17], v[16:17], v[60:61] op_sel_hi:[1,0]
	v_cvt_pk_bf16_f32 v0, v2, v4
	v_cvt_pk_bf16_f32 v4, v3, v5
	v_cvt_pk_bf16_f32 v5, v9, v13
	v_cvt_pk_bf16_f32 v9, v10, v14
	v_cvt_pk_bf16_f32 v10, v18, v22
	v_cvt_pk_bf16_f32 v14, v19, v23
	v_pk_mul_f32 v[26:27], v[26:27], v[62:63] op_sel_hi:[1,0]
	v_lshl_add_u64 v[42:43], v[42:43], 0, 16
	v_mov_b32_e32 v45, v33
	v_cvt_pk_bf16_f32 v1, v8, v12
	v_cvt_pk_bf16_f32 v2, v16, v20
	v_cvt_pk_bf16_f32 v6, v17, v21
	v_cvt_pk_bf16_f32 v8, v48, v40
	v_lshl_add_u64 v[16:17], v[42:43], 0, v[32:33]
	v_cvt_pk_bf16_f32 v12, v49, v41
	v_cvt_pk_bf16_f32 v13, v11, v15
	v_lshl_add_u64 v[18:19], v[42:43], 0, v[44:45]
	s_waitcnt vmcnt(0)
	v_pk_mul_f32 v[22:23], v[36:37], v[56:57] op_sel_hi:[1,0]
	v_pk_mul_f32 v[20:21], v[38:39], v[56:57] op_sel_hi:[1,0]
	v_cvt_pk_bf16_f32 v3, v24, v22
	v_cvt_pk_bf16_f32 v7, v25, v23
	v_cvt_pk_bf16_f32 v11, v26, v20
	v_cvt_pk_bf16_f32 v15, v27, v21
	global_store_dwordx4 v[46:47], v[0:3], off offset:16
	global_store_dwordx4 v[46:47], v[4:7], off offset:2064
	global_store_dwordx4 v[16:17], v[8:11], off
	global_store_dwordx4 v[18:19], v[12:15], off

; __device__ __forceinline__ unsigned pk2(float lo, float hi) { f32x2 v = {lo, hi}; bf16x2_t b = __builtin_convertvector(v, bf16x2_t); return __builtin_bit_cast(unsigned, b); }
; __device__ __forceinline__ void p0_cvt_item(const float* W, int K, int N, bf16_t* WT, int row_off, const float* gain, int item, int lane) {
;     const int nblk = N / 256, kb = item / nblk, nb = item % nblk, k0 = 16 * kb, n0 = 256 * nb + 4 * lane;
; #pragma unroll
;     for (int kk = 0; kk < 16; kk += 8) {
;         f32x4 v[8];
; #pragma unroll
;         for (int j = 0; j < 8; ++j) { const float gk = gain ? gain[k0 + kk + j] : 1.f; v[j] = *(const f32x4*)(W + (size_t)(k0 + kk + j) * N + n0) * gk; }
; #pragma unroll
;         for (int c = 0; c < 4; ++c) { u32x4 o; o.x = pk2(v[0][c], v[1][c]); o.y = pk2(v[2][c], v[3][c]); o.z = pk2(v[4][c], v[5][c]); o.w = pk2(v[6][c], v[7][c]);
;             *(u32x4*)(WT + (size_t)(row_off + n0 + c) * K + k0 + kk) = o; }
;     }
; __device__ __forceinline__ void p0_phase(const Args& a, LAS unsigned char* lds, int G, int wg, int part, bool split) {
;     ...
;         if (r < 4 * I_CW) { const int g = r / I_CW; r -= g * I_CW;
;             p0_cvt_item(a.in[11] + (size_t)g * 256 * 256, 256, 256, (bf16_t*)(ws + WS_CW), g * 256, nullptr, r, lane); continue; } r -= 4 * I_CW;
.LBB0_78:
	s_andn2_saveexec_b64 s[4:5], s[60:61]
	s_cbranch_execz .LBB0_80
	v_add_u32_e32 v0, 0xffff1940, v57
	v_lshrrev_b32_e32 v32, 4, v0
	v_and_b32_e32 v2, 0xf0, v59
	v_lshlrev_b64 v[0:1], 18, v[32:33]
	v_lshl_or_b32 v40, v32, 8, v28
	v_lshlrev_b32_e32 v32, 1, v2
	v_lshl_add_u64 v[0:1], v[34:35], 0, v[0:1]
	v_lshl_add_u64 v[42:43], s[6:7], 0, v[32:33]
	v_lshlrev_b32_e32 v32, 10, v2
	v_lshl_add_u64 v[44:45], v[0:1], 0, v[32:33]
	s_movk_i32 s60, 0x1000
	v_add_co_u32_e32 v36, vcc, s60, v44
	global_load_dwordx4 v[0:3], v[44:45], off nt
	global_load_dwordx4 v[4:7], v[44:45], off offset:1024 nt
	global_load_dwordx4 v[8:11], v[44:45], off offset:2048 nt
	global_load_dwordx4 v[12:15], v[44:45], off offset:3072 nt
	v_addc_co_u32_e32 v37, vcc, 0, v45, vcc
	v_add_co_u32_e32 v46, vcc, s73, v44
	v_or_b32_e32 v32, 1, v40
	s_nop 0
	v_addc_co_u32_e32 v47, vcc, 0, v45, vcc
	global_load_dwordx4 v[16:19], v[36:37], off offset:1024 nt
	global_load_dwordx4 v[20:23], v[36:37], off offset:2048 nt
	global_load_dwordx4 v[24:27], v[46:47], off offset:-4096 nt
	s_nop 0
	global_load_dwordx4 v[36:39], v[36:37], off offset:3072 nt
	v_lshlrev_b64 v[78:79], 9, v[32:33]
	v_or_b32_e32 v32, 2, v40
	v_mov_b32_e32 v41, v33
	v_lshl_add_u64 v[82:83], v[42:43], 0, v[78:79]
	v_lshlrev_b64 v[78:79], 9, v[32:33]
	v_or_b32_e32 v32, 3, v40
	v_lshlrev_b64 v[48:49], 9, v[40:41]
	v_lshlrev_b64 v[40:41], 9, v[32:33]
	v_lshl_add_u64 v[48:49], v[42:43], 0, v[48:49]
	v_lshl_add_u64 v[84:85], v[42:43], 0, v[78:79]
	v_lshl_add_u64 v[86:87], v[42:43], 0, v[40:41]
	v_add_co_u32_e32 v44, vcc, s77, v44
	s_waitcnt vmcnt(6)
	v_cvt_pk_bf16_f32 v40, v0, v4
	v_cvt_pk_bf16_f32 v0, v1, v5
	s_waitcnt vmcnt(4)
	v_cvt_pk_bf16_f32 v41, v8, v12
	v_cvt_pk_bf16_f32 v1, v9, v13
	v_cvt_pk_bf16_f32 v4, v2, v6
	v_cvt_pk_bf16_f32 v5, v10, v14
	v_cvt_pk_bf16_f32 v8, v3, v7
	v_cvt_pk_bf16_f32 v9, v11, v15
	v_addc_co_u32_e32 v45, vcc, 0, v45, vcc
	s_waitcnt vmcnt(1)
	v_cvt_pk_bf16_f32 v42, v24, v16
	s_waitcnt vmcnt(0)
	v_cvt_pk_bf16_f32 v43, v20, v36
	v_cvt_pk_bf16_f32 v2, v25, v17
	v_cvt_pk_bf16_f32 v3, v21, v37
	v_cvt_pk_bf16_f32 v6, v26, v18
	v_cvt_pk_bf16_f32 v7, v22, v38
	v_cvt_pk_bf16_f32 v10, v27, v19
	v_cvt_pk_bf16_f32 v11, v23, v39
	global_store_dwordx4 v[48:49], v[40:43], off
	global_store_dwordx4 v[82:83], v[0:3], off
	global_store_dwordx4 v[84:85], v[4:7], off
	global_store_dwordx4 v[86:87], v[8:11], off
	global_load_dwordx4 v[0:3], v[46:47], off nt
	s_nop 0
	global_load_dwordx4 v[4:7], v[46:47], off offset:1024 nt
	global_load_dwordx4 v[8:11], v[46:47], off offset:2048 nt
	global_load_dwordx4 v[12:15], v[46:47], off offset:3072 nt
	global_load_dwordx4 v[16:19], v[44:45], off nt
	global_load_dwordx4 v[20:23], v[44:45], off offset:1024 nt
	global_load_dwordx4 v[24:27], v[44:45], off offset:2048 nt
	global_load_dwordx4 v[36:39], v[44:45], off offset:3072 nt
	s_waitcnt vmcnt(6)
	v_cvt_pk_bf16_f32 v40, v0, v4
	v_cvt_pk_bf16_f32 v44, v1, v5
	s_waitcnt vmcnt(4)
	v_cvt_pk_bf16_f32 v41, v8, v12
	v_cvt_pk_bf16_f32 v45, v9, v13
	s_waitcnt vmcnt(2)
	v_cvt_pk_bf16_f32 v42, v16, v20
	v_cvt_pk_bf16_f32 v46, v17, v21
	s_waitcnt vmcnt(0)
	v_cvt_pk_bf16_f32 v43, v24, v36
	v_cvt_pk_bf16_f32 v47, v25, v37
	v_cvt_pk_bf16_f32 v78, v2, v6
	v_cvt_pk_bf16_f32 v79, v10, v14
	v_cvt_pk_bf16_f32 v80, v18, v22
	v_cvt_pk_bf16_f32 v81, v26, v38
	v_cvt_pk_bf16_f32 v0, v3, v7
	v_cvt_pk_bf16_f32 v1, v11, v15
	v_cvt_pk_bf16_f32 v2, v19, v23
	v_cvt_pk_bf16_f32 v3, v27, v39
	global_store_dwordx4 v[48:49], v[40:43], off offset:16
	global_store_dwordx4 v[82:83], v[44:47], off offset:16
	global_store_dwordx4 v[84:85], v[78:81], off offset:16
	global_store_dwordx4 v[86:87], v[0:3], off offset:16

; __device__ __forceinline__ unsigned pk2(float lo, float hi) { f32x2 v = {lo, hi}; bf16x2_t b = __builtin_convertvector(v, bf16x2_t); return __builtin_bit_cast(unsigned, b); }
; __device__ __forceinline__ void p0_cvt_item(const float* W, int K, int N, bf16_t* WT, int row_off, const float* gain, int item, int lane) {
;     const int nblk = N / 256, kb = item / nblk, nb = item % nblk, k0 = 16 * kb, n0 = 256 * nb + 4 * lane;
; #pragma unroll
;     for (int kk = 0; kk < 16; kk += 8) {
;         f32x4 v[8];
; #pragma unroll
;         for (int j = 0; j < 8; ++j) { const float gk = gain ? gain[k0 + kk + j] : 1.f; v[j] = *(const f32x4*)(W + (size_t)(k0 + kk + j) * N + n0) * gk; }
; #pragma unroll
;         for (int c = 0; c < 4; ++c) { u32x4 o; o.x = pk2(v[0][c], v[1][c]); o.y = pk2(v[2][c], v[3][c]); o.z = pk2(v[4][c], v[5][c]); o.w = pk2(v[6][c], v[7][c]);
;             *(u32x4*)(WT + (size_t)(row_off + n0 + c) * K + k0 + kk) = o; }
;     }
; __device__ __forceinline__ void p0_phase(const Args& a, LAS unsigned char* lds, int G, int wg, int part, bool split) {
;     ...
;         if (r < I_SQ) { p0_cvt_item(a.in[9], DM, DM, (bf16_t*)(ws + WS_BOUT), 0, nullptr, r, lane); continue; } r -= I_SQ;
.LBB0_81:
	s_andn2_saveexec_b64 s[4:5], s[58:59]
	s_cbranch_execz .LBB0_83
	v_and_or_b32 v40, v31, s72, v28
	v_readlane_b32 s8, v252, 16
	v_and_b32_e32 v2, 0x3f0, v29
	v_lshlrev_b32_e32 v32, 2, v40
	v_readlane_b32 s10, v252, 18
	v_readlane_b32 s11, v252, 19
	v_mov_b32_e32 v81, v33
	v_readlane_b32 s9, v252, 17
	v_lshl_add_u64 v[0:1], s[10:11], 0, v[32:33]
	v_lshlrev_b32_e32 v32, 1, v2
	v_lshl_add_u64 v[48:49], s[30:31], 0, v[32:33]
	v_lshlrev_b32_e32 v32, 12, v2
	v_lshl_add_u64 v[78:79], v[0:1], 0, v[32:33]
	v_add_co_u32_e32 v4, vcc, 0x1000, v78
	v_lshlrev_b32_e32 v32, 11, v40
	s_nop 0
	v_addc_co_u32_e32 v5, vcc, 0, v79, vcc
	v_add_co_u32_e32 v8, vcc, s73, v78
	global_load_dwordx4 v[0:3], v[78:79], off nt
	s_nop 0
	global_load_dwordx4 v[4:7], v[4:5], off nt
	v_addc_co_u32_e32 v9, vcc, 0, v79, vcc
	v_add_co_u32_e32 v12, vcc, 0x3000, v78
	v_lshl_add_u64 v[82:83], v[48:49], 0, v[32:33]
	s_nop 0
	v_addc_co_u32_e32 v13, vcc, 0, v79, vcc
	v_add_co_u32_e32 v16, vcc, s74, v78
	global_load_dwordx4 v[8:11], v[8:9], off nt
	s_nop 0
	global_load_dwordx4 v[12:15], v[12:13], off nt
	v_addc_co_u32_e32 v17, vcc, 0, v79, vcc
	v_add_co_u32_e32 v20, vcc, 0x5000, v78
	v_or_b32_e32 v80, 0x1000, v32
	s_nop 0
	v_addc_co_u32_e32 v21, vcc, 0, v79, vcc
	v_add_co_u32_e32 v24, vcc, s75, v78
	global_load_dwordx4 v[16:19], v[16:17], off nt
	s_nop 0
	global_load_dwordx4 v[20:23], v[20:21], off nt
	v_addc_co_u32_e32 v25, vcc, 0, v79, vcc
	v_add_co_u32_e32 v36, vcc, 0x7000, v78
	v_or_b32_e32 v32, 0x1800, v32
	s_nop 0
	v_addc_co_u32_e32 v37, vcc, 0, v79, vcc
	global_load_dwordx4 v[24:27], v[24:25], off nt
	s_nop 0
	global_load_dwordx4 v[36:39], v[36:37], off nt
	v_add_co_u32_e32 v84, vcc, s78, v78
	v_lshl_add_u64 v[90:91], v[48:49], 0, v[80:81]
	s_nop 0
	v_addc_co_u32_e32 v85, vcc, 0, v79, vcc
	v_add_co_u32_e32 v86, vcc, s79, v78
	v_lshl_add_u64 v[92:93], v[48:49], 0, v[32:33]
	s_nop 0
	v_addc_co_u32_e32 v87, vcc, 0, v79, vcc
	v_add_co_u32_e32 v88, vcc, s80, v78
	v_readlane_b32 s12, v252, 20
	s_nop 0
	v_addc_co_u32_e32 v89, vcc, 0, v79, vcc
	v_readlane_b32 s13, v252, 21
	v_readlane_b32 s14, v252, 22
	v_readlane_b32 s15, v252, 23
	v_readlane_b32 s16, v252, 24
	v_readlane_b32 s17, v252, 25
	v_readlane_b32 s18, v252, 26
	v_readlane_b32 s19, v252, 27
	v_readlane_b32 s20, v252, 28
	v_readlane_b32 s21, v252, 29
	v_readlane_b32 s22, v252, 30
	v_readlane_b32 s23, v252, 31
	s_waitcnt vmcnt(6)
	v_cvt_pk_bf16_f32 v0, v0, v4
	v_cvt_pk_bf16_f32 v4, v1, v5
	v_cvt_pk_bf16_f32 v40, v2, v6
	v_cvt_pk_bf16_f32 v44, v3, v7
	s_waitcnt vmcnt(4)
	v_cvt_pk_bf16_f32 v1, v8, v12
	v_cvt_pk_bf16_f32 v5, v9, v13
	v_cvt_pk_bf16_f32 v41, v10, v14
	v_cvt_pk_bf16_f32 v45, v11, v15
	s_waitcnt vmcnt(2)
	v_cvt_pk_bf16_f32 v2, v16, v20
	v_cvt_pk_bf16_f32 v6, v17, v21
	v_cvt_pk_bf16_f32 v42, v18, v22
	v_cvt_pk_bf16_f32 v46, v19, v23
	s_waitcnt vmcnt(0)
	v_cvt_pk_bf16_f32 v3, v24, v36
	v_add_co_u32_e32 v36, vcc, s81, v78
	v_cvt_pk_bf16_f32 v7, v25, v37
	v_cvt_pk_bf16_f32 v43, v26, v38
	v_cvt_pk_bf16_f32 v47, v27, v39
	global_store_dwordx4 v[82:83], v[0:3], off
	global_store_dwordx4 v[82:83], v[4:7], off offset:2048
	global_store_dwordx4 v[90:91], v[40:43], off
	global_store_dwordx4 v[92:93], v[44:47], off
	v_addc_co_u32_e32 v37, vcc, 0, v79, vcc
	global_load_dwordx4 v[0:3], v[84:85], off offset:-4096 nt
	global_load_dwordx4 v[4:7], v[84:85], off nt
	global_load_dwordx4 v[8:11], v[86:87], off offset:-4096 nt
	global_load_dwordx4 v[12:15], v[86:87], off nt
	global_load_dwordx4 v[16:19], v[88:89], off offset:-4096 nt
	global_load_dwordx4 v[20:23], v[88:89], off nt
	global_load_dwordx4 v[24:27], v[36:37], off offset:-4096 nt
	s_nop 0
	global_load_dwordx4 v[36:39], v[36:37], off nt
	v_lshl_add_u64 v[40:41], v[48:49], 0, 16
	v_lshl_add_u64 v[48:49], v[40:41], 0, v[80:81]
	v_lshl_add_u64 v[84:85], v[40:41], 0, v[32:33]
	s_waitcnt vmcnt(6)
	v_cvt_pk_bf16_f32 v40, v0, v4
	v_cvt_pk_bf16_f32 v44, v1, v5
	s_waitcnt vmcnt(4)
	v_cvt_pk_bf16_f32 v41, v8, v12
	v_cvt_pk_bf16_f32 v45, v9, v13
	s_waitcnt vmcnt(2)
	v_cvt_pk_bf16_f32 v42, v16, v20
	s_waitcnt vmcnt(0)
	v_cvt_pk_bf16_f32 v43, v24, v36
	v_cvt_pk_bf16_f32 v46, v17, v21
	v_cvt_pk_bf16_f32 v47, v25, v37
	v_cvt_pk_bf16_f32 v78, v2, v6
	v_cvt_pk_bf16_f32 v79, v10, v14
	v_cvt_pk_bf16_f32 v80, v18, v22
	v_cvt_pk_bf16_f32 v81, v26, v38
	v_cvt_pk_bf16_f32 v0, v3, v7
	v_cvt_pk_bf16_f32 v1, v11, v15
	v_cvt_pk_bf16_f32 v2, v19, v23
	v_cvt_pk_bf16_f32 v3, v27, v39
	global_store_dwordx4 v[82:83], v[40:43], off offset:16
	global_store_dwordx4 v[82:83], v[44:47], off offset:2064
	global_store_dwordx4 v[48:49], v[78:81], off
	global_store_dwordx4 v[84:85], v[0:3], off

; __device__ __forceinline__ unsigned pk2(float lo, float hi) { f32x2 v = {lo, hi}; bf16x2_t b = __builtin_convertvector(v, bf16x2_t); return __builtin_bit_cast(unsigned, b); }
; __device__ __forceinline__ void p0_cvt_item(const float* W, int K, int N, bf16_t* WT, int row_off, const float* gain, int item, int lane) {
;     const int nblk = N / 256, kb = item / nblk, nb = item % nblk, k0 = 16 * kb, n0 = 256 * nb + 4 * lane;
; #pragma unroll
;     for (int kk = 0; kk < 16; kk += 8) {
;         f32x4 v[8];
; #pragma unroll
;         for (int j = 0; j < 8; ++j) { const float gk = gain ? gain[k0 + kk + j] : 1.f; v[j] = *(const f32x4*)(W + (size_t)(k0 + kk + j) * N + n0) * gk; }
; #pragma unroll
;         for (int c = 0; c < 4; ++c) { u32x4 o; o.x = pk2(v[0][c], v[1][c]); o.y = pk2(v[2][c], v[3][c]); o.z = pk2(v[4][c], v[5][c]); o.w = pk2(v[6][c], v[7][c]);
;             *(u32x4*)(WT + (size_t)(row_off + n0 + c) * K + k0 + kk) = o; }
; __device__ __forceinline__ void p0_phase(const Args& a, LAS unsigned char* lds, int G, int wg, int part, bool split) {
;     ...
;         if (r < I_QKV) { p0_cvt_item(a.in[8], DM, 3072, (bf16_t*)(ws + WS_BQKV), 0, norm_mix + 1 * DM, r, lane); continue; } r -= I_QKV;
.LBB0_84:
	s_andn2_saveexec_b64 s[4:5], s[56:57]
	s_cbranch_execz .LBB0_86
	v_add_u16_e32 v0, 0xf700, v0
	v_mul_u32_u24_e32 v1, 0xaaab, v0
	v_lshrrev_b32_e32 v50, 19, v1
	v_mul_lo_u16_e32 v1, 12, v50
	v_sub_u16_sdwa v0, v0, v1 dst_sel:BYTE_1 dst_unused:UNUSED_PAD src0_sel:DWORD src1_sel:DWORD
	v_readlane_b32 s8, v252, 16
	v_or_b32_e32 v52, v28, v0
	v_lshlrev_b32_e32 v54, 4, v50
	v_lshlrev_b32_e32 v32, 2, v52
	v_readlane_b32 s9, v252, 17
	v_lshlrev_b32_e32 v4, 6, v50
	v_or_b32_e32 v10, 1, v54
	v_lshl_add_u64 v[48:49], s[8:9], 0, v[32:33]
	v_or_b32_e32 v32, 6, v54
	v_or_b32_e32 v16, 2, v54
	v_or_b32_e32 v18, 3, v54
	v_or_b32_e32 v24, 4, v54
	v_or_b32_e32 v26, 5, v54
	v_mad_u64_u32 v[40:41], s[56:57], v32, s77, v[48:49]
	v_or_b32_e32 v32, 7, v54
	global_load_dwordx4 v[0:3], v4, s[36:37] offset:16
	s_nop 0
	global_load_dwordx4 v[4:7], v4, s[36:37]
	v_mad_u64_u32 v[8:9], s[56:57], v54, s77, v[48:49]
	v_mad_u64_u32 v[12:13], s[56:57], v10, s77, v[48:49]
	v_mad_u64_u32 v[16:17], s[56:57], v16, s77, v[48:49]
	v_mad_u64_u32 v[20:21], s[56:57], v18, s77, v[48:49]
	v_mad_u64_u32 v[24:25], s[56:57], v24, s77, v[48:49]
	v_mad_u64_u32 v[36:37], s[56:57], v26, s77, v[48:49]
	v_mad_u64_u32 v[44:45], s[56:57], v32, s77, v[48:49]
	global_load_dwordx4 v[8:11], v[8:9], off nt
	s_nop 0
	global_load_dwordx4 v[12:15], v[12:13], off nt
	s_nop 0
	global_load_dwordx4 v[16:19], v[16:17], off nt
	s_nop 0
	global_load_dwordx4 v[20:23], v[20:21], off nt
	s_nop 0
	global_load_dwordx4 v[24:27], v[24:25], off nt
	s_nop 0
	global_load_dwordx4 v[36:39], v[36:37], off nt
	v_lshlrev_b32_e32 v32, 5, v50
	global_load_dwordx4 v[40:43], v[40:41], off nt
	v_lshl_add_u64 v[80:81], s[34:35], 0, v[32:33]
	global_load_dwordx4 v[44:47], v[44:45], off nt
	v_lshlrev_b32_e32 v32, 11, v52
	v_mov_b32_e32 v79, v33
	v_lshl_add_u64 v[82:83], v[80:81], 0, v[32:33]
	v_or_b32_e32 v78, 0x1000, v32
	v_or_b32_e32 v32, 0x1800, v32
	v_lshl_add_u64 v[84:85], v[80:81], 0, v[78:79]
	v_lshl_add_u64 v[86:87], v[80:81], 0, v[32:33]
	v_or_b32_e32 v56, 8, v54
	v_lshlrev_b32_e32 v58, 2, v56
	v_readlane_b32 s10, v252, 18
	v_readlane_b32 s11, v252, 19
	v_readlane_b32 s12, v252, 20
	v_readlane_b32 s13, v252, 21
	v_readlane_b32 s14, v252, 22
	v_readlane_b32 s15, v252, 23
	v_readlane_b32 s16, v252, 24
	v_readlane_b32 s17, v252, 25
	v_readlane_b32 s18, v252, 26
	v_readlane_b32 s19, v252, 27
	v_readlane_b32 s20, v252, 28
	v_readlane_b32 s21, v252, 29
	v_readlane_b32 s22, v252, 30
	v_readlane_b32 s23, v252, 31
	s_waitcnt vmcnt(9)
	v_mov_b32_e32 v52, v3
	s_waitcnt vmcnt(8)
	v_mov_b32_e32 v50, v7
	s_waitcnt vmcnt(7)
	v_pk_mul_f32 v[88:89], v[10:11], v[4:5] op_sel_hi:[1,0]
	v_pk_mul_f32 v[8:9], v[8:9], v[4:5] op_sel_hi:[1,0]
	s_waitcnt vmcnt(6)
	v_pk_mul_f32 v[14:15], v[14:15], v[4:5] op_sel:[0,1]
	v_pk_mul_f32 v[4:5], v[12:13], v[4:5] op_sel:[0,1]
	s_waitcnt vmcnt(5)
	v_pk_mul_f32 v[12:13], v[18:19], v[6:7] op_sel_hi:[1,0]
	v_pk_mul_f32 v[6:7], v[16:17], v[6:7] op_sel_hi:[1,0]
	s_waitcnt vmcnt(4)
	v_pk_mul_f32 v[10:11], v[20:21], v[50:51] op_sel_hi:[1,0]
	s_waitcnt vmcnt(3)
	v_pk_mul_f32 v[20:21], v[24:25], v[0:1] op_sel_hi:[1,0]
	s_waitcnt vmcnt(2)
	v_pk_mul_f32 v[24:25], v[36:37], v[0:1] op_sel:[0,1]
	s_waitcnt vmcnt(1)
	v_pk_mul_f32 v[36:37], v[40:41], v[2:3] op_sel_hi:[1,0]
	s_waitcnt vmcnt(0)
; __device__ __forceinline__ unsigned pk2(float lo, float hi) { f32x2 v = {lo, hi}; bf16x2_t b = __builtin_convertvector(v, bf16x2_t); return __builtin_bit_cast(unsigned, b); }
; __device__ __forceinline__ void p0_cvt_item(const float* W, int K, int N, bf16_t* WT, int row_off, const float* gain, int item, int lane) {
;     const int nblk = N / 256, kb = item / nblk, nb = item % nblk, k0 = 16 * kb, n0 = 256 * nb + 4 * lane;
; #pragma unroll
;     for (int kk = 0; kk < 16; kk += 8) {
;         f32x4 v[8];
; #pragma unroll
;         for (int j = 0; j < 8; ++j) { const float gk = gain ? gain[k0 + kk + j] : 1.f; v[j] = *(const f32x4*)(W + (size_t)(k0 + kk + j) * N + n0) * gk; }
; #pragma unroll
;         for (int c = 0; c < 4; ++c) { u32x4 o; o.x = pk2(v[0][c], v[1][c]); o.y = pk2(v[2][c], v[3][c]); o.z = pk2(v[4][c], v[5][c]); o.w = pk2(v[6][c], v[7][c]);
;             *(u32x4*)(WT + (size_t)(row_off + n0 + c) * K + k0 + kk) = o; }
; __device__ __forceinline__ void p0_phase(const Args& a, LAS unsigned char* lds, int G, int wg, int part, bool split) {
;     ...
;         if (r < I_QKV) { p0_cvt_item(a.in[8], DM, 3072, (bf16_t*)(ws + WS_BQKV), 0, norm_mix + 1 * DM, r, lane); continue; } r -= I_QKV;
	v_pk_mul_f32 v[40:41], v[44:45], v[52:53] op_sel_hi:[1,0]
	v_pk_mul_f32 v[16:17], v[22:23], v[50:51] op_sel_hi:[1,0]
	v_pk_mul_f32 v[18:19], v[26:27], v[0:1] op_sel_hi:[1,0]
	v_pk_mul_f32 v[22:23], v[38:39], v[0:1] op_sel:[0,1]
	v_pk_mul_f32 v[26:27], v[42:43], v[2:3] op_sel_hi:[1,0]
	v_pk_mul_f32 v[38:39], v[46:47], v[52:53] op_sel_hi:[1,0]
	v_cvt_pk_bf16_f32 v0, v8, v4
	v_cvt_pk_bf16_f32 v1, v6, v10
	v_cvt_pk_bf16_f32 v2, v20, v24
	v_cvt_pk_bf16_f32 v3, v36, v40
	v_cvt_pk_bf16_f32 v8, v88, v14
	v_cvt_pk_bf16_f32 v4, v9, v5
	v_cvt_pk_bf16_f32 v5, v7, v11
	v_cvt_pk_bf16_f32 v6, v21, v25
	v_cvt_pk_bf16_f32 v7, v37, v41
	v_cvt_pk_bf16_f32 v9, v12, v16
	v_cvt_pk_bf16_f32 v10, v18, v22
	v_cvt_pk_bf16_f32 v11, v26, v38
	v_cvt_pk_bf16_f32 v12, v89, v15
	v_cvt_pk_bf16_f32 v13, v13, v17
	v_cvt_pk_bf16_f32 v14, v19, v23
	v_cvt_pk_bf16_f32 v15, v27, v39
	global_store_dwordx4 v[82:83], v[0:3], off
	global_store_dwordx4 v[82:83], v[4:7], off offset:2048
	global_store_dwordx4 v[84:85], v[8:11], off
	global_store_dwordx4 v[86:87], v[12:15], off
	v_or_b32_e32 v20, 10, v54
	v_or_b32_e32 v8, 9, v54
	v_mad_u64_u32 v[36:37], s[56:57], v8, s77, v[48:49]
	v_or_b32_e32 v8, 12, v54
	v_mad_u64_u32 v[12:13], s[56:57], v8, s77, v[48:49]
	v_or_b32_e32 v8, 13, v54
	v_mad_u64_u32 v[16:17], s[56:57], v8, s77, v[48:49]
	v_or_b32_e32 v8, 14, v54
	v_mad_u64_u32 v[8:9], s[56:57], v8, s77, v[48:49]
	v_or_b32_e32 v40, 11, v54
	v_or_b32_e32 v44, 15, v54
	global_load_dwordx4 v[0:3], v58, s[36:37] offset:16
	global_load_dwordx4 v[4:7], v58, s[36:37]
	v_mad_u64_u32 v[24:25], s[56:57], v56, s77, v[48:49]
	global_load_dwordx4 v[8:11], v[8:9], off nt
	s_nop 0
	global_load_dwordx4 v[12:15], v[12:13], off nt
	s_nop 0
	global_load_dwordx4 v[16:19], v[16:17], off nt
	v_mad_u64_u32 v[20:21], s[56:57], v20, s77, v[48:49]
	v_mad_u64_u32 v[40:41], s[56:57], v40, s77, v[48:49]
	v_mad_u64_u32 v[44:45], s[56:57], v44, s77, v[48:49]
	global_load_dwordx4 v[20:23], v[20:21], off nt
	s_nop 0
	global_load_dwordx4 v[24:27], v[24:25], off nt
	s_nop 0
	global_load_dwordx4 v[36:39], v[36:37], off nt
	v_lshl_add_u64 v[48:49], v[80:81], 0, 16
	global_load_dwordx4 v[40:43], v[40:41], off nt
	v_lshl_add_u64 v[78:79], v[48:49], 0, v[78:79]
	global_load_dwordx4 v[44:47], v[44:45], off nt
	v_lshl_add_u64 v[48:49], v[48:49], 0, v[32:33]
	s_waitcnt vmcnt(7)
	v_pk_mul_f32 v[80:81], v[10:11], v[2:3] op_sel_hi:[1,0]
	v_pk_mul_f32 v[84:85], v[8:9], v[2:3] op_sel_hi:[1,0]
	s_waitcnt vmcnt(5)
	v_pk_mul_f32 v[10:11], v[18:19], v[0:1] op_sel:[0,1]
	v_pk_mul_f32 v[8:9], v[16:17], v[0:1] op_sel:[0,1]
	v_pk_mul_f32 v[14:15], v[14:15], v[0:1] op_sel_hi:[1,0]
	v_pk_mul_f32 v[12:13], v[12:13], v[0:1] op_sel_hi:[1,0]
	v_mov_b32_e32 v0, v7
	v_mov_b32_e32 v2, v3
	s_waitcnt vmcnt(4)
	v_pk_mul_f32 v[16:17], v[22:23], v[6:7] op_sel_hi:[1,0]
	v_pk_mul_f32 v[18:19], v[20:21], v[6:7] op_sel_hi:[1,0]
	s_waitcnt vmcnt(2)
	v_pk_mul_f32 v[20:21], v[38:39], v[4:5] op_sel:[0,1]
	v_pk_mul_f32 v[6:7], v[36:37], v[4:5] op_sel:[0,1]
	v_pk_mul_f32 v[22:23], v[26:27], v[4:5] op_sel_hi:[1,0]
	v_pk_mul_f32 v[4:5], v[24:25], v[4:5] op_sel_hi:[1,0]
	s_waitcnt vmcnt(1)
	v_pk_mul_f32 v[26:27], v[40:41], v[0:1] op_sel_hi:[1,0]
	s_waitcnt vmcnt(0)
	v_pk_mul_f32 v[38:39], v[44:45], v[2:3] op_sel_hi:[1,0]
	v_pk_mul_f32 v[24:25], v[42:43], v[0:1] op_sel_hi:[1,0]
	v_pk_mul_f32 v[36:37], v[46:47], v[2:3] op_sel_hi:[1,0]
	v_cvt_pk_bf16_f32 v0, v4, v6
	v_cvt_pk_bf16_f32 v2, v12, v8
	v_cvt_pk_bf16_f32 v1, v18, v26
	v_cvt_pk_bf16_f32 v3, v84, v38
	v_cvt_pk_bf16_f32 v4, v5, v7
	v_cvt_pk_bf16_f32 v6, v13, v9
	v_cvt_pk_bf16_f32 v8, v22, v20
	v_cvt_pk_bf16_f32 v10, v14, v10
	v_cvt_pk_bf16_f32 v12, v23, v21
	v_cvt_pk_bf16_f32 v14, v15, v11
	v_cvt_pk_bf16_f32 v5, v19, v27
	v_cvt_pk_bf16_f32 v7, v85, v39
	v_cvt_pk_bf16_f32 v9, v16, v24
	v_cvt_pk_bf16_f32 v11, v80, v36
	v_cvt_pk_bf16_f32 v13, v17, v25
	v_cvt_pk_bf16_f32 v15, v81, v37
	global_store_dwordx4 v[82:83], v[0:3], off offset:16
	global_store_dwordx4 v[82:83], v[4:7], off offset:2064
	global_store_dwordx4 v[78:79], v[8:11], off
	global_store_dwordx4 v[48:49], v[12:15], off

; __device__ __forceinline__ unsigned pk2(float lo, float hi) { f32x2 v = {lo, hi}; bf16x2_t b = __builtin_convertvector(v, bf16x2_t); return __builtin_bit_cast(unsigned, b); }
; __device__ __forceinline__ void p0_cvt_item(const float* W, int K, int N, bf16_t* WT, int row_off, const float* gain, int item, int lane) {
;     const int nblk = N / 256, kb = item / nblk, nb = item % nblk, k0 = 16 * kb, n0 = 256 * nb + 4 * lane;
; #pragma unroll
;     for (int kk = 0; kk < 16; kk += 8) {
;         f32x4 v[8];
; #pragma unroll
;         for (int j = 0; j < 8; ++j) { const float gk = gain ? gain[k0 + kk + j] : 1.f; v[j] = *(const f32x4*)(W + (size_t)(k0 + kk + j) * N + n0) * gk; }
; #pragma unroll
;         for (int c = 0; c < 4; ++c) { u32x4 o; o.x = pk2(v[0][c], v[1][c]); o.y = pk2(v[2][c], v[3][c]); o.z = pk2(v[4][c], v[5][c]); o.w = pk2(v[6][c], v[7][c]);
;             *(u32x4*)(WT + (size_t)(row_off + n0 + c) * K + k0 + kk) = o; }
; __device__ __forceinline__ void p0_phase(const Args& a, LAS unsigned char* lds, int G, int wg, int part, bool split) {
;     ...
;         if (r < I_SQ) { p0_cvt_item(a.in[7], DM, DM, (bf16_t*)(ws + WS_AWOUT), 0, nullptr, r, lane); continue; } r -= I_SQ;
;         if (r < I_QKV) { p0_cvt_item(a.in[8], DM, 3072, (bf16_t*)(ws + WS_BQKV), 0, norm_mix + 1 * DM, r, lane); continue; } r -= I_QKV;
;         if (r < I_SQ) { p0_cvt_item(a.in[9], DM, DM, (bf16_t*)(ws + WS_BOUT), 0, nullptr, r, lane); continue; } r -= I_SQ;
.LBB0_87:
	s_andn2_saveexec_b64 s[4:5], s[54:55]
	s_cbranch_execz .LBB0_89
	v_and_or_b32 v40, v31, s72, v28
	v_readlane_b32 s8, v252, 0
	v_and_b32_e32 v2, 0x3f0, v29
	v_lshlrev_b32_e32 v32, 2, v40
	v_readlane_b32 s22, v252, 14
	v_readlane_b32 s23, v252, 15
	v_mov_b32_e32 v81, v33
	v_readlane_b32 s9, v252, 1
	v_lshl_add_u64 v[0:1], s[22:23], 0, v[32:33]
	v_lshlrev_b32_e32 v32, 1, v2
	v_lshl_add_u64 v[48:49], s[38:39], 0, v[32:33]
	v_lshlrev_b32_e32 v32, 12, v2
	v_lshl_add_u64 v[78:79], v[0:1], 0, v[32:33]
	v_add_co_u32_e32 v4, vcc, 0x1000, v78
	v_lshlrev_b32_e32 v32, 11, v40
	s_nop 0
	v_addc_co_u32_e32 v5, vcc, 0, v79, vcc
	v_add_co_u32_e32 v8, vcc, s73, v78
	global_load_dwordx4 v[0:3], v[78:79], off nt
	s_nop 0
	global_load_dwordx4 v[4:7], v[4:5], off nt
	v_addc_co_u32_e32 v9, vcc, 0, v79, vcc
	v_add_co_u32_e32 v12, vcc, 0x3000, v78
	v_lshl_add_u64 v[82:83], v[48:49], 0, v[32:33]
	s_nop 0
	v_addc_co_u32_e32 v13, vcc, 0, v79, vcc
	v_add_co_u32_e32 v16, vcc, s74, v78
	global_load_dwordx4 v[8:11], v[8:9], off nt
	s_nop 0
	global_load_dwordx4 v[12:15], v[12:13], off nt
	v_addc_co_u32_e32 v17, vcc, 0, v79, vcc
	v_add_co_u32_e32 v20, vcc, 0x5000, v78
	v_or_b32_e32 v80, 0x1000, v32
	s_nop 0
	v_addc_co_u32_e32 v21, vcc, 0, v79, vcc
	v_add_co_u32_e32 v24, vcc, s75, v78
	global_load_dwordx4 v[16:19], v[16:17], off nt
	s_nop 0
	global_load_dwordx4 v[20:23], v[20:21], off nt
	v_addc_co_u32_e32 v25, vcc, 0, v79, vcc
	v_add_co_u32_e32 v36, vcc, 0x7000, v78
	v_or_b32_e32 v32, 0x1800, v32
	s_nop 0
	v_addc_co_u32_e32 v37, vcc, 0, v79, vcc
	global_load_dwordx4 v[24:27], v[24:25], off nt
	s_nop 0
	global_load_dwordx4 v[36:39], v[36:37], off nt
	v_add_co_u32_e32 v84, vcc, s78, v78
	v_lshl_add_u64 v[90:91], v[48:49], 0, v[80:81]
	s_nop 0
	v_addc_co_u32_e32 v85, vcc, 0, v79, vcc
	v_add_co_u32_e32 v86, vcc, s79, v78
	v_lshl_add_u64 v[92:93], v[48:49], 0, v[32:33]
	s_nop 0
	v_addc_co_u32_e32 v87, vcc, 0, v79, vcc
	v_add_co_u32_e32 v88, vcc, s80, v78
	v_readlane_b32 s10, v252, 2
	s_nop 0
	v_addc_co_u32_e32 v89, vcc, 0, v79, vcc
	v_readlane_b32 s11, v252, 3
	v_readlane_b32 s12, v252, 4
	v_readlane_b32 s13, v252, 5
	v_readlane_b32 s14, v252, 6
	v_readlane_b32 s15, v252, 7
	v_readlane_b32 s16, v252, 8
	v_readlane_b32 s17, v252, 9
	v_readlane_b32 s18, v252, 10
	v_readlane_b32 s19, v252, 11
	v_readlane_b32 s20, v252, 12
	v_readlane_b32 s21, v252, 13
	s_waitcnt vmcnt(6)
	v_cvt_pk_bf16_f32 v0, v0, v4
	v_cvt_pk_bf16_f32 v4, v1, v5
	v_cvt_pk_bf16_f32 v40, v2, v6
	v_cvt_pk_bf16_f32 v44, v3, v7
	s_waitcnt vmcnt(4)
	v_cvt_pk_bf16_f32 v1, v8, v12
	v_cvt_pk_bf16_f32 v5, v9, v13
	v_cvt_pk_bf16_f32 v41, v10, v14
	v_cvt_pk_bf16_f32 v45, v11, v15
	s_waitcnt vmcnt(2)
	v_cvt_pk_bf16_f32 v2, v16, v20
	v_cvt_pk_bf16_f32 v6, v17, v21
	v_cvt_pk_bf16_f32 v42, v18, v22
	v_cvt_pk_bf16_f32 v46, v19, v23
	s_waitcnt vmcnt(0)
	v_cvt_pk_bf16_f32 v3, v24, v36
	v_add_co_u32_e32 v36, vcc, s81, v78
	v_cvt_pk_bf16_f32 v7, v25, v37
	v_cvt_pk_bf16_f32 v43, v26, v38
	v_cvt_pk_bf16_f32 v47, v27, v39
	global_store_dwordx4 v[82:83], v[0:3], off
	global_store_dwordx4 v[82:83], v[4:7], off offset:2048
	global_store_dwordx4 v[90:91], v[40:43], off
	global_store_dwordx4 v[92:93], v[44:47], off
	v_addc_co_u32_e32 v37, vcc, 0, v79, vcc
	global_load_dwordx4 v[0:3], v[84:85], off offset:-4096 nt
	global_load_dwordx4 v[4:7], v[84:85], off nt
	global_load_dwordx4 v[8:11], v[86:87], off offset:-4096 nt
	global_load_dwordx4 v[12:15], v[86:87], off nt
	global_load_dwordx4 v[16:19], v[88:89], off offset:-4096 nt
	global_load_dwordx4 v[20:23], v[88:89], off nt
	global_load_dwordx4 v[24:27], v[36:37], off offset:-4096 nt
	s_nop 0
	global_load_dwordx4 v[36:39], v[36:37], off nt
	v_lshl_add_u64 v[40:41], v[48:49], 0, 16
	v_lshl_add_u64 v[48:49], v[40:41], 0, v[80:81]
	v_lshl_add_u64 v[84:85], v[40:41], 0, v[32:33]
	s_waitcnt vmcnt(6)
	v_cvt_pk_bf16_f32 v40, v0, v4
	v_cvt_pk_bf16_f32 v44, v1, v5
	s_waitcnt vmcnt(4)
	v_cvt_pk_bf16_f32 v41, v8, v12
	v_cvt_pk_bf16_f32 v45, v9, v13
	s_waitcnt vmcnt(2)
	v_cvt_pk_bf16_f32 v42, v16, v20
	s_waitcnt vmcnt(0)
	v_cvt_pk_bf16_f32 v43, v24, v36
	v_cvt_pk_bf16_f32 v46, v17, v21
	v_cvt_pk_bf16_f32 v47, v25, v37
	v_cvt_pk_bf16_f32 v78, v2, v6
	v_cvt_pk_bf16_f32 v79, v10, v14
	v_cvt_pk_bf16_f32 v80, v18, v22
	v_cvt_pk_bf16_f32 v81, v26, v38
	v_cvt_pk_bf16_f32 v0, v3, v7
	v_cvt_pk_bf16_f32 v1, v11, v15
	v_cvt_pk_bf16_f32 v2, v19, v23
	v_cvt_pk_bf16_f32 v3, v27, v39
	global_store_dwordx4 v[82:83], v[40:43], off offset:16
	global_store_dwordx4 v[82:83], v[44:47], off offset:2064
	global_store_dwordx4 v[48:49], v[78:81], off
	global_store_dwordx4 v[84:85], v[0:3], off

; __device__ __forceinline__ void p0_cvt_item(const float* W, int K, int N, bf16_t* WT, int row_off, const float* gain, int item, int lane) {
;     const int nblk = N / 256, kb = item / nblk, nb = item % nblk, k0 = 16 * kb, n0 = 256 * nb + 4 * lane;
; #pragma unroll
;     for (int kk = 0; kk < 16; kk += 8) {
;         f32x4 v[8];
; #pragma unroll
;         for (int j = 0; j < 8; ++j) { const float gk = gain ? gain[k0 + kk + j] : 1.f; v[j] = *(const f32x4*)(W + (size_t)(k0 + kk + j) * N + n0) * gk; }
; #pragma unroll
; __device__ __forceinline__ void p0_phase(const Args& a, LAS unsigned char* lds, int G, int wg, int part, bool split) {
;     ...
;         if (r < 2 * I_AIN) { const int j = r / I_AIN; r -= j * I_AIN;
;             p0_cvt_item(a.in[4] + (size_t)j * DM * 4096, DM, 4096, (bf16_t*)(ws + WS_AWIN) + (size_t)j * 4096 * DM, 0, norm_mix + (3 * j) * DM, r, lane); continue; } r -= 2 * I_AIN;
.LBB0_93:
	v_ashrrev_i32_e32 v1, 4, v1
	v_lshlrev_b32_e32 v1, 4, v1
	v_ashrrev_i32_e32 v43, 31, v42
	v_readlane_b32 s8, v252, 0
	v_sub_u32_e32 v0, v0, v1
	v_lshlrev_b64 v[2:3], 24, v[42:43]
	v_readlane_b32 s16, v252, 8
	v_readlane_b32 s17, v252, 9
	v_lshl_or_b32 v44, v0, 8, v28
	v_ashrrev_i32_e32 v45, 31, v44
	v_lshl_add_u64 v[2:3], s[16:17], 0, v[2:3]
	v_lshl_add_u64 v[38:39], v[44:45], 2, v[2:3]
	v_lshlrev_b64 v[0:1], 14, v[36:37]
	v_lshl_add_u64 v[0:1], v[38:39], 0, v[0:1]
	global_load_dwordx4 v[0:3], v[0:1], off nt
	s_and_b64 vcc, exec, s[4:5]
	v_readlane_b32 s9, v252, 1
	v_readlane_b32 s10, v252, 2
	v_readlane_b32 s11, v252, 3
	v_readlane_b32 s12, v252, 4
	v_readlane_b32 s13, v252, 5
	v_readlane_b32 s14, v252, 6
	v_readlane_b32 s15, v252, 7
	v_readlane_b32 s18, v252, 10
	v_readlane_b32 s19, v252, 11
	v_readlane_b32 s20, v252, 12
	v_readlane_b32 s21, v252, 13
	v_readlane_b32 s22, v252, 14
	v_readlane_b32 s23, v252, 15
	s_cbranch_vccnz .LBB0_95
	global_load_dword v32, v[40:41], off offset:4
.LBB0_95:
	v_or_b32_e32 v4, 1, v36
	v_ashrrev_i32_e32 v5, 31, v4
	v_lshlrev_b64 v[4:5], 14, v[4:5]
	v_lshl_add_u64 v[4:5], v[38:39], 0, v[4:5]
	global_load_dwordx4 v[4:7], v[4:5], off nt
	v_mov_b32_e32 v48, 1.0
	s_and_b64 vcc, exec, s[4:5]
	v_mov_b32_e32 v52, 1.0
	s_cbranch_vccnz .LBB0_97
	global_load_dword v52, v[40:41], off offset:8
.LBB0_97:
	v_or_b32_e32 v8, 2, v36
	v_ashrrev_i32_e32 v9, 31, v8
	v_lshlrev_b64 v[8:9], 14, v[8:9]
	v_lshl_add_u64 v[8:9], v[38:39], 0, v[8:9]
	global_load_dwordx4 v[8:11], v[8:9], off nt
	s_and_b64 vcc, exec, s[4:5]
	s_cbranch_vccnz .LBB0_99
	global_load_dword v48, v[40:41], off offset:12
.LBB0_99:
	v_or_b32_e32 v12, 3, v36
	v_ashrrev_i32_e32 v13, 31, v12
	v_lshlrev_b64 v[12:13], 14, v[12:13]
	v_lshl_add_u64 v[12:13], v[38:39], 0, v[12:13]
	global_load_dwordx4 v[12:15], v[12:13], off nt
	v_mov_b32_e32 v54, 1.0
	s_and_b64 vcc, exec, s[4:5]
	v_mov_b32_e32 v56, 1.0
	s_cbranch_vccnz .LBB0_101
	global_load_dword v56, v[40:41], off offset:16
.LBB0_101:
	v_or_b32_e32 v16, 4, v36
	v_ashrrev_i32_e32 v17, 31, v16
	v_lshlrev_b64 v[16:17], 14, v[16:17]
	v_lshl_add_u64 v[16:17], v[38:39], 0, v[16:17]
	global_load_dwordx4 v[16:19], v[16:17], off nt
	s_and_b64 vcc, exec, s[4:5]
	s_cbranch_vccnz .LBB0_103
	global_load_dword v54, v[40:41], off offset:20
.LBB0_103:
	v_or_b32_e32 v20, 5, v36
	v_ashrrev_i32_e32 v21, 31, v20
	v_lshlrev_b64 v[20:21], 14, v[20:21]
	v_lshl_add_u64 v[20:21], v[38:39], 0, v[20:21]
	global_load_dwordx4 v[20:23], v[20:21], off nt
	v_mov_b32_e32 v50, 1.0
	s_and_b64 vcc, exec, s[4:5]
	v_mov_b32_e32 v58, 1.0
	s_cbranch_vccnz .LBB0_105
	global_load_dword v58, v[40:41], off offset:24
.LBB0_105:
	v_or_b32_e32 v24, 6, v36
	v_ashrrev_i32_e32 v25, 31, v24
	v_lshlrev_b64 v[24:25], 14, v[24:25]
	v_lshl_add_u64 v[24:25], v[38:39], 0, v[24:25]
	global_load_dwordx4 v[24:27], v[24:25], off nt
	s_and_b64 vcc, exec, s[4:5]
	s_cbranch_vccnz .LBB0_107
	global_load_dword v50, v[40:41], off offset:28
; __device__ __forceinline__ unsigned pk2(float lo, float hi) { f32x2 v = {lo, hi}; bf16x2_t b = __builtin_convertvector(v, bf16x2_t); return __builtin_bit_cast(unsigned, b); }
; __device__ __forceinline__ void p0_cvt_item(const float* W, int K, int N, bf16_t* WT, int row_off, const float* gain, int item, int lane) {
;     const int nblk = N / 256, kb = item / nblk, nb = item % nblk, k0 = 16 * kb, n0 = 256 * nb + 4 * lane;
; #pragma unroll
;     for (int kk = 0; kk < 16; kk += 8) {
;         f32x4 v[8];
; #pragma unroll
;         for (int j = 0; j < 8; ++j) { const float gk = gain ? gain[k0 + kk + j] : 1.f; v[j] = *(const f32x4*)(W + (size_t)(k0 + kk + j) * N + n0) * gk; }
; #pragma unroll
;         for (int c = 0; c < 4; ++c) { u32x4 o; o.x = pk2(v[0][c], v[1][c]); o.y = pk2(v[2][c], v[3][c]); o.z = pk2(v[4][c], v[5][c]); o.w = pk2(v[6][c], v[7][c]);
;             *(u32x4*)(WT + (size_t)(row_off + n0 + c) * K + k0 + kk) = o; }
; __device__ __forceinline__ void p0_phase(const Args& a, LAS unsigned char* lds, int G, int wg, int part, bool split) {
;     ...
;         if (r < 2 * I_AIN) { const int j = r / I_AIN; r -= j * I_AIN;
;             p0_cvt_item(a.in[4] + (size_t)j * DM * 4096, DM, 4096, (bf16_t*)(ws + WS_AWIN) + (size_t)j * 4096 * DM, 0, norm_mix + (3 * j) * DM, r, lane); continue; } r -= 2 * I_AIN;
.LBB0_107:
	v_or_b32_e32 v78, 7, v36
	v_ashrrev_i32_e32 v79, 31, v78
	v_lshlrev_b64 v[78:79], 14, v[78:79]
	v_lshl_add_u64 v[78:79], v[38:39], 0, v[78:79]
	global_load_dwordx4 v[78:81], v[78:79], off nt
	s_waitcnt vmcnt(7)
	v_pk_mul_f32 v[82:83], v[2:3], v[46:47] op_sel_hi:[1,0]
	v_pk_mul_f32 v[2:3], v[0:1], v[46:47] op_sel_hi:[1,0]
	v_lshlrev_b64 v[0:1], 23, v[42:43]
	v_or_b32_e32 v46, 1, v44
	s_waitcnt vmcnt(2)
	v_pk_mul_f32 v[22:23], v[22:23], v[54:55] op_sel_hi:[1,0]
	v_pk_mul_f32 v[20:21], v[20:21], v[54:55] op_sel_hi:[1,0]
	v_pk_mul_f32 v[18:19], v[18:19], v[56:57] op_sel_hi:[1,0]
	v_pk_mul_f32 v[16:17], v[16:17], v[56:57] op_sel_hi:[1,0]
	v_pk_mul_f32 v[14:15], v[14:15], v[48:49] op_sel_hi:[1,0]
	v_pk_mul_f32 v[12:13], v[12:13], v[48:49] op_sel_hi:[1,0]
	v_pk_mul_f32 v[10:11], v[10:11], v[52:53] op_sel_hi:[1,0]
	v_pk_mul_f32 v[8:9], v[8:9], v[52:53] op_sel_hi:[1,0]
	v_pk_mul_f32 v[4:5], v[4:5], v[32:33] op_sel_hi:[1,0]
	v_lshlrev_b64 v[42:43], 11, v[44:45]
	v_or_b32_e32 v84, 2, v44
	v_or_b32_e32 v44, 3, v44
	v_lshl_add_u64 v[86:87], s[40:41], 0, v[0:1]
	v_ashrrev_i32_e32 v47, 31, v46
	v_pk_mul_f32 v[48:49], v[6:7], v[32:33] op_sel_hi:[1,0]
	v_cvt_pk_bf16_f32 v0, v2, v4
	v_cvt_pk_bf16_f32 v2, v16, v20
	v_cvt_pk_bf16_f32 v4, v3, v5
	v_cvt_pk_bf16_f32 v5, v9, v13
	v_cvt_pk_bf16_f32 v6, v17, v21
	v_cvt_pk_bf16_f32 v9, v10, v14
	v_cvt_pk_bf16_f32 v10, v18, v22
	v_ashrrev_i32_e32 v85, 31, v84
	v_cvt_pk_bf16_f32 v14, v19, v23
	v_ashrrev_i32_e32 v45, 31, v44
	v_lshl_add_u64 v[16:17], v[36:37], 1, v[86:87]
	v_lshlrev_b64 v[18:19], 11, v[46:47]
	s_waitcnt vmcnt(1)
	v_pk_mul_f32 v[24:25], v[24:25], v[58:59] op_sel_hi:[1,0]
	v_lshlrev_b64 v[20:21], 11, v[84:85]
	v_lshlrev_b64 v[22:23], 11, v[44:45]
	v_lshl_add_u64 v[46:47], v[16:17], 0, v[18:19]
	v_pk_mul_f32 v[26:27], v[26:27], v[58:59] op_sel_hi:[1,0]
	v_mov_b32_e32 v32, 1.0
	s_and_b64 vcc, exec, s[4:5]
	v_cvt_pk_bf16_f32 v1, v8, v12
	v_cvt_pk_bf16_f32 v8, v82, v48
	v_cvt_pk_bf16_f32 v12, v83, v49
	v_lshl_add_u64 v[44:45], v[16:17], 0, v[42:43]
	v_lshl_add_u64 v[48:49], v[16:17], 0, v[20:21]
	v_lshl_add_u64 v[42:43], v[16:17], 0, v[22:23]
	v_cvt_pk_bf16_f32 v13, v11, v15
	s_waitcnt vmcnt(0)
	v_pk_mul_f32 v[18:19], v[78:79], v[50:51] op_sel_hi:[1,0]
	v_pk_mul_f32 v[16:17], v[80:81], v[50:51] op_sel_hi:[1,0]
	v_cvt_pk_bf16_f32 v3, v24, v18
	v_mov_b32_e32 v50, 1.0
	v_cvt_pk_bf16_f32 v7, v25, v19
	v_cvt_pk_bf16_f32 v11, v26, v16
	v_cvt_pk_bf16_f32 v15, v27, v17
	global_store_dwordx4 v[44:45], v[0:3], off
	global_store_dwordx4 v[46:47], v[4:7], off
	global_store_dwordx4 v[48:49], v[8:11], off
	global_store_dwordx4 v[42:43], v[12:15], off
	s_cbranch_vccnz .LBB0_109
	global_load_dword v50, v[40:41], off offset:32
.LBB0_109:
	v_or_b32_e32 v0, 8, v36
	v_ashrrev_i32_e32 v1, 31, v0
	v_lshlrev_b64 v[0:1], 14, v[0:1]
	v_lshl_add_u64 v[0:1], v[38:39], 0, v[0:1]
	global_load_dwordx4 v[0:3], v[0:1], off nt
	s_and_b64 vcc, exec, s[4:5]
	s_cbranch_vccnz .LBB0_111
	global_load_dword v32, v[40:41], off offset:36
.LBB0_111:
	v_or_b32_e32 v4, 9, v36
	v_ashrrev_i32_e32 v5, 31, v4
	v_lshlrev_b64 v[4:5], 14, v[4:5]
	v_lshl_add_u64 v[4:5], v[38:39], 0, v[4:5]
	global_load_dwordx4 v[4:7], v[4:5], off nt
	v_mov_b32_e32 v52, 1.0
	s_and_b64 vcc, exec, s[4:5]
	v_mov_b32_e32 v54, 1.0
	s_cbranch_vccnz .LBB0_113
	global_load_dword v54, v[40:41], off offset:40
.LBB0_113:
	v_or_b32_e32 v8, 10, v36
	v_ashrrev_i32_e32 v9, 31, v8
	v_lshlrev_b64 v[8:9], 14, v[8:9]
	v_lshl_add_u64 v[8:9], v[38:39], 0, v[8:9]
	global_load_dwordx4 v[8:11], v[8:9], off nt
	s_and_b64 vcc, exec, s[4:5]
	s_cbranch_vccnz .LBB0_115
	global_load_dword v52, v[40:41], off offset:44
.LBB0_115:
	v_or_b32_e32 v12, 11, v36
	v_ashrrev_i32_e32 v13, 31, v12
	v_lshlrev_b64 v[12:13], 14, v[12:13]
	v_lshl_add_u64 v[12:13], v[38:39], 0, v[12:13]
	global_load_dwordx4 v[12:15], v[12:13], off nt
	v_mov_b32_e32 v58, 1.0
	s_and_b64 vcc, exec, s[4:5]
	v_mov_b32_e32 v60, 1.0
	s_cbranch_vccnz .LBB0_117
	global_load_dword v60, v[40:41], off offset:48
.LBB0_117:
	v_or_b32_e32 v16, 12, v36
	v_ashrrev_i32_e32 v17, 31, v16
	v_lshlrev_b64 v[16:17], 14, v[16:17]
	v_lshl_add_u64 v[16:17], v[38:39], 0, v[16:17]
	global_load_dwordx4 v[16:19], v[16:17], off nt
	s_and_b64 vcc, exec, s[4:5]
	s_cbranch_vccnz .LBB0_119
	global_load_dword v58, v[40:41], off offset:52
.LBB0_119:
	v_or_b32_e32 v20, 13, v36
	v_ashrrev_i32_e32 v21, 31, v20
	v_lshlrev_b64 v[20:21], 14, v[20:21]
	v_lshl_add_u64 v[20:21], v[38:39], 0, v[20:21]
	global_load_dwordx4 v[20:23], v[20:21], off nt
	v_mov_b32_e32 v56, 1.0
	s_and_b64 vcc, exec, s[4:5]
	v_mov_b32_e32 v62, 1.0
	s_cbranch_vccnz .LBB0_121
	global_load_dword v62, v[40:41], off offset:56
.LBB0_121:
	v_or_b32_e32 v24, 14, v36
	v_ashrrev_i32_e32 v25, 31, v24
	v_lshlrev_b64 v[24:25], 14, v[24:25]
	v_lshl_add_u64 v[24:25], v[38:39], 0, v[24:25]
	global_load_dwordx4 v[24:27], v[24:25], off nt
	s_and_b64 vcc, exec, s[4:5]
	s_cbranch_vccnz .LBB0_22
	global_load_dword v56, v[40:41], off offset:60
	s_branch .LBB0_22

; __device__ __forceinline__ unsigned pk2(float lo, float hi) { f32x2 v = {lo, hi}; bf16x2_t b = __builtin_convertvector(v, bf16x2_t); return __builtin_bit_cast(unsigned, b); }
; __device__ __forceinline__ void p0_cvt_item(const float* W, int K, int N, bf16_t* WT, int row_off, const float* gain, int item, int lane) {
;     const int nblk = N / 256, kb = item / nblk, nb = item % nblk, k0 = 16 * kb, n0 = 256 * nb + 4 * lane;
; #pragma unroll
;     for (int kk = 0; kk < 16; kk += 8) {
;         f32x4 v[8];
; #pragma unroll
;         for (int j = 0; j < 8; ++j) { const float gk = gain ? gain[k0 + kk + j] : 1.f; v[j] = *(const f32x4*)(W + (size_t)(k0 + kk + j) * N + n0) * gk; }
; #pragma unroll
;         for (int c = 0; c < 4; ++c) { u32x4 o; o.x = pk2(v[0][c], v[1][c]); o.y = pk2(v[2][c], v[3][c]); o.z = pk2(v[4][c], v[5][c]); o.w = pk2(v[6][c], v[7][c]);
;             *(u32x4*)(WT + (size_t)(row_off + n0 + c) * K + k0 + kk) = o; }
; __device__ __forceinline__ void p0_phase(const Args& a, LAS unsigned char* lds, int G, int wg, int part, bool split) {
;     ...
;         if (r < 2 * I_AIN) { const int j = r / I_AIN; r -= j * I_AIN;
;             p0_cvt_item(a.in[4] + (size_t)j * DM * 4096, DM, 4096, (bf16_t*)(ws + WS_AWIN) + (size_t)j * 4096 * DM, 0, norm_mix + (3 * j) * DM, r, lane); continue; } r -= 2 * I_AIN;
.LBB0_1419:
	v_or_b32_e32 v32, 15, v32
	v_ashrrev_i32_e32 v33, 31, v32
	v_lshlrev_b64 v[32:33], 14, v[32:33]
	v_lshl_add_u64 v[30:31], v[30:31], 0, v[32:33]
	global_load_dwordx4 v[30:33], v[30:31], off nt
	s_waitcnt vmcnt(2)
	v_pk_mul_f32 v[22:23], v[22:23], v[54:55] op_sel_hi:[1,0]
	v_pk_mul_f32 v[20:21], v[20:21], v[54:55] op_sel_hi:[1,0]
	v_pk_mul_f32 v[18:19], v[18:19], v[56:57] op_sel_hi:[1,0]
	v_pk_mul_f32 v[14:15], v[14:15], v[48:49] op_sel_hi:[1,0]
	v_pk_mul_f32 v[12:13], v[12:13], v[48:49] op_sel_hi:[1,0]
	v_pk_mul_f32 v[10:11], v[10:11], v[50:51] op_sel_hi:[1,0]
	v_pk_mul_f32 v[8:9], v[8:9], v[50:51] op_sel_hi:[1,0]
	v_pk_mul_f32 v[4:5], v[4:5], v[44:45] op_sel_hi:[1,0]
	v_pk_mul_f32 v[54:55], v[2:3], v[46:47] op_sel_hi:[1,0]
	v_pk_mul_f32 v[2:3], v[0:1], v[46:47] op_sel_hi:[1,0]
	s_waitcnt vmcnt(1)
	v_pk_mul_f32 v[24:25], v[24:25], v[58:59] op_sel_hi:[1,0]
	v_pk_mul_f32 v[16:17], v[16:17], v[56:57] op_sel_hi:[1,0]
	v_cvt_pk_bf16_f32 v0, v2, v4
	v_cvt_pk_bf16_f32 v4, v3, v5
	v_cvt_pk_bf16_f32 v5, v9, v13
	v_cvt_pk_bf16_f32 v9, v10, v14
	v_cvt_pk_bf16_f32 v10, v18, v22
	v_cvt_pk_bf16_f32 v14, v19, v23
	v_pk_mul_f32 v[26:27], v[26:27], v[58:59] op_sel_hi:[1,0]
	v_pk_mul_f32 v[34:35], v[6:7], v[44:45] op_sel_hi:[1,0]
	v_cvt_pk_bf16_f32 v1, v8, v12
	v_cvt_pk_bf16_f32 v2, v16, v20
	v_cvt_pk_bf16_f32 v6, v17, v21
	v_cvt_pk_bf16_f32 v8, v54, v34
	v_cvt_pk_bf16_f32 v12, v55, v35
	v_cvt_pk_bf16_f32 v13, v11, v15
	s_waitcnt vmcnt(0)
	v_pk_mul_f32 v[18:19], v[30:31], v[52:53] op_sel_hi:[1,0]
	v_pk_mul_f32 v[16:17], v[32:33], v[52:53] op_sel_hi:[1,0]
	v_cvt_pk_bf16_f32 v3, v24, v18
	v_cvt_pk_bf16_f32 v7, v25, v19
	v_cvt_pk_bf16_f32 v11, v26, v16
	v_cvt_pk_bf16_f32 v15, v27, v17
	global_store_dwordx4 v[36:37], v[0:3], off offset:16
	global_store_dwordx4 v[38:39], v[4:7], off offset:16
	global_store_dwordx4 v[42:43], v[8:11], off offset:16
	global_store_dwordx4 v[40:41], v[12:15], off offset:16

; __device__ __forceinline__ void p0_phase(const Args& a, LAS unsigned char* lds, int G, int wg, int part, bool split) {
;     ...
;     for (int it = it_lo + gw; it < it_hi; it += NGW) {
;         int r = it;
;         if (r < 2 * I_AIN) { const int j = r / I_AIN; r -= j * I_AIN;
;             p0_cvt_item(a.in[4] + (size_t)j * DM * 4096, DM, 4096, (bf16_t*)(ws + WS_AWIN) + (size_t)j * 4096 * DM, 0, norm_mix + (3 * j) * DM, r, lane); continue; } r -= 2 * I_AIN;
;         if (r < I_SQ) { p0_cvt_item(a.in[7], DM, DM, (bf16_t*)(ws + WS_AWOUT), 0, nullptr, r, lane); continue; } r -= I_SQ;
;         if (r < I_QKV) { p0_cvt_item(a.in[8], DM, 3072, (bf16_t*)(ws + WS_BQKV), 0, norm_mix + 1 * DM, r, lane); continue; } r -= I_QKV;
;         if (r < I_SQ) { p0_cvt_item(a.in[9], DM, DM, (bf16_t*)(ws + WS_BOUT), 0, nullptr, r, lane); continue; } r -= I_SQ;
;         if (r < 4 * I_CW) { const int g = r / I_CW; r -= g * I_CW;
;             p0_cvt_item(a.in[11] + (size_t)g * 256 * 256, 256, 256, (bf16_t*)(ws + WS_CW), g * 256, nullptr, r, lane); continue; } r -= 4 * I_CW;
;         if (r < 3 * I_W1) { const int j = r / I_W1; r -= j * I_W1;
;             p0_cvt_item(a.in[13] + (size_t)j * DM * FF, DM, FF, (bf16_t*)(ws + WS_W1) + (size_t)j * FF * DM, 0, norm_mlp + j * DM, r, lane); continue; } r -= 3 * I_W1;
;         if (r < 3 * I_W2) { const int j = r / I_W2; r -= j * I_W2;
;             p0_cvt_item(a.in[14] + (size_t)j * FF * DM, FF, DM, (bf16_t*)(ws + WS_W2) + (size_t)j * DM * FF, 0, nullptr, r, lane); continue; } r -= 3 * I_W2;
;         if (r < I_SQ) { p0_cvt_item(a.in[7] + (size_t)DM * DM, DM, DM, (bf16_t*)(ws + WS_AWOUT) + (size_t)DM * DM, 0, nullptr, r, lane); continue; } r -= I_SQ;
;         if (r < I_W1) { p0_cvt_item(a.in[13] + (size_t)3 * DM * FF, DM, FF, (bf16_t*)(ws + WS_W1) + (size_t)3 * FF * DM, 0, norm_mlp + 3 * DM, r, lane); continue; } r -= I_W1;
;         p0_cvt_item(a.in[14] + (size_t)3 * FF * DM, FF, DM, (bf16_t*)(ws + WS_W2) + (size_t)3 * DM * FF, 0, nullptr, r, lane);
.LBB0_1421:
	v_add_u32_e32 v0, 0xffff2640, v51
	s_movk_i32 s0, 0x7ff
	v_cmp_lt_i32_e32 vcc, s0, v0
	s_and_saveexec_b64 s[0:1], vcc
	s_xor_b64 s[46:47], exec, s[0:1]
	s_cbranch_execz .LBB0_1487
	s_movk_i32 s0, 0x8ff
	v_cmp_lt_u32_e32 vcc, s0, v0
	s_and_saveexec_b64 s[0:1], vcc
	s_xor_b64 s[48:49], exec, s[0:1]
	s_cbranch_execz .LBB0_1484
	s_movk_i32 s0, 0xbff
	v_cmp_lt_u32_e32 vcc, s0, v0
	s_and_saveexec_b64 s[0:1], vcc
	s_xor_b64 s[50:51], exec, s[0:1]
	s_cbranch_execz .LBB0_1481
	s_movk_i32 s0, 0xcff
	v_cmp_lt_u32_e32 vcc, s0, v0
	s_and_saveexec_b64 s[0:1], vcc
	s_xor_b64 s[52:53], exec, s[0:1]
	s_cbranch_execz .LBB0_1478
	s_movk_i32 s0, 0xd3f
	v_cmp_lt_u32_e32 vcc, s0, v0
	s_and_saveexec_b64 s[0:1], vcc
	s_xor_b64 s[54:55], exec, s[0:1]
	s_cbranch_execz .LBB0_1475
	s_movk_i32 s0, 0x193f
	v_cmp_lt_u32_e32 vcc, s0, v0
	s_and_saveexec_b64 s[0:1], vcc
	s_xor_b64 s[38:39], exec, s[0:1]
	s_cbranch_execz .LBB0_1440
	s_movk_i32 s0, 0x253f
	v_cmp_lt_u32_e32 vcc, s0, v0
	s_and_saveexec_b64 s[0:1], vcc
	s_xor_b64 s[40:41], exec, s[0:1]
	s_cbranch_execz .LBB0_1437
	s_movk_i32 s0, 0x263f
	v_cmp_lt_u32_e32 vcc, s0, v0
	s_and_saveexec_b64 s[0:1], vcc
	s_xor_b64 s[0:1], exec, s[0:1]
	s_cbranch_execz .LBB0_1434
	s_movk_i32 s16, 0x2a3f
	v_cmp_lt_u32_e32 vcc, s16, v0
	s_and_saveexec_b64 s[56:57], vcc
	s_xor_b64 s[56:57], exec, s[56:57]
	s_cbranch_execz .LBB0_1431
	v_add_u32_e32 v0, s9, v47
	s_movk_i32 s16, 0x300
	v_add_u32_e32 v0, 0xfffff000, v0
	v_and_or_b32 v30, v49, s16, v45
	v_readlane_b32 s58, v254, 16
	v_and_b32_e32 v32, 0x7ffffff0, v0
	v_lshlrev_b32_e32 v174, 2, v30
	v_readlane_b32 s59, v254, 17
	v_add_u32_e32 v0, 0xffff5700, v32
	v_mov_b32_e32 v1, v175
	v_lshl_add_u64 v[20:21], s[58:59], 0, v[174:175]
	v_add_u32_e32 v174, 0xffff5701, v32
	v_lshlrev_b64 v[4:5], 12, v[174:175]
	v_add_u32_e32 v174, 0xffff5702, v32
	v_lshlrev_b64 v[8:9], 12, v[174:175]
	v_add_u32_e32 v174, 0xffff5703, v32
	v_lshlrev_b64 v[12:13], 12, v[174:175]
	v_add_u32_e32 v174, 0xffff5704, v32
	v_lshlrev_b64 v[16:17], 12, v[174:175]
	v_add_u32_e32 v174, 0xffff5705, v32
	v_lshlrev_b64 v[24:25], 12, v[174:175]
	v_lshl_add_u64 v[16:17], v[20:21], 0, v[16:17]
	v_lshl_add_u64 v[24:25], v[20:21], 0, v[24:25]
	v_add_u32_e32 v174, 0xffff5706, v32
	v_readlane_b32 s58, v253, 56
	global_load_dwordx4 v[16:19], v[16:17], off nt
	v_readlane_b32 s59, v253, 57
	global_load_dwordx4 v[34:37], v[24:25], off nt
	v_lshlrev_b64 v[24:25], 12, v[174:175]
	v_lshl_add_u64 v[24:25], v[20:21], 0, v[24:25]
	v_add_u32_e32 v174, 0xffff5707, v32
	v_lshl_add_u64 v[22:23], v[0:1], 1, s[58:59]
	v_lshlrev_b64 v[0:1], 12, v[0:1]
	global_load_dwordx4 v[38:41], v[24:25], off nt
	v_lshlrev_b64 v[24:25], 12, v[174:175]
	v_lshl_add_u64 v[0:1], v[20:21], 0, v[0:1]
	v_lshl_add_u64 v[4:5], v[20:21], 0, v[4:5]
	v_lshl_add_u64 v[8:9], v[20:21], 0, v[8:9]
	v_lshl_add_u64 v[12:13], v[20:21], 0, v[12:13]
	v_lshl_add_u64 v[24:25], v[20:21], 0, v[24:25]
	global_load_dwordx4 v[0:3], v[0:1], off nt
	v_lshlrev_b32_e32 v174, 13, v30
	global_load_dwordx4 v[4:7], v[4:5], off nt
	v_lshl_add_u64 v[30:31], v[22:23], 0, v[174:175]
	global_load_dwordx4 v[8:11], v[8:9], off nt
	v_mov_b32_e32 v33, v175
	global_load_dwordx4 v[12:15], v[12:13], off nt
	s_waitcnt vmcnt(5)
	v_cvt_pk_bf16_f32 v26, v16, v34
	global_load_dwordx4 v[54:57], v[24:25], off nt
	v_cvt_pk_bf16_f32 v60, v17, v35
	v_add_u32_e32 v16, 0xffff570c, v32
	v_mov_b32_e32 v17, v175
	v_add_u32_e32 v34, 0xffff570d, v32
	v_mov_b32_e32 v35, v175
	v_lshlrev_b64 v[16:17], 12, v[16:17]
	v_lshlrev_b64 v[34:35], 12, v[34:35]
	v_lshl_add_u64 v[16:17], v[20:21], 0, v[16:17]
	v_lshl_add_u64 v[34:35], v[20:21], 0, v[34:35]
	s_waitcnt vmcnt(3)
	v_cvt_pk_bf16_f32 v24, v0, v4
	v_cvt_pk_bf16_f32 v58, v1, v5
	s_waitcnt vmcnt(1)
	v_cvt_pk_bf16_f32 v25, v8, v12
	v_cvt_pk_bf16_f32 v59, v9, v13
	v_add_u32_e32 v8, 0xffff570a, v32
	v_mov_b32_e32 v9, v175
	v_add_u32_e32 v12, 0xffff570b, v32
	v_mov_b32_e32 v13, v175
	v_lshlrev_b64 v[8:9], 12, v[8:9]
	v_lshlrev_b64 v[12:13], 12, v[12:13]
	v_lshl_add_u64 v[8:9], v[20:21], 0, v[8:9]
	v_lshl_add_u64 v[12:13], v[20:21], 0, v[12:13]
	s_waitcnt vmcnt(0)
	v_cvt_pk_bf16_f32 v27, v38, v54
	global_store_dwordx4 v[30:31], v[24:27], off
	v_cvt_pk_bf16_f32 v61, v39, v55
	v_add_u32_e32 v38, 0xffff570e, v32
	v_or_b32_e32 v24, 0x2000, v174
	v_mov_b32_e32 v25, v175
	v_lshl_add_u64 v[0:1], v[22:23], 0, v[24:25]
	v_or_b32_e32 v26, 0x4000, v174
	v_mov_b32_e32 v27, v175
	global_store_dwordx4 v[0:1], v[58:61], off
	v_lshl_add_u64 v[0:1], v[22:23], 0, v[26:27]
	v_or_b32_e32 v174, 0x6000, v174
	v_cvt_pk_bf16_f32 v58, v2, v6
	v_cvt_pk_bf16_f32 v59, v10, v14
	v_cvt_pk_bf16_f32 v60, v18, v36
	v_cvt_pk_bf16_f32 v61, v40, v56
	global_store_dwordx4 v[0:1], v[58:61], off
	v_cvt_pk_bf16_f32 v0, v3, v7
	v_cvt_pk_bf16_f32 v1, v11, v15
	v_cvt_pk_bf16_f32 v2, v19, v37
	v_cvt_pk_bf16_f32 v3, v41, v57
	v_lshl_add_u64 v[4:5], v[22:23], 0, v[174:175]
	global_store_dwordx4 v[4:5], v[0:3], off
	v_add_u32_e32 v4, 0xffff5709, v32
	v_mov_b32_e32 v5, v175
	v_add_u32_e32 v0, 0xffff5708, v32
	v_mov_b32_e32 v1, v175
	v_mov_b32_e32 v39, v175
	v_add_u32_e32 v32, 0xffff570f, v32
	v_lshlrev_b64 v[0:1], 12, v[0:1]
	v_lshlrev_b64 v[4:5], 12, v[4:5]
	v_lshlrev_b64 v[38:39], 12, v[38:39]
	v_lshlrev_b64 v[32:33], 12, v[32:33]
	v_lshl_add_u64 v[0:1], v[20:21], 0, v[0:1]
	v_lshl_add_u64 v[4:5], v[20:21], 0, v[4:5]
	v_lshl_add_u64 v[38:39], v[20:21], 0, v[38:39]
	v_lshl_add_u64 v[20:21], v[20:21], 0, v[32:33]
	global_load_dwordx4 v[0:3], v[0:1], off nt
	v_lshl_add_u64 v[32:33], v[22:23], 0, 16
	global_load_dwordx4 v[4:7], v[4:5], off nt
	s_nop 0
	global_load_dwordx4 v[8:11], v[8:9], off nt
	s_nop 0
	global_load_dwordx4 v[12:15], v[12:13], off nt
	s_nop 0
	global_load_dwordx4 v[16:19], v[16:17], off nt
	s_nop 0
	global_load_dwordx4 v[54:57], v[20:21], off nt
	s_waitcnt vmcnt(4)
	v_cvt_pk_bf16_f32 v20, v0, v4
	global_load_dwordx4 v[34:37], v[34:35], off nt
	s_waitcnt vmcnt(3)
	v_cvt_pk_bf16_f32 v21, v8, v12
	global_load_dwordx4 v[38:41], v[38:39], off nt
	s_waitcnt vmcnt(1)
	v_cvt_pk_bf16_f32 v22, v16, v34
	s_waitcnt vmcnt(0)
	v_cvt_pk_bf16_f32 v23, v38, v54
	global_store_dwordx4 v[30:31], v[20:23], off offset:16
	s_nop 1
	v_cvt_pk_bf16_f32 v20, v1, v5
	v_cvt_pk_bf16_f32 v21, v9, v13
	v_cvt_pk_bf16_f32 v22, v17, v35
	v_cvt_pk_bf16_f32 v23, v39, v55
	v_lshl_add_u64 v[0:1], v[32:33], 0, v[24:25]
	global_store_dwordx4 v[0:1], v[20:23], off
	v_lshl_add_u64 v[0:1], v[32:33], 0, v[26:27]
	v_lshl_add_u64 v[4:5], v[32:33], 0, v[174:175]
	v_cvt_pk_bf16_f32 v20, v2, v6
	v_cvt_pk_bf16_f32 v21, v10, v14
	v_cvt_pk_bf16_f32 v22, v18, v36
	v_cvt_pk_bf16_f32 v23, v40, v56
	global_store_dwordx4 v[0:1], v[20:23], off
	v_cvt_pk_bf16_f32 v0, v3, v7
	v_cvt_pk_bf16_f32 v1, v11, v15
	v_cvt_pk_bf16_f32 v2, v19, v37
	v_cvt_pk_bf16_f32 v3, v41, v57
	global_store_dwordx4 v[4:5], v[0:3], off
; __device__ __forceinline__ unsigned pk2(float lo, float hi) { f32x2 v = {lo, hi}; bf16x2_t b = __builtin_convertvector(v, bf16x2_t); return __builtin_bit_cast(unsigned, b); }
; __device__ __forceinline__ void p0_cvt_item(const float* W, int K, int N, bf16_t* WT, int row_off, const float* gain, int item, int lane) {
;     const int nblk = N / 256, kb = item / nblk, nb = item % nblk, k0 = 16 * kb, n0 = 256 * nb + 4 * lane;
; #pragma unroll
;     for (int kk = 0; kk < 16; kk += 8) {
;         f32x4 v[8];
; #pragma unroll
;         for (int j = 0; j < 8; ++j) { const float gk = gain ? gain[k0 + kk + j] : 1.f; v[j] = *(const f32x4*)(W + (size_t)(k0 + kk + j) * N + n0) * gk; }
; #pragma unroll
;         for (int c = 0; c < 4; ++c) { u32x4 o; o.x = pk2(v[0][c], v[1][c]); o.y = pk2(v[2][c], v[3][c]); o.z = pk2(v[4][c], v[5][c]); o.w = pk2(v[6][c], v[7][c]);
;             *(u32x4*)(WT + (size_t)(row_off + n0 + c) * K + k0 + kk) = o; }
; __device__ __forceinline__ void p0_phase(const Args& a, LAS unsigned char* lds, int G, int wg, int part, bool split) {
;     ...
;         if (r < I_W1) { p0_cvt_item(a.in[13] + (size_t)3 * DM * FF, DM, FF, (bf16_t*)(ws + WS_W1) + (size_t)3 * FF * DM, 0, norm_mlp + 3 * DM, r, lane); continue; } r -= I_W1;
.LBB0_1431:
	s_andn2_saveexec_b64 s[56:57], s[56:57]
	s_cbranch_execz .LBB0_1433
	s_movk_i32 s16, 0xf00
	v_and_or_b32 v46, v49, s16, v45
	v_readlane_b32 s58, v254, 18
	v_lshlrev_b32_e32 v174, 2, v46
	v_readlane_b32 s59, v254, 19
	v_and_b32_e32 v44, 0xfff0, v51
	v_lshlrev_b32_e32 v4, 2, v44
	v_lshl_add_u64 v[2:3], s[58:59], 0, v[174:175]
	v_readlane_b32 s58, v253, 58
	v_lshlrev_b32_e32 v174, 1, v44
	v_readlane_b32 s59, v253, 59
	v_mov_b32_e32 v17, v175
	v_lshlrev_b32_e32 v54, 11, v46
	v_lshl_add_u64 v[0:1], s[58:59], 0, v[174:175]
	v_readlane_b32 s58, v253, 60
	v_lshlrev_b32_e32 v174, 14, v44
	v_readlane_b32 s59, v253, 61
	v_or_b32_e32 v16, 0x4000, v174
	s_nop 3
	global_load_dwordx4 v[8:11], v4, s[58:59] offset:16
	global_load_dwordx4 v[12:15], v4, s[58:59]
	v_lshl_add_u64 v[4:5], v[2:3], 0, v[174:175]
	v_lshl_add_u64 v[16:17], v[2:3], 0, v[16:17]
	global_load_dwordx4 v[4:7], v[4:5], off nt
	v_mov_b32_e32 v55, v175
	global_load_dwordx4 v[16:19], v[16:17], off nt
	s_waitcnt vmcnt(1)
	v_pk_mul_f32 v[6:7], v[6:7], v[12:13] op_sel_hi:[1,0]
	v_pk_mul_f32 v[4:5], v[4:5], v[12:13] op_sel_hi:[1,0]
	s_waitcnt vmcnt(0)
	v_pk_mul_f32 v[20:21], v[18:19], v[12:13] op_sel:[0,1]
	v_pk_mul_f32 v[22:23], v[16:17], v[12:13] op_sel:[0,1]
	v_or_b32_e32 v12, 0x8000, v174
	v_mov_b32_e32 v13, v175
	v_lshl_add_u64 v[12:13], v[2:3], 0, v[12:13]
	global_load_dwordx4 v[16:19], v[12:13], off nt
	v_or_b32_e32 v12, 0xc000, v174
	v_mov_b32_e32 v13, v175
	v_lshl_add_u64 v[12:13], v[2:3], 0, v[12:13]
	s_waitcnt vmcnt(0)
	v_pk_mul_f32 v[24:25], v[18:19], v[14:15] op_sel_hi:[1,0]
	v_pk_mul_f32 v[26:27], v[16:17], v[14:15] op_sel_hi:[1,0]
	global_load_dwordx4 v[16:19], v[12:13], off nt
	v_mov_b32_e32 v12, v15
	s_waitcnt vmcnt(0)
	v_pk_mul_f32 v[18:19], v[18:19], v[12:13] op_sel_hi:[1,0]
	v_pk_mul_f32 v[16:17], v[16:17], v[12:13] op_sel_hi:[1,0]
	v_or_b32_e32 v12, 0x10000, v174
	v_mov_b32_e32 v13, v175
	v_lshl_add_u64 v[12:13], v[2:3], 0, v[12:13]
	global_load_dwordx4 v[12:15], v[12:13], off nt
	s_waitcnt vmcnt(0)
	v_pk_mul_f32 v[32:33], v[12:13], v[8:9] op_sel_hi:[1,0]
	v_or_b32_e32 v12, 0x14000, v174
	v_mov_b32_e32 v13, v175
	v_lshl_add_u64 v[12:13], v[2:3], 0, v[12:13]
	v_pk_mul_f32 v[30:31], v[14:15], v[8:9] op_sel_hi:[1,0]
	global_load_dwordx4 v[12:15], v[12:13], off nt
	s_waitcnt vmcnt(0)
	v_pk_mul_f32 v[34:35], v[14:15], v[8:9] op_sel:[0,1]
	v_pk_mul_f32 v[36:37], v[12:13], v[8:9] op_sel:[0,1]
	v_or_b32_e32 v8, 0x18000, v174
	v_mov_b32_e32 v9, v175
	v_lshl_add_u64 v[8:9], v[2:3], 0, v[8:9]
	global_load_dwordx4 v[12:15], v[8:9], off nt
	v_or_b32_e32 v8, 0x1c000, v174
	v_mov_b32_e32 v9, v175
	v_lshl_add_u64 v[8:9], v[2:3], 0, v[8:9]
	s_waitcnt vmcnt(0)
	v_pk_mul_f32 v[38:39], v[14:15], v[10:11] op_sel_hi:[1,0]
	v_pk_mul_f32 v[40:41], v[12:13], v[10:11] op_sel_hi:[1,0]
	global_load_dwordx4 v[12:15], v[8:9], off nt
	v_mov_b32_e32 v8, v11
	v_cvt_pk_bf16_f32 v10, v4, v22
	v_cvt_pk_bf16_f32 v11, v26, v16
	v_or_b32_e32 v4, 0x1000, v54
	s_waitcnt vmcnt(0)
; __device__ __forceinline__ unsigned pk2(float lo, float hi) { f32x2 v = {lo, hi}; bf16x2_t b = __builtin_convertvector(v, bf16x2_t); return __builtin_bit_cast(unsigned, b); }
; __device__ __forceinline__ void p0_cvt_item(const float* W, int K, int N, bf16_t* WT, int row_off, const float* gain, int item, int lane) {
;     const int nblk = N / 256, kb = item / nblk, nb = item % nblk, k0 = 16 * kb, n0 = 256 * nb + 4 * lane;
; #pragma unroll
;     for (int kk = 0; kk < 16; kk += 8) {
;         f32x4 v[8];
; #pragma unroll
;         for (int j = 0; j < 8; ++j) { const float gk = gain ? gain[k0 + kk + j] : 1.f; v[j] = *(const f32x4*)(W + (size_t)(k0 + kk + j) * N + n0) * gk; }
; #pragma unroll
;         for (int c = 0; c < 4; ++c) { u32x4 o; o.x = pk2(v[0][c], v[1][c]); o.y = pk2(v[2][c], v[3][c]); o.z = pk2(v[4][c], v[5][c]); o.w = pk2(v[6][c], v[7][c]);
;             *(u32x4*)(WT + (size_t)(row_off + n0 + c) * K + k0 + kk) = o; }
; __device__ __forceinline__ void p0_phase(const Args& a, LAS unsigned char* lds, int G, int wg, int part, bool split) {
;     ...
;         if (r < I_W1) { p0_cvt_item(a.in[13] + (size_t)3 * DM * FF, DM, FF, (bf16_t*)(ws + WS_W1) + (size_t)3 * FF * DM, 0, norm_mlp + 3 * DM, r, lane); continue; } r -= I_W1;
	v_pk_mul_f32 v[42:43], v[12:13], v[8:9] op_sel_hi:[1,0]
	v_pk_mul_f32 v[14:15], v[14:15], v[8:9] op_sel_hi:[1,0]
	v_cvt_pk_bf16_f32 v12, v32, v36
	v_cvt_pk_bf16_f32 v13, v40, v42
	v_lshl_add_u64 v[8:9], v[0:1], 0, v[54:55]
	global_store_dwordx4 v[8:9], v[10:13], off
	s_nop 1
	v_cvt_pk_bf16_f32 v10, v5, v23
	v_cvt_pk_bf16_f32 v11, v27, v17
	v_cvt_pk_bf16_f32 v12, v33, v37
	v_cvt_pk_bf16_f32 v13, v41, v43
	v_mov_b32_e32 v5, v175
	global_store_dwordx4 v[8:9], v[10:13], off offset:2048
	v_lshl_add_u64 v[16:17], v[0:1], 0, v[4:5]
	s_nop 0
	v_cvt_pk_bf16_f32 v10, v6, v20
	v_cvt_pk_bf16_f32 v11, v24, v18
	v_cvt_pk_bf16_f32 v12, v30, v34
	v_cvt_pk_bf16_f32 v13, v38, v14
	global_store_dwordx4 v[16:17], v[10:13], off
	v_or_b32_e32 v6, 0x1800, v54
	s_nop 0
	v_cvt_pk_bf16_f32 v10, v7, v21
	v_mov_b32_e32 v7, v175
	v_cvt_pk_bf16_f32 v11, v25, v19
	v_cvt_pk_bf16_f32 v12, v31, v35
	v_cvt_pk_bf16_f32 v13, v39, v15
	v_lshl_add_u64 v[14:15], v[0:1], 0, v[6:7]
	global_store_dwordx4 v[14:15], v[10:13], off
	s_nop 1
	v_or_b32_e32 v10, 8, v44
	v_lshlrev_b32_e32 v11, 2, v10
	global_load_dwordx4 v[12:15], v11, s[58:59] offset:16
	global_load_dwordx4 v[16:19], v11, s[58:59]
	v_lshlrev_b32_e32 v10, 14, v10
	v_mov_b32_e32 v11, v175
	v_lshl_add_u64 v[10:11], v[2:3], 0, v[10:11]
	global_load_dwordx4 v[20:23], v[10:11], off nt
	v_or_b32_e32 v10, 0x24000, v174
	v_mov_b32_e32 v11, v175
	v_lshl_add_u64 v[10:11], v[2:3], 0, v[10:11]
	global_load_dwordx4 v[24:27], v[10:11], off nt
	v_or_b32_e32 v10, 0x28000, v174
	v_mov_b32_e32 v11, v175
	v_lshl_add_u64 v[10:11], v[2:3], 0, v[10:11]
	global_load_dwordx4 v[30:33], v[10:11], off nt
	v_or_b32_e32 v10, 0x2c000, v174
	v_mov_b32_e32 v11, v175
	v_lshl_add_u64 v[10:11], v[2:3], 0, v[10:11]
	global_load_dwordx4 v[34:37], v[10:11], off nt
	v_or_b32_e32 v10, 0x30000, v174
	v_mov_b32_e32 v11, v175
	v_lshl_add_u64 v[10:11], v[2:3], 0, v[10:11]
	global_load_dwordx4 v[38:41], v[10:11], off nt
	v_or_b32_e32 v10, 0x34000, v174
	v_mov_b32_e32 v11, v175
	v_lshl_add_u64 v[10:11], v[2:3], 0, v[10:11]
	global_load_dwordx4 v[54:57], v[10:11], off nt
	v_or_b32_e32 v10, 0x38000, v174
	v_mov_b32_e32 v11, v175
	v_lshl_add_u64 v[10:11], v[2:3], 0, v[10:11]
	global_load_dwordx4 v[58:61], v[10:11], off nt
	v_or_b32_e32 v174, 0x3c000, v174
	v_lshl_add_u64 v[2:3], v[2:3], 0, v[174:175]
	s_waitcnt vmcnt(6)
	v_pk_mul_f32 v[22:23], v[22:23], v[16:17] op_sel_hi:[1,0]
	v_pk_mul_f32 v[20:21], v[20:21], v[16:17] op_sel_hi:[1,0]
	s_waitcnt vmcnt(5)
	v_pk_mul_f32 v[26:27], v[26:27], v[16:17] op_sel:[0,1]
	v_pk_mul_f32 v[24:25], v[24:25], v[16:17] op_sel:[0,1]
	s_waitcnt vmcnt(4)
	v_pk_mul_f32 v[32:33], v[32:33], v[18:19] op_sel_hi:[1,0]
	v_pk_mul_f32 v[30:31], v[30:31], v[18:19] op_sel_hi:[1,0]
	s_waitcnt vmcnt(2)
	v_pk_mul_f32 v[40:41], v[40:41], v[12:13] op_sel_hi:[1,0]
	s_waitcnt vmcnt(1)
	v_pk_mul_f32 v[56:57], v[56:57], v[12:13] op_sel:[0,1]
	v_pk_mul_f32 v[54:55], v[54:55], v[12:13] op_sel:[0,1]
	v_pk_mul_f32 v[12:13], v[38:39], v[12:13] op_sel_hi:[1,0]
	s_waitcnt vmcnt(0)
	v_pk_mul_f32 v[10:11], v[60:61], v[14:15] op_sel_hi:[1,0]
	v_pk_mul_f32 v[42:43], v[58:59], v[14:15] op_sel_hi:[1,0]
	v_mov_b32_e32 v14, v19
	global_load_dwordx4 v[16:19], v[2:3], off nt
	v_mov_b32_e32 v2, v15
	v_pk_mul_f32 v[34:35], v[34:35], v[14:15] op_sel_hi:[1,0]
	v_pk_mul_f32 v[36:37], v[36:37], v[14:15] op_sel_hi:[1,0]
	s_waitcnt vmcnt(0)
	v_pk_mul_f32 v[16:17], v[16:17], v[2:3] op_sel_hi:[1,0]
	v_pk_mul_f32 v[14:15], v[18:19], v[2:3] op_sel_hi:[1,0]
	v_lshl_add_u64 v[18:19], v[0:1], 0, 16
	v_cvt_pk_bf16_f32 v0, v20, v24
	v_cvt_pk_bf16_f32 v1, v30, v34
	v_cvt_pk_bf16_f32 v2, v12, v54
	v_cvt_pk_bf16_f32 v3, v42, v16
	global_store_dwordx4 v[8:9], v[0:3], off offset:16
	v_lshl_add_u64 v[4:5], v[18:19], 0, v[4:5]
	s_nop 0
	v_cvt_pk_bf16_f32 v0, v21, v25
	v_cvt_pk_bf16_f32 v1, v31, v35
	v_cvt_pk_bf16_f32 v2, v13, v55
	v_cvt_pk_bf16_f32 v3, v43, v17
	global_store_dwordx4 v[8:9], v[0:3], off offset:2064
	s_nop 1
	v_cvt_pk_bf16_f32 v0, v22, v26
	v_cvt_pk_bf16_f32 v1, v32, v36
	v_cvt_pk_bf16_f32 v2, v40, v56
	v_cvt_pk_bf16_f32 v3, v10, v14
	global_store_dwordx4 v[4:5], v[0:3], off
	v_lshl_add_u64 v[4:5], v[18:19], 0, v[6:7]
	s_nop 0
	v_cvt_pk_bf16_f32 v0, v23, v27
	v_cvt_pk_bf16_f32 v1, v33, v37
	v_cvt_pk_bf16_f32 v2, v41, v57
	v_cvt_pk_bf16_f32 v3, v11, v15
	global_store_dwordx4 v[4:5], v[0:3], off

; __device__ __forceinline__ unsigned pk2(float lo, float hi) { f32x2 v = {lo, hi}; bf16x2_t b = __builtin_convertvector(v, bf16x2_t); return __builtin_bit_cast(unsigned, b); }
; __device__ __forceinline__ void p0_cvt_item(const float* W, int K, int N, bf16_t* WT, int row_off, const float* gain, int item, int lane) {
;     const int nblk = N / 256, kb = item / nblk, nb = item % nblk, k0 = 16 * kb, n0 = 256 * nb + 4 * lane;
; #pragma unroll
;     for (int kk = 0; kk < 16; kk += 8) {
;         f32x4 v[8];
; #pragma unroll
;         for (int j = 0; j < 8; ++j) { const float gk = gain ? gain[k0 + kk + j] : 1.f; v[j] = *(const f32x4*)(W + (size_t)(k0 + kk + j) * N + n0) * gk; }
; #pragma unroll
;         for (int c = 0; c < 4; ++c) { u32x4 o; o.x = pk2(v[0][c], v[1][c]); o.y = pk2(v[2][c], v[3][c]); o.z = pk2(v[4][c], v[5][c]); o.w = pk2(v[6][c], v[7][c]);
;             *(u32x4*)(WT + (size_t)(row_off + n0 + c) * K + k0 + kk) = o; }
; __device__ __forceinline__ void p0_phase(const Args& a, LAS unsigned char* lds, int G, int wg, int part, bool split) {
;     ...
;         if (r < I_SQ) { p0_cvt_item(a.in[7] + (size_t)DM * DM, DM, DM, (bf16_t*)(ws + WS_AWOUT) + (size_t)DM * DM, 0, nullptr, r, lane); continue; } r -= I_SQ;
.LBB0_1434:
	s_andn2_saveexec_b64 s[0:1], s[0:1]
	s_cbranch_execz .LBB0_1436
	s_movk_i32 s16, 0x300
	v_add_u32_e32 v0, s9, v47
	v_and_or_b32 v6, v49, s16, v45
	v_readlane_b32 s56, v254, 20
	v_add_u32_e32 v0, 0xfffff300, v0
	v_lshlrev_b32_e32 v174, 2, v6
	v_readlane_b32 s57, v254, 21
	v_and_b32_e32 v4, 0x3f0, v0
	s_mov_b32 s16, 0x9000
	v_lshl_add_u64 v[2:3], s[56:57], 0, v[174:175]
	v_readlane_b32 s56, v253, 62
	v_lshlrev_b32_e32 v174, 1, v4
	v_readlane_b32 s57, v253, 63
	s_nop 1
	v_lshl_add_u64 v[0:1], s[56:57], 0, v[174:175]
	v_lshlrev_b32_e32 v174, 12, v4
	v_lshl_add_u64 v[2:3], v[2:3], 0, v[174:175]
	v_add_co_u32_e32 v4, vcc, 0x1000, v2
	global_load_dwordx4 v[8:11], v[2:3], off nt
	s_nop 0
	v_addc_co_u32_e32 v5, vcc, 0, v3, vcc
	global_load_dwordx4 v[12:15], v[4:5], off nt
	v_add_co_u32_e32 v4, vcc, s23, v2
	v_lshlrev_b32_e32 v174, 11, v6
	s_nop 0
	v_addc_co_u32_e32 v5, vcc, 0, v3, vcc
	global_load_dwordx4 v[16:19], v[4:5], off nt
	v_add_co_u32_e32 v4, vcc, 0x3000, v2
	v_lshl_add_u64 v[6:7], v[0:1], 0, v[174:175]
	s_nop 0
	v_addc_co_u32_e32 v5, vcc, 0, v3, vcc
	global_load_dwordx4 v[20:23], v[4:5], off nt
	v_add_co_u32_e32 v4, vcc, s31, v2
	v_lshl_add_u64 v[42:43], v[0:1], 0, 16
	s_nop 0
	v_addc_co_u32_e32 v5, vcc, 0, v3, vcc
	global_load_dwordx4 v[24:27], v[4:5], off nt
	v_add_co_u32_e32 v4, vcc, 0x5000, v2
	s_waitcnt vmcnt(3)
	v_cvt_pk_bf16_f32 v54, v8, v12
	v_addc_co_u32_e32 v5, vcc, 0, v3, vcc
	global_load_dwordx4 v[30:33], v[4:5], off nt
	v_add_co_u32_e32 v4, vcc, s33, v2
	s_waitcnt vmcnt(2)
	v_cvt_pk_bf16_f32 v55, v16, v20
	v_addc_co_u32_e32 v5, vcc, 0, v3, vcc
	global_load_dwordx4 v[34:37], v[4:5], off nt
	v_add_co_u32_e32 v4, vcc, 0x7000, v2
	s_waitcnt vmcnt(1)
	v_cvt_pk_bf16_f32 v56, v24, v30
	v_addc_co_u32_e32 v5, vcc, 0, v3, vcc
	global_load_dwordx4 v[38:41], v[4:5], off nt
	v_or_b32_e32 v4, 0x1000, v174
	v_mov_b32_e32 v5, v175
	v_or_b32_e32 v174, 0x1800, v174
	s_waitcnt vmcnt(0)
	v_cvt_pk_bf16_f32 v57, v34, v38
	global_store_dwordx4 v[6:7], v[54:57], off
	s_nop 1
	v_cvt_pk_bf16_f32 v54, v9, v13
	v_cvt_pk_bf16_f32 v55, v17, v21
	v_cvt_pk_bf16_f32 v56, v25, v31
	v_cvt_pk_bf16_f32 v57, v35, v39
	global_store_dwordx4 v[6:7], v[54:57], off offset:2048
	v_lshl_add_u64 v[8:9], v[0:1], 0, v[4:5]
	v_lshl_add_u64 v[12:13], v[0:1], 0, v[174:175]
	v_cvt_pk_bf16_f32 v54, v10, v14
	v_cvt_pk_bf16_f32 v55, v18, v22
	v_cvt_pk_bf16_f32 v56, v26, v32
	v_cvt_pk_bf16_f32 v57, v36, v40
	global_store_dwordx4 v[8:9], v[54:57], off
	v_cvt_pk_bf16_f32 v8, v11, v15
	v_cvt_pk_bf16_f32 v9, v19, v23
	v_cvt_pk_bf16_f32 v10, v27, v33
	v_cvt_pk_bf16_f32 v11, v37, v41
	global_store_dwordx4 v[12:13], v[8:11], off
	v_add_co_u32_e32 v12, vcc, s16, v2
	s_mov_b32 s16, 0xb000
	s_nop 0
	v_addc_co_u32_e32 v13, vcc, 0, v3, vcc
	v_add_co_u32_e32 v20, vcc, s16, v2
	s_mov_b32 s16, 0xd000
	s_nop 0
	v_addc_co_u32_e32 v21, vcc, 0, v3, vcc
	v_add_co_u32_e32 v30, vcc, s16, v2
	s_mov_b32 s16, 0xf000
	s_nop 0
	v_addc_co_u32_e32 v31, vcc, 0, v3, vcc
	v_add_co_u32_e32 v2, vcc, s16, v2
	global_load_dwordx4 v[8:11], v[12:13], off offset:-4096 nt
	s_nop 0
	global_load_dwordx4 v[12:15], v[12:13], off nt
	v_addc_co_u32_e32 v3, vcc, 0, v3, vcc
	global_load_dwordx4 v[16:19], v[20:21], off offset:-4096 nt
	s_nop 0
	global_load_dwordx4 v[20:23], v[20:21], off nt
	s_nop 0
	global_load_dwordx4 v[24:27], v[30:31], off offset:-4096 nt
	s_nop 0
	global_load_dwordx4 v[30:33], v[30:31], off nt
	s_nop 0
	global_load_dwordx4 v[34:37], v[2:3], off offset:-4096 nt
	global_load_dwordx4 v[38:41], v[2:3], off nt
	v_lshl_add_u64 v[4:5], v[42:43], 0, v[4:5]
	s_waitcnt vmcnt(6)
	v_cvt_pk_bf16_f32 v0, v8, v12
	s_waitcnt vmcnt(4)
	v_cvt_pk_bf16_f32 v1, v16, v20
	s_waitcnt vmcnt(2)
	v_cvt_pk_bf16_f32 v2, v24, v30
	s_waitcnt vmcnt(0)
	v_cvt_pk_bf16_f32 v3, v34, v38
	global_store_dwordx4 v[6:7], v[0:3], off offset:16
	s_nop 1
	v_cvt_pk_bf16_f32 v0, v9, v13
	v_cvt_pk_bf16_f32 v1, v17, v21
	v_cvt_pk_bf16_f32 v2, v25, v31
	v_cvt_pk_bf16_f32 v3, v35, v39
	global_store_dwordx4 v[6:7], v[0:3], off offset:2064
	s_nop 1
	v_cvt_pk_bf16_f32 v0, v10, v14
	v_cvt_pk_bf16_f32 v1, v18, v22
	v_cvt_pk_bf16_f32 v2, v26, v32
	v_cvt_pk_bf16_f32 v3, v36, v40
	global_store_dwordx4 v[4:5], v[0:3], off
	v_lshl_add_u64 v[4:5], v[42:43], 0, v[174:175]
	s_nop 0
	v_cvt_pk_bf16_f32 v0, v11, v15
	v_cvt_pk_bf16_f32 v1, v19, v23
	v_cvt_pk_bf16_f32 v2, v27, v33
	v_cvt_pk_bf16_f32 v3, v37, v41
	global_store_dwordx4 v[4:5], v[0:3], off

; __device__ __forceinline__ unsigned pk2(float lo, float hi) { f32x2 v = {lo, hi}; bf16x2_t b = __builtin_convertvector(v, bf16x2_t); return __builtin_bit_cast(unsigned, b); }
; __device__ __forceinline__ void p0_cvt_item(const float* W, int K, int N, bf16_t* WT, int row_off, const float* gain, int item, int lane) {
;     const int nblk = N / 256, kb = item / nblk, nb = item % nblk, k0 = 16 * kb, n0 = 256 * nb + 4 * lane;
; #pragma unroll
;     for (int kk = 0; kk < 16; kk += 8) {
;         f32x4 v[8];
; #pragma unroll
;         for (int j = 0; j < 8; ++j) { const float gk = gain ? gain[k0 + kk + j] : 1.f; v[j] = *(const f32x4*)(W + (size_t)(k0 + kk + j) * N + n0) * gk; }
; #pragma unroll
;         for (int c = 0; c < 4; ++c) { u32x4 o; o.x = pk2(v[0][c], v[1][c]); o.y = pk2(v[2][c], v[3][c]); o.z = pk2(v[4][c], v[5][c]); o.w = pk2(v[6][c], v[7][c]);
;             *(u32x4*)(WT + (size_t)(row_off + n0 + c) * K + k0 + kk) = o; }
; __device__ __forceinline__ void p0_phase(const Args& a, LAS unsigned char* lds, int G, int wg, int part, bool split) {
;     ...
;         if (r < 3 * I_W2) { const int j = r / I_W2; r -= j * I_W2;
;             p0_cvt_item(a.in[14] + (size_t)j * FF * DM, FF, DM, (bf16_t*)(ws + WS_W2) + (size_t)j * DM * FF, 0, nullptr, r, lane); continue; } r -= 3 * I_W2;
.LBB0_1437:
	s_andn2_saveexec_b64 s[0:1], s[40:41]
	s_cbranch_execz .LBB0_1439
	v_add_u32_e32 v0, 0xffff0d00, v51
	v_lshrrev_b32_e32 v174, 10, v0
	v_readlane_b32 s56, v252, 16
	v_add_u32_e32 v4, s9, v47
	s_movk_i32 s16, 0x300
	v_lshlrev_b64 v[0:1], 24, v[174:175]
	v_readlane_b32 s68, v252, 28
	v_readlane_b32 s69, v252, 29
	v_readlane_b32 s40, v254, 0
	v_add_u32_e32 v4, 0xffff8b00, v4
	v_and_or_b32 v18, v49, s16, v45
	v_lshl_add_u64 v[0:1], s[68:69], 0, v[0:1]
	v_lshlrev_b64 v[2:3], 23, v[174:175]
	v_readlane_b32 s41, v254, 1
	v_and_b32_e32 v4, 0xff0, v4
	v_lshlrev_b32_e32 v174, 2, v18
	v_lshl_add_u64 v[2:3], s[40:41], 0, v[2:3]
	v_lshl_add_u64 v[0:1], v[0:1], 0, v[174:175]
	v_lshlrev_b32_e32 v174, 1, v4
	v_lshl_add_u64 v[12:13], v[2:3], 0, v[174:175]
	v_lshlrev_b32_e32 v174, 12, v4
	v_lshl_add_u64 v[20:21], v[0:1], 0, v[174:175]
	v_add_co_u32_e32 v8, vcc, s23, v20
	global_load_dwordx4 v[0:3], v[20:21], off nt
	s_nop 0
	v_addc_co_u32_e32 v9, vcc, 0, v21, vcc
	v_add_co_u32_e32 v14, vcc, s31, v20
	global_load_dwordx4 v[4:7], v[8:9], off offset:-4096 nt
	s_nop 0
	global_load_dwordx4 v[8:11], v[8:9], off nt
	v_addc_co_u32_e32 v15, vcc, 0, v21, vcc
	global_load_dwordx4 v[22:25], v[14:15], off offset:-4096 nt
	global_load_dwordx4 v[30:33], v[14:15], off nt
	v_add_co_u32_e32 v14, vcc, s33, v20
	v_lshlrev_b32_e32 v174, 13, v18
	s_nop 0
	v_addc_co_u32_e32 v15, vcc, 0, v21, vcc
	v_add_co_u32_e32 v26, vcc, s19, v20
	global_load_dwordx4 v[34:37], v[14:15], off offset:-4096 nt
	global_load_dwordx4 v[38:41], v[14:15], off nt
	v_addc_co_u32_e32 v27, vcc, 0, v21, vcc
	global_load_dwordx4 v[54:57], v[26:27], off offset:-4096 nt
	v_lshl_add_u64 v[18:19], v[12:13], 0, v[174:175]
	s_mov_b32 s16, 0xe000
	v_readlane_b32 s70, v252, 30
	v_readlane_b32 s71, v252, 31
	v_readlane_b32 s68, v252, 0
	v_readlane_b32 s64, v252, 24
	v_readlane_b32 s65, v252, 25
	v_readlane_b32 s69, v252, 1
	v_readlane_b32 s78, v252, 10
	v_readlane_b32 s79, v252, 11
	v_readlane_b32 s80, v252, 12
	v_readlane_b32 s81, v252, 13
	v_readlane_b32 s63, v252, 23
	v_readlane_b32 s67, v252, 27
	v_readlane_b32 s64, v255, 6
	v_readlane_b32 s78, v255, 2
	v_readlane_b32 s68, v255, 0
	v_readlane_b32 s80, v255, 4
	s_mov_b32 s63, 0x10000
	v_readlane_b32 s67, v255, 8
	v_readlane_b32 s65, v255, 7
	v_readlane_b32 s70, v252, 2
	v_readlane_b32 s71, v252, 3
	v_readlane_b32 s72, v252, 4
	v_readlane_b32 s73, v252, 5
	v_readlane_b32 s74, v252, 6
	v_readlane_b32 s75, v252, 7
	v_readlane_b32 s76, v252, 8
	v_readlane_b32 s77, v252, 9
	v_readlane_b32 s82, v252, 14
	v_readlane_b32 s83, v252, 15
	v_readlane_b32 s79, v255, 3
	v_readlane_b32 s69, v255, 1
	v_readlane_b32 s81, v255, 5
	v_readlane_b32 s57, v252, 17
	v_readlane_b32 s58, v252, 18
	v_readlane_b32 s59, v252, 19
	v_readlane_b32 s60, v252, 20
	v_readlane_b32 s61, v252, 21
	v_readlane_b32 s62, v252, 22
	v_readlane_b32 s66, v252, 26
	s_waitcnt vmcnt(6)
	v_cvt_pk_bf16_f32 v14, v0, v4
	v_cvt_pk_bf16_f32 v58, v1, v5
	s_waitcnt vmcnt(4)
	v_cvt_pk_bf16_f32 v15, v8, v22
	v_cvt_pk_bf16_f32 v59, v9, v23
	v_add_co_u32_e32 v8, vcc, s92, v20
	s_waitcnt vmcnt(2)
	v_cvt_pk_bf16_f32 v16, v30, v34
	v_cvt_pk_bf16_f32 v60, v31, v35
	v_addc_co_u32_e32 v9, vcc, 0, v21, vcc
	s_waitcnt vmcnt(0)
	v_cvt_pk_bf16_f32 v17, v38, v54
	global_store_dwordx4 v[18:19], v[14:17], off
	v_cvt_pk_bf16_f32 v61, v39, v55
	s_nop 0
	v_or_b32_e32 v14, 0x2000, v174
	v_mov_b32_e32 v15, v175
	v_lshl_add_u64 v[0:1], v[12:13], 0, v[14:15]
	v_or_b32_e32 v16, 0x4000, v174
	v_mov_b32_e32 v17, v175
	global_store_dwordx4 v[0:1], v[58:61], off
	v_lshl_add_u64 v[0:1], v[12:13], 0, v[16:17]
	v_or_b32_e32 v174, 0x6000, v174
	v_cvt_pk_bf16_f32 v58, v2, v6
	v_cvt_pk_bf16_f32 v59, v10, v24
	v_cvt_pk_bf16_f32 v60, v32, v36
	v_cvt_pk_bf16_f32 v61, v40, v56
	global_store_dwordx4 v[0:1], v[58:61], off
	v_cvt_pk_bf16_f32 v0, v3, v7
	v_cvt_pk_bf16_f32 v1, v11, v25
	v_cvt_pk_bf16_f32 v2, v33, v37
	v_cvt_pk_bf16_f32 v3, v41, v57
	v_lshl_add_u64 v[4:5], v[12:13], 0, v[174:175]
	global_store_dwordx4 v[4:5], v[0:3], off
	global_load_dwordx4 v[0:3], v[26:27], off nt
	v_add_co_u32_e32 v26, vcc, s12, v20
	global_load_dwordx4 v[4:7], v[8:9], off offset:-4096 nt
	s_nop 0
	global_load_dwordx4 v[8:11], v[8:9], off nt
	v_addc_co_u32_e32 v27, vcc, 0, v21, vcc
	global_load_dwordx4 v[22:25], v[26:27], off offset:-4096 nt
	global_load_dwordx4 v[30:33], v[26:27], off nt
	v_add_co_u32_e32 v26, vcc, s16, v20
	s_mov_b32 s16, 0xf000
	s_nop 0
	v_addc_co_u32_e32 v27, vcc, 0, v21, vcc
	v_add_co_u32_e32 v20, vcc, s16, v20
	global_load_dwordx4 v[34:37], v[26:27], off offset:-4096 nt
	global_load_dwordx4 v[38:41], v[26:27], off nt
	v_addc_co_u32_e32 v21, vcc, 0, v21, vcc
	global_load_dwordx4 v[54:57], v[20:21], off nt
	v_lshl_add_u64 v[26:27], v[12:13], 0, 16
	s_waitcnt vmcnt(6)
	v_cvt_pk_bf16_f32 v58, v0, v4
	v_cvt_pk_bf16_f32 v12, v2, v6
	s_waitcnt vmcnt(4)
	v_cvt_pk_bf16_f32 v59, v8, v22
	v_cvt_pk_bf16_f32 v13, v10, v24
	s_waitcnt vmcnt(2)
	v_cvt_pk_bf16_f32 v60, v30, v34
	v_cvt_pk_bf16_f32 v20, v31, v35
	v_cvt_pk_bf16_f32 v2, v33, v37
	s_waitcnt vmcnt(0)
	v_cvt_pk_bf16_f32 v61, v38, v54
	global_store_dwordx4 v[18:19], v[58:61], off offset:16
	v_cvt_pk_bf16_f32 v18, v1, v5
	v_cvt_pk_bf16_f32 v19, v9, v23
	v_cvt_pk_bf16_f32 v21, v39, v55
	v_lshl_add_u64 v[0:1], v[26:27], 0, v[14:15]
	global_store_dwordx4 v[0:1], v[18:21], off
	v_cvt_pk_bf16_f32 v14, v32, v36
	v_cvt_pk_bf16_f32 v15, v40, v56
	v_lshl_add_u64 v[0:1], v[26:27], 0, v[16:17]
	global_store_dwordx4 v[0:1], v[12:15], off
	v_cvt_pk_bf16_f32 v0, v3, v7
	v_cvt_pk_bf16_f32 v1, v11, v25
	v_cvt_pk_bf16_f32 v3, v41, v57
	v_lshl_add_u64 v[4:5], v[26:27], 0, v[174:175]
	global_store_dwordx4 v[4:5], v[0:3], off

; __device__ __forceinline__ unsigned pk2(float lo, float hi) { f32x2 v = {lo, hi}; bf16x2_t b = __builtin_convertvector(v, bf16x2_t); return __builtin_bit_cast(unsigned, b); }
; __device__ __forceinline__ void p0_cvt_item(const float* W, int K, int N, bf16_t* WT, int row_off, const float* gain, int item, int lane) {
;     const int nblk = N / 256, kb = item / nblk, nb = item % nblk, k0 = 16 * kb, n0 = 256 * nb + 4 * lane;
; #pragma unroll
;     for (int kk = 0; kk < 16; kk += 8) {
;         f32x4 v[8];
; #pragma unroll
;         for (int j = 0; j < 8; ++j) { const float gk = gain ? gain[k0 + kk + j] : 1.f; v[j] = *(const f32x4*)(W + (size_t)(k0 + kk + j) * N + n0) * gk; }
; #pragma unroll
;         for (int c = 0; c < 4; ++c) { u32x4 o; o.x = pk2(v[0][c], v[1][c]); o.y = pk2(v[2][c], v[3][c]); o.z = pk2(v[4][c], v[5][c]); o.w = pk2(v[6][c], v[7][c]);
;             *(u32x4*)(WT + (size_t)(row_off + n0 + c) * K + k0 + kk) = o; }
; __device__ __forceinline__ void p0_phase(const Args& a, LAS unsigned char* lds, int G, int wg, int part, bool split) {
;     ...
;         if (r < 3 * I_W1) { const int j = r / I_W1; r -= j * I_W1;
;             p0_cvt_item(a.in[13] + (size_t)j * DM * FF, DM, FF, (bf16_t*)(ws + WS_W1) + (size_t)j * FF * DM, 0, norm_mlp + j * DM, r, lane); continue; } r -= 3 * I_W1;
.LBB0_1443:
	v_lshrrev_b32_e32 v174, 10, v0
	v_readlane_b32 s56, v252, 16
	s_movk_i32 s16, 0xf00
	v_lshlrev_b64 v[0:1], 24, v[174:175]
	v_readlane_b32 s66, v252, 26
	v_readlane_b32 s67, v252, 27
	v_and_or_b32 v37, v49, s16, v45
	v_lshlrev_b32_e32 v2, 2, v37
	v_lshl_add_u64 v[0:1], s[66:67], 0, v[0:1]
	v_mov_b32_e32 v3, v175
	v_lshl_add_u64 v[30:31], v[0:1], 0, v[2:3]
	v_lshlrev_b32_e32 v0, 14, v43
	v_mov_b32_e32 v1, v175
	v_lshl_add_u64 v[0:1], v[30:31], 0, v[0:1]
	global_load_dwordx4 v[0:3], v[0:1], off nt
	s_and_b64 vcc, exec, s[40:41]
	v_readlane_b32 s57, v252, 17
	v_readlane_b32 s58, v252, 18
	v_readlane_b32 s59, v252, 19
	v_readlane_b32 s60, v252, 20
	v_readlane_b32 s61, v252, 21
	v_readlane_b32 s62, v252, 22
	v_readlane_b32 s63, v252, 23
	v_readlane_b32 s64, v252, 24
	v_readlane_b32 s65, v252, 25
	v_readlane_b32 s68, v252, 28
	v_readlane_b32 s69, v252, 29
	v_readlane_b32 s70, v252, 30
	v_readlane_b32 s71, v252, 31
	s_cbranch_vccnz .LBB0_1445
	v_mov_b32_e32 v35, v175
	v_lshl_add_u64 v[4:5], v[32:33], 0, v[34:35]
	global_load_dword v36, v[4:5], off offset:4
.LBB0_1445:
	v_mov_b32_e32 v4, 0x4000
	v_lshl_or_b32 v4, v43, 14, v4
	v_mov_b32_e32 v5, v175
	v_lshl_add_u64 v[4:5], v[30:31], 0, v[4:5]
	global_load_dwordx4 v[4:7], v[4:5], off nt
	v_mov_b32_e32 v40, 1.0
	s_and_b64 vcc, exec, s[40:41]
	v_mov_b32_e32 v42, 1.0
	s_cbranch_vccnz .LBB0_1447
	v_mov_b32_e32 v35, v175
	v_lshl_add_u64 v[8:9], v[32:33], 0, v[34:35]
	global_load_dword v42, v[8:9], off offset:8
.LBB0_1447:
	v_mov_b32_e32 v8, 0x8000
	v_lshl_or_b32 v8, v43, 14, v8
	v_mov_b32_e32 v9, v175
	v_lshl_add_u64 v[8:9], v[30:31], 0, v[8:9]
	global_load_dwordx4 v[8:11], v[8:9], off nt
	v_readlane_b32 s68, v252, 0
	v_readlane_b32 s64, v255, 6
	s_and_b64 vcc, exec, s[40:41]
	v_readlane_b32 s70, v252, 2
	v_readlane_b32 s71, v252, 3
	v_readlane_b32 s72, v252, 4
	v_readlane_b32 s73, v252, 5
	v_readlane_b32 s74, v252, 6
	v_readlane_b32 s75, v252, 7
	v_readlane_b32 s76, v252, 8
	v_readlane_b32 s77, v252, 9
	v_readlane_b32 s82, v252, 14
	v_readlane_b32 s83, v252, 15
	v_readlane_b32 s65, v255, 7
	v_readlane_b32 s67, v255, 8
	s_mov_b32 s63, 0x10000
	v_readlane_b32 s69, v252, 1
	v_readlane_b32 s78, v252, 10
	v_readlane_b32 s79, v252, 11
	v_readlane_b32 s80, v252, 12
	v_readlane_b32 s81, v252, 13
	s_cbranch_vccnz .LBB0_1449
	v_mov_b32_e32 v35, v175
	v_lshl_add_u64 v[12:13], v[32:33], 0, v[34:35]
	global_load_dword v40, v[12:13], off offset:12
.LBB0_1449:
	v_mov_b32_e32 v12, 0xc000
	v_lshl_or_b32 v12, v43, 14, v12
	v_mov_b32_e32 v13, v175
	v_lshl_add_u64 v[12:13], v[30:31], 0, v[12:13]
	global_load_dwordx4 v[12:15], v[12:13], off nt
	v_readlane_b32 s68, v255, 0
	v_mov_b32_e32 v46, 1.0
	s_and_b64 vcc, exec, s[40:41]
	v_mov_b32_e32 v48, 1.0
	v_readlane_b32 s69, v255, 1
	s_cbranch_vccnz .LBB0_1451
	v_mov_b32_e32 v35, v175
	v_lshl_add_u64 v[16:17], v[32:33], 0, v[34:35]
	global_load_dword v48, v[16:17], off offset:16
.LBB0_1451:
	v_mov_b32_e32 v16, 0x10000
	v_lshl_or_b32 v16, v43, 14, v16
	v_mov_b32_e32 v17, v175
	v_lshl_add_u64 v[16:17], v[30:31], 0, v[16:17]
	global_load_dwordx4 v[16:19], v[16:17], off nt
	v_readlane_b32 s78, v255, 2
	v_readlane_b32 s80, v255, 4
	s_and_b64 vcc, exec, s[40:41]
	v_readlane_b32 s79, v255, 3
	v_readlane_b32 s81, v255, 5
	s_cbranch_vccnz .LBB0_1453
	v_mov_b32_e32 v35, v175
	v_lshl_add_u64 v[20:21], v[32:33], 0, v[34:35]
	global_load_dword v46, v[20:21], off offset:20
.LBB0_1453:
	v_mov_b32_e32 v20, 0x14000
	v_lshl_or_b32 v20, v43, 14, v20
	v_mov_b32_e32 v21, v175
	v_lshl_add_u64 v[20:21], v[30:31], 0, v[20:21]
	global_load_dwordx4 v[20:23], v[20:21], off nt
	v_mov_b32_e32 v44, 1.0
	s_and_b64 vcc, exec, s[40:41]
	v_mov_b32_e32 v50, 1.0
	s_cbranch_vccnz .LBB0_1455
	v_mov_b32_e32 v35, v175
	v_lshl_add_u64 v[24:25], v[32:33], 0, v[34:35]
	global_load_dword v50, v[24:25], off offset:24
.LBB0_1455:
	v_mov_b32_e32 v24, 0x18000
	v_lshl_or_b32 v24, v43, 14, v24
	v_mov_b32_e32 v25, v175
	v_lshl_add_u64 v[24:25], v[30:31], 0, v[24:25]
	global_load_dwordx4 v[24:27], v[24:25], off nt
	s_and_b64 vcc, exec, s[40:41]
	s_cbranch_vccnz .LBB0_1457
	v_mov_b32_e32 v35, v175
	v_lshl_add_u64 v[54:55], v[32:33], 0, v[34:35]
	global_load_dword v44, v[54:55], off offset:28
.LBB0_1457:
	v_readlane_b32 s38, v254, 2
	s_waitcnt vmcnt(6)
	v_pk_mul_f32 v[56:57], v[0:1], v[38:39] op_sel_hi:[1,0]
	v_lshlrev_b64 v[0:1], 23, v[174:175]
	v_readlane_b32 s39, v254, 3
	v_lshlrev_b32_e32 v174, 1, v43
	v_pk_mul_f32 v[54:55], v[2:3], v[38:39] op_sel_hi:[1,0]
	v_lshl_add_u64 v[0:1], s[38:39], 0, v[0:1]
	v_lshl_add_u64 v[38:39], v[0:1], 0, v[174:175]
	v_mov_b32_e32 v0, 0x1c000
	v_lshl_or_b32 v174, v43, 14, v0
	v_lshl_add_u64 v[0:1], v[30:31], 0, v[174:175]
	global_load_dwordx4 v[0:3], v[0:1], off nt
	s_waitcnt vmcnt(4)
	v_pk_mul_f32 v[12:13], v[12:13], v[40:41] op_sel_hi:[1,0]
	v_pk_mul_f32 v[8:9], v[8:9], v[42:43] op_sel_hi:[1,0]
	s_waitcnt vmcnt(1)
	v_pk_mul_f32 v[24:25], v[24:25], v[50:51] op_sel_hi:[1,0]
	v_pk_mul_f32 v[20:21], v[20:21], v[46:47] op_sel_hi:[1,0]
	v_pk_mul_f32 v[16:17], v[16:17], v[48:49] op_sel_hi:[1,0]
	v_pk_mul_f32 v[4:5], v[4:5], v[36:37] op_sel_hi:[1,0]
	v_lshlrev_b32_e32 v174, 11, v37
	v_pk_mul_f32 v[14:15], v[14:15], v[40:41] op_sel_hi:[1,0]
	v_lshl_add_u64 v[40:41], v[38:39], 0, v[174:175]
	v_pk_mul_f32 v[26:27], v[26:27], v[50:51] op_sel_hi:[1,0]
	v_pk_mul_f32 v[22:23], v[22:23], v[46:47] op_sel_hi:[1,0]
	v_pk_mul_f32 v[18:19], v[18:19], v[48:49] op_sel_hi:[1,0]
	v_pk_mul_f32 v[10:11], v[10:11], v[42:43] op_sel_hi:[1,0]
	v_pk_mul_f32 v[6:7], v[6:7], v[36:37] op_sel_hi:[1,0]
	v_mov_b32_e32 v42, 1.0
	s_and_b64 vcc, exec, s[40:41]
	s_waitcnt vmcnt(0)
	v_pk_mul_f32 v[60:61], v[0:1], v[44:45] op_sel_hi:[1,0]
	v_cvt_pk_bf16_f32 v1, v8, v12
	v_lshlrev_b32_e32 v8, 10, v37
	v_pk_mul_f32 v[58:59], v[2:3], v[44:45] op_sel_hi:[1,0]
	v_cvt_pk_bf16_f32 v0, v56, v4
	v_cvt_pk_bf16_f32 v2, v16, v20
	v_cvt_pk_bf16_f32 v3, v24, v60
	v_or_b32_e32 v4, 0x800, v8
	global_store_dwordx4 v[40:41], v[0:3], off
	v_lshlrev_b32_e32 v174, 1, v4
	v_mov_b32_e32 v37, v175
	v_cvt_pk_bf16_f32 v0, v57, v5
	v_cvt_pk_bf16_f32 v1, v9, v13
	v_cvt_pk_bf16_f32 v2, v17, v21
	v_cvt_pk_bf16_f32 v3, v25, v61
	global_store_dwordx4 v[40:41], v[0:3], off offset:2048
	v_lshl_add_u64 v[4:5], v[38:39], 0, v[174:175]
	v_mov_b32_e32 v44, 1.0
	v_cvt_pk_bf16_f32 v0, v54, v6
	v_cvt_pk_bf16_f32 v1, v10, v14
	v_cvt_pk_bf16_f32 v2, v18, v22
	v_cvt_pk_bf16_f32 v3, v26, v58
	global_store_dwordx4 v[4:5], v[0:3], off
	v_or_b32_e32 v4, 0xc00, v8
	v_lshlrev_b32_e32 v36, 1, v4
	v_cvt_pk_bf16_f32 v0, v55, v7
	v_cvt_pk_bf16_f32 v1, v11, v15
	v_cvt_pk_bf16_f32 v2, v19, v23
	v_cvt_pk_bf16_f32 v3, v27, v59
	v_lshl_add_u64 v[4:5], v[38:39], 0, v[36:37]
	global_store_dwordx4 v[4:5], v[0:3], off
	s_cbranch_vccnz .LBB0_1459
	v_mov_b32_e32 v35, v175
	v_lshl_add_u64 v[0:1], v[32:33], 0, v[34:35]
	global_load_dword v44, v[0:1], off offset:32
; __device__ __forceinline__ unsigned pk2(float lo, float hi) { f32x2 v = {lo, hi}; bf16x2_t b = __builtin_convertvector(v, bf16x2_t); return __builtin_bit_cast(unsigned, b); }
; __device__ __forceinline__ void p0_cvt_item(const float* W, int K, int N, bf16_t* WT, int row_off, const float* gain, int item, int lane) {
;     const int nblk = N / 256, kb = item / nblk, nb = item % nblk, k0 = 16 * kb, n0 = 256 * nb + 4 * lane;
; #pragma unroll
;     for (int kk = 0; kk < 16; kk += 8) {
;         f32x4 v[8];
; #pragma unroll
;         for (int j = 0; j < 8; ++j) { const float gk = gain ? gain[k0 + kk + j] : 1.f; v[j] = *(const f32x4*)(W + (size_t)(k0 + kk + j) * N + n0) * gk; }
; #pragma unroll
;         for (int c = 0; c < 4; ++c) { u32x4 o; o.x = pk2(v[0][c], v[1][c]); o.y = pk2(v[2][c], v[3][c]); o.z = pk2(v[4][c], v[5][c]); o.w = pk2(v[6][c], v[7][c]);
;             *(u32x4*)(WT + (size_t)(row_off + n0 + c) * K + k0 + kk) = o; }
; __device__ __forceinline__ void p0_phase(const Args& a, LAS unsigned char* lds, int G, int wg, int part, bool split) {
;     ...
;         if (r < 3 * I_W1) { const int j = r / I_W1; r -= j * I_W1;
;             p0_cvt_item(a.in[13] + (size_t)j * DM * FF, DM, FF, (bf16_t*)(ws + WS_W1) + (size_t)j * FF * DM, 0, norm_mlp + j * DM, r, lane); continue; } r -= 3 * I_W1;
.LBB0_1459:
	s_nop 0
	v_mov_b32_e32 v0, 0x20000
	v_lshl_or_b32 v0, v43, 14, v0
	v_mov_b32_e32 v1, v175
	v_lshl_add_u64 v[0:1], v[30:31], 0, v[0:1]
	global_load_dwordx4 v[0:3], v[0:1], off nt
	s_and_b64 vcc, exec, s[40:41]
	s_cbranch_vccnz .LBB0_1461
	v_mov_b32_e32 v35, v175
	v_lshl_add_u64 v[4:5], v[32:33], 0, v[34:35]
	global_load_dword v42, v[4:5], off offset:36
.LBB0_1461:
	v_mov_b32_e32 v4, 0x24000
	v_lshl_or_b32 v4, v43, 14, v4
	v_mov_b32_e32 v5, v175
	v_lshl_add_u64 v[4:5], v[30:31], 0, v[4:5]
	global_load_dwordx4 v[4:7], v[4:5], off nt
	v_mov_b32_e32 v48, 1.0
	s_and_b64 vcc, exec, s[40:41]
	v_mov_b32_e32 v50, 1.0
	s_cbranch_vccnz .LBB0_1463
	v_mov_b32_e32 v35, v175
	v_lshl_add_u64 v[8:9], v[32:33], 0, v[34:35]
	global_load_dword v50, v[8:9], off offset:40
.LBB0_1463:
	v_mov_b32_e32 v8, 0x28000
	v_lshl_or_b32 v8, v43, 14, v8
	v_mov_b32_e32 v9, v175
	v_lshl_add_u64 v[8:9], v[30:31], 0, v[8:9]
	global_load_dwordx4 v[8:11], v[8:9], off nt
	s_and_b64 vcc, exec, s[40:41]
	s_cbranch_vccnz .LBB0_1465
	v_mov_b32_e32 v35, v175
	v_lshl_add_u64 v[12:13], v[32:33], 0, v[34:35]
	global_load_dword v48, v[12:13], off offset:44
.LBB0_1465:
	v_mov_b32_e32 v12, 0x2c000
	v_lshl_or_b32 v12, v43, 14, v12
	v_mov_b32_e32 v13, v175
	v_lshl_add_u64 v[12:13], v[30:31], 0, v[12:13]
	global_load_dwordx4 v[12:15], v[12:13], off nt
	v_mov_b32_e32 v52, 1.0
	s_and_b64 vcc, exec, s[40:41]
	v_mov_b32_e32 v54, 1.0
	s_cbranch_vccnz .LBB0_1467
	v_mov_b32_e32 v35, v175
	v_lshl_add_u64 v[16:17], v[32:33], 0, v[34:35]
	global_load_dword v54, v[16:17], off offset:48
.LBB0_1467:
	v_mov_b32_e32 v16, 0x30000
	v_lshl_or_b32 v16, v43, 14, v16
	v_mov_b32_e32 v17, v175
	v_lshl_add_u64 v[16:17], v[30:31], 0, v[16:17]
	global_load_dwordx4 v[16:19], v[16:17], off nt
	s_and_b64 vcc, exec, s[40:41]
	s_cbranch_vccnz .LBB0_1469
	v_mov_b32_e32 v35, v175
	v_lshl_add_u64 v[20:21], v[32:33], 0, v[34:35]
	global_load_dword v52, v[20:21], off offset:52
.LBB0_1469:
	v_mov_b32_e32 v20, 0x34000
	v_lshl_or_b32 v20, v43, 14, v20
	v_mov_b32_e32 v21, v175
	v_lshl_add_u64 v[20:21], v[30:31], 0, v[20:21]
	global_load_dwordx4 v[20:23], v[20:21], off nt
	v_mov_b32_e32 v46, 1.0
	s_and_b64 vcc, exec, s[40:41]
	v_mov_b32_e32 v56, 1.0
	s_cbranch_vccnz .LBB0_1471
	v_mov_b32_e32 v35, v175
	v_lshl_add_u64 v[24:25], v[32:33], 0, v[34:35]
	global_load_dword v56, v[24:25], off offset:56
.LBB0_1471:
	v_mov_b32_e32 v24, 0x38000
	v_lshl_or_b32 v24, v43, 14, v24
	v_mov_b32_e32 v25, v175
	v_lshl_add_u64 v[24:25], v[30:31], 0, v[24:25]
	global_load_dwordx4 v[24:27], v[24:25], off nt
	s_and_b64 vcc, exec, s[40:41]
	s_cbranch_vccnz .LBB0_1473
	v_mov_b32_e32 v35, v175
	v_lshl_add_u64 v[32:33], v[32:33], 0, v[34:35]
	global_load_dword v46, v[32:33], off offset:60
.LBB0_1473:
	s_waitcnt vmcnt(6)
	v_pk_mul_f32 v[34:35], v[0:1], v[44:45] op_sel_hi:[1,0]
	v_mov_b32_e32 v0, 0x3c000
	v_lshl_or_b32 v0, v43, 14, v0
	v_mov_b32_e32 v1, v175
	v_lshl_add_u64 v[0:1], v[30:31], 0, v[0:1]
	v_pk_mul_f32 v[32:33], v[2:3], v[44:45] op_sel_hi:[1,0]
	global_load_dwordx4 v[0:3], v[0:1], off nt
	s_waitcnt vmcnt(1)
	v_pk_mul_f32 v[24:25], v[24:25], v[56:57] op_sel_hi:[1,0]
	v_pk_mul_f32 v[20:21], v[20:21], v[52:53] op_sel_hi:[1,0]
	v_pk_mul_f32 v[16:17], v[16:17], v[54:55] op_sel_hi:[1,0]
	v_pk_mul_f32 v[12:13], v[12:13], v[48:49] op_sel_hi:[1,0]
	v_pk_mul_f32 v[8:9], v[8:9], v[50:51] op_sel_hi:[1,0]
	v_pk_mul_f32 v[6:7], v[6:7], v[42:43] op_sel_hi:[1,0]
	v_pk_mul_f32 v[4:5], v[4:5], v[42:43] op_sel_hi:[1,0]
	v_pk_mul_f32 v[26:27], v[26:27], v[56:57] op_sel_hi:[1,0]
	v_pk_mul_f32 v[22:23], v[22:23], v[52:53] op_sel_hi:[1,0]
	v_pk_mul_f32 v[18:19], v[18:19], v[54:55] op_sel_hi:[1,0]
	v_pk_mul_f32 v[14:15], v[14:15], v[48:49] op_sel_hi:[1,0]
	v_pk_mul_f32 v[10:11], v[10:11], v[50:51] op_sel_hi:[1,0]
	v_lshl_add_u64 v[38:39], v[38:39], 0, 16
	v_mov_b32_e32 v37, v175
	s_waitcnt vmcnt(0)
	v_pk_mul_f32 v[42:43], v[0:1], v[46:47] op_sel_hi:[1,0]
	v_pk_mul_f32 v[30:31], v[2:3], v[46:47] op_sel_hi:[1,0]
	v_cvt_pk_bf16_f32 v0, v34, v4
	v_cvt_pk_bf16_f32 v1, v8, v12
	v_cvt_pk_bf16_f32 v2, v16, v20
	v_cvt_pk_bf16_f32 v3, v24, v42
	global_store_dwordx4 v[40:41], v[0:3], off offset:16
	s_nop 1
	v_cvt_pk_bf16_f32 v0, v35, v5
	v_cvt_pk_bf16_f32 v1, v9, v13
	v_cvt_pk_bf16_f32 v2, v17, v21
	v_cvt_pk_bf16_f32 v3, v25, v43
	global_store_dwordx4 v[40:41], v[0:3], off offset:2064
	v_lshl_add_u64 v[4:5], v[38:39], 0, v[174:175]
	s_nop 0
	v_cvt_pk_bf16_f32 v0, v32, v6
	v_cvt_pk_bf16_f32 v1, v10, v14
	v_cvt_pk_bf16_f32 v2, v18, v22
	v_cvt_pk_bf16_f32 v3, v26, v30
	global_store_dwordx4 v[4:5], v[0:3], off
	v_lshl_add_u64 v[4:5], v[38:39], 0, v[36:37]
	s_nop 0
	v_cvt_pk_bf16_f32 v0, v33, v7
	v_cvt_pk_bf16_f32 v1, v11, v15
	v_cvt_pk_bf16_f32 v2, v19, v23
	v_cvt_pk_bf16_f32 v3, v27, v31
	global_store_dwordx4 v[4:5], v[0:3], off

; __device__ __forceinline__ unsigned pk2(float lo, float hi) { f32x2 v = {lo, hi}; bf16x2_t b = __builtin_convertvector(v, bf16x2_t); return __builtin_bit_cast(unsigned, b); }
; __device__ __forceinline__ void p0_cvt_item(const float* W, int K, int N, bf16_t* WT, int row_off, const float* gain, int item, int lane) {
;     const int nblk = N / 256, kb = item / nblk, nb = item % nblk, k0 = 16 * kb, n0 = 256 * nb + 4 * lane;
; #pragma unroll
;     for (int kk = 0; kk < 16; kk += 8) {
;         f32x4 v[8];
; #pragma unroll
;         for (int j = 0; j < 8; ++j) { const float gk = gain ? gain[k0 + kk + j] : 1.f; v[j] = *(const f32x4*)(W + (size_t)(k0 + kk + j) * N + n0) * gk; }
; #pragma unroll
;         for (int c = 0; c < 4; ++c) { u32x4 o; o.x = pk2(v[0][c], v[1][c]); o.y = pk2(v[2][c], v[3][c]); o.z = pk2(v[4][c], v[5][c]); o.w = pk2(v[6][c], v[7][c]);
;             *(u32x4*)(WT + (size_t)(row_off + n0 + c) * K + k0 + kk) = o; }
; __device__ __forceinline__ void p0_phase(const Args& a, LAS unsigned char* lds, int G, int wg, int part, bool split) {
;     ...
;         if (r < 4 * I_CW) { const int g = r / I_CW; r -= g * I_CW;
;             p0_cvt_item(a.in[11] + (size_t)g * 256 * 256, 256, 256, (bf16_t*)(ws + WS_CW), g * 256, nullptr, r, lane); continue; } r -= 4 * I_CW;
.LBB0_1475:
	s_andn2_saveexec_b64 s[0:1], s[54:55]
	s_cbranch_execz .LBB0_1477
	v_add_u32_e32 v0, 0xffff1940, v51
	v_lshrrev_b32_e32 v174, 4, v0
	v_and_b32_e32 v2, 0xf0, v53
	v_readlane_b32 s38, v254, 6
	v_lshlrev_b64 v[0:1], 18, v[174:175]
	v_lshl_or_b32 v26, v174, 8, v45
	v_lshlrev_b32_e32 v174, 1, v2
	v_readlane_b32 s39, v254, 7
	v_lshl_add_u64 v[0:1], v[28:29], 0, v[0:1]
	s_movk_i32 s16, 0x1000
	v_lshl_add_u64 v[42:43], s[38:39], 0, v[174:175]
	v_lshlrev_b32_e32 v174, 10, v2
	v_lshl_add_u64 v[54:55], v[0:1], 0, v[174:175]
	v_add_co_u32_e32 v0, vcc, s16, v54
	global_load_dwordx4 v[2:5], v[54:55], off nt
	global_load_dwordx4 v[6:9], v[54:55], off offset:1024 nt
	global_load_dwordx4 v[10:13], v[54:55], off offset:2048 nt
	global_load_dwordx4 v[14:17], v[54:55], off offset:3072 nt
	v_addc_co_u32_e32 v1, vcc, 0, v55, vcc
	v_add_co_u32_e32 v56, vcc, s23, v54
	v_mov_b32_e32 v27, v175
	s_nop 0
	v_addc_co_u32_e32 v57, vcc, 0, v55, vcc
	global_load_dwordx4 v[18:21], v[56:57], off offset:-4096 nt
	global_load_dwordx4 v[22:25], v[0:1], off offset:1024 nt
	global_load_dwordx4 v[30:33], v[0:1], off offset:2048 nt
	global_load_dwordx4 v[34:37], v[0:1], off offset:3072 nt
	v_lshlrev_b64 v[0:1], 9, v[26:27]
	v_lshl_add_u64 v[0:1], v[42:43], 0, v[0:1]
	v_or_b32_e32 v174, 1, v26
	s_movk_i32 s16, 0x3000
	s_waitcnt vmcnt(6)
	v_cvt_pk_bf16_f32 v38, v2, v6
	s_waitcnt vmcnt(4)
	v_cvt_pk_bf16_f32 v39, v10, v14
	s_waitcnt vmcnt(2)
	v_cvt_pk_bf16_f32 v40, v18, v22
	s_waitcnt vmcnt(0)
	v_cvt_pk_bf16_f32 v41, v30, v34
	global_store_dwordx4 v[0:1], v[38:41], off
	s_nop 1
	v_cvt_pk_bf16_f32 v38, v3, v7
	v_lshlrev_b64 v[2:3], 9, v[174:175]
	v_or_b32_e32 v174, 2, v26
	v_cvt_pk_bf16_f32 v39, v11, v15
	v_cvt_pk_bf16_f32 v40, v19, v23
	v_cvt_pk_bf16_f32 v41, v31, v35
	v_lshl_add_u64 v[2:3], v[42:43], 0, v[2:3]
	v_lshlrev_b64 v[6:7], 9, v[174:175]
	v_or_b32_e32 v174, 3, v26
	global_store_dwordx4 v[2:3], v[38:41], off
	v_lshl_add_u64 v[58:59], v[42:43], 0, v[6:7]
	v_cvt_pk_bf16_f32 v6, v5, v9
	v_cvt_pk_bf16_f32 v38, v4, v8
	v_lshlrev_b64 v[4:5], 9, v[174:175]
	v_cvt_pk_bf16_f32 v39, v12, v16
	v_cvt_pk_bf16_f32 v40, v20, v24
	v_cvt_pk_bf16_f32 v41, v32, v36
	v_cvt_pk_bf16_f32 v7, v13, v17
	v_cvt_pk_bf16_f32 v8, v21, v25
	v_cvt_pk_bf16_f32 v9, v33, v37
	v_lshl_add_u64 v[4:5], v[42:43], 0, v[4:5]
	v_add_co_u32_e32 v26, vcc, s16, v54
	global_store_dwordx4 v[58:59], v[38:41], off
	global_store_dwordx4 v[4:5], v[6:9], off
	v_addc_co_u32_e32 v27, vcc, 0, v55, vcc
	global_load_dwordx4 v[6:9], v[56:57], off nt
	global_load_dwordx4 v[10:13], v[56:57], off offset:1024 nt
	global_load_dwordx4 v[14:17], v[56:57], off offset:2048 nt
	global_load_dwordx4 v[18:21], v[56:57], off offset:3072 nt
	global_load_dwordx4 v[22:25], v[26:27], off nt
	global_load_dwordx4 v[30:33], v[26:27], off offset:1024 nt
	global_load_dwordx4 v[34:37], v[26:27], off offset:2048 nt
	global_load_dwordx4 v[38:41], v[26:27], off offset:3072 nt
	s_waitcnt vmcnt(6)
	v_cvt_pk_bf16_f32 v54, v6, v10
	s_waitcnt vmcnt(2)
	v_cvt_pk_bf16_f32 v56, v22, v30
	v_cvt_pk_bf16_f32 v55, v14, v18
	s_waitcnt vmcnt(0)
	v_cvt_pk_bf16_f32 v57, v34, v38
	global_store_dwordx4 v[0:1], v[54:57], off offset:16
	v_cvt_pk_bf16_f32 v0, v8, v12
	v_cvt_pk_bf16_f32 v1, v16, v20
	v_cvt_pk_bf16_f32 v54, v7, v11
	v_cvt_pk_bf16_f32 v55, v15, v19
	v_cvt_pk_bf16_f32 v56, v23, v31
	v_cvt_pk_bf16_f32 v57, v35, v39
	global_store_dwordx4 v[2:3], v[54:57], off offset:16
	v_cvt_pk_bf16_f32 v2, v24, v32
	v_cvt_pk_bf16_f32 v3, v36, v40
	global_store_dwordx4 v[58:59], v[0:3], off offset:16
	s_nop 1
	v_cvt_pk_bf16_f32 v0, v9, v13
	v_cvt_pk_bf16_f32 v1, v17, v21
	v_cvt_pk_bf16_f32 v2, v25, v33
	v_cvt_pk_bf16_f32 v3, v37, v41
	global_store_dwordx4 v[4:5], v[0:3], off offset:16

; __device__ __forceinline__ unsigned pk2(float lo, float hi) { f32x2 v = {lo, hi}; bf16x2_t b = __builtin_convertvector(v, bf16x2_t); return __builtin_bit_cast(unsigned, b); }
; __device__ __forceinline__ void p0_cvt_item(const float* W, int K, int N, bf16_t* WT, int row_off, const float* gain, int item, int lane) {
;     const int nblk = N / 256, kb = item / nblk, nb = item % nblk, k0 = 16 * kb, n0 = 256 * nb + 4 * lane;
; #pragma unroll
;     for (int kk = 0; kk < 16; kk += 8) {
;         f32x4 v[8];
; #pragma unroll
;         for (int j = 0; j < 8; ++j) { const float gk = gain ? gain[k0 + kk + j] : 1.f; v[j] = *(const f32x4*)(W + (size_t)(k0 + kk + j) * N + n0) * gk; }
; #pragma unroll
;         for (int c = 0; c < 4; ++c) { u32x4 o; o.x = pk2(v[0][c], v[1][c]); o.y = pk2(v[2][c], v[3][c]); o.z = pk2(v[4][c], v[5][c]); o.w = pk2(v[6][c], v[7][c]);
;             *(u32x4*)(WT + (size_t)(row_off + n0 + c) * K + k0 + kk) = o; }
; __device__ __forceinline__ void p0_phase(const Args& a, LAS unsigned char* lds, int G, int wg, int part, bool split) {
;     ...
;         if (r < I_SQ) { p0_cvt_item(a.in[9], DM, DM, (bf16_t*)(ws + WS_BOUT), 0, nullptr, r, lane); continue; } r -= I_SQ;
.LBB0_1478:
	s_andn2_saveexec_b64 s[0:1], s[52:53]
	s_cbranch_execz .LBB0_1480
	v_add_u32_e32 v0, s9, v47
	s_movk_i32 s16, 0x300
	v_add_u32_e32 v0, 0xfffff000, v0
	v_and_or_b32 v6, v49, s16, v45
	v_readlane_b32 s52, v252, 16
	v_and_b32_e32 v4, 0x3f0, v0
	v_lshlrev_b32_e32 v174, 2, v6
	v_readlane_b32 s54, v252, 18
	v_readlane_b32 s55, v252, 19
	v_readlane_b32 s38, v254, 8
	v_readlane_b32 s39, v254, 9
	v_lshl_add_u64 v[2:3], s[54:55], 0, v[174:175]
	v_lshlrev_b32_e32 v174, 1, v4
	v_lshl_add_u64 v[0:1], s[38:39], 0, v[174:175]
	v_lshlrev_b32_e32 v174, 12, v4
	v_lshl_add_u64 v[2:3], v[2:3], 0, v[174:175]
	v_add_co_u32_e32 v4, vcc, 0x1000, v2
	global_load_dwordx4 v[8:11], v[2:3], off nt
	s_nop 0
	v_addc_co_u32_e32 v5, vcc, 0, v3, vcc
	global_load_dwordx4 v[12:15], v[4:5], off nt
	v_add_co_u32_e32 v4, vcc, s23, v2
	v_lshlrev_b32_e32 v174, 11, v6
	s_nop 0
	v_addc_co_u32_e32 v5, vcc, 0, v3, vcc
	global_load_dwordx4 v[16:19], v[4:5], off nt
	v_add_co_u32_e32 v4, vcc, 0x3000, v2
	v_lshl_add_u64 v[6:7], v[0:1], 0, v[174:175]
	s_nop 0
	v_addc_co_u32_e32 v5, vcc, 0, v3, vcc
	global_load_dwordx4 v[20:23], v[4:5], off nt
	v_add_co_u32_e32 v4, vcc, s31, v2
	s_mov_b32 s16, 0x9000
	s_nop 0
	v_addc_co_u32_e32 v5, vcc, 0, v3, vcc
	global_load_dwordx4 v[24:27], v[4:5], off nt
	v_add_co_u32_e32 v4, vcc, 0x5000, v2
	v_lshl_add_u64 v[42:43], v[0:1], 0, 16
	s_nop 0
	v_addc_co_u32_e32 v5, vcc, 0, v3, vcc
	global_load_dwordx4 v[30:33], v[4:5], off nt
	v_add_co_u32_e32 v4, vcc, s33, v2
	v_readlane_b32 s64, v252, 28
	s_nop 0
	v_addc_co_u32_e32 v5, vcc, 0, v3, vcc
	global_load_dwordx4 v[34:37], v[4:5], off nt
	v_add_co_u32_e32 v4, vcc, 0x7000, v2
	v_readlane_b32 s65, v252, 29
	s_nop 0
	v_addc_co_u32_e32 v5, vcc, 0, v3, vcc
	global_load_dwordx4 v[38:41], v[4:5], off nt
	v_or_b32_e32 v4, 0x1000, v174
	v_mov_b32_e32 v5, v175
	v_or_b32_e32 v174, 0x1800, v174
	v_readlane_b32 s63, v252, 27
	v_readlane_b32 s67, v252, 31
	v_readlane_b32 s64, v255, 6
	s_mov_b32 s63, 0x10000
	v_readlane_b32 s67, v255, 8
	v_readlane_b32 s65, v255, 7
	v_readlane_b32 s53, v252, 17
	v_readlane_b32 s56, v252, 20
	v_readlane_b32 s57, v252, 21
	v_readlane_b32 s58, v252, 22
	v_readlane_b32 s59, v252, 23
	v_readlane_b32 s60, v252, 24
	v_readlane_b32 s61, v252, 25
	v_readlane_b32 s62, v252, 26
	v_readlane_b32 s66, v252, 30
	s_waitcnt vmcnt(6)
	v_cvt_pk_bf16_f32 v54, v8, v12
	s_waitcnt vmcnt(4)
	v_cvt_pk_bf16_f32 v55, v16, v20
	s_waitcnt vmcnt(2)
	v_cvt_pk_bf16_f32 v56, v24, v30
	s_waitcnt vmcnt(0)
	v_cvt_pk_bf16_f32 v57, v34, v38
	global_store_dwordx4 v[6:7], v[54:57], off
	s_nop 1
	v_cvt_pk_bf16_f32 v54, v9, v13
	v_cvt_pk_bf16_f32 v55, v17, v21
	v_cvt_pk_bf16_f32 v56, v25, v31
	v_cvt_pk_bf16_f32 v57, v35, v39
	global_store_dwordx4 v[6:7], v[54:57], off offset:2048
	v_lshl_add_u64 v[8:9], v[0:1], 0, v[4:5]
	v_lshl_add_u64 v[12:13], v[0:1], 0, v[174:175]
	v_cvt_pk_bf16_f32 v54, v10, v14
	v_cvt_pk_bf16_f32 v55, v18, v22
	v_cvt_pk_bf16_f32 v56, v26, v32
	v_cvt_pk_bf16_f32 v57, v36, v40
	global_store_dwordx4 v[8:9], v[54:57], off
	v_cvt_pk_bf16_f32 v8, v11, v15
	v_cvt_pk_bf16_f32 v9, v19, v23
	v_cvt_pk_bf16_f32 v10, v27, v33
	v_cvt_pk_bf16_f32 v11, v37, v41
	global_store_dwordx4 v[12:13], v[8:11], off
	v_add_co_u32_e32 v12, vcc, s16, v2
	s_mov_b32 s16, 0xb000
	s_nop 0
	v_addc_co_u32_e32 v13, vcc, 0, v3, vcc
	v_add_co_u32_e32 v20, vcc, s16, v2
	s_mov_b32 s16, 0xd000
	s_nop 0
	v_addc_co_u32_e32 v21, vcc, 0, v3, vcc
	v_add_co_u32_e32 v30, vcc, s16, v2
	s_mov_b32 s16, 0xf000
	s_nop 0
	v_addc_co_u32_e32 v31, vcc, 0, v3, vcc
	v_add_co_u32_e32 v2, vcc, s16, v2
	global_load_dwordx4 v[8:11], v[12:13], off offset:-4096 nt
	s_nop 0
	global_load_dwordx4 v[12:15], v[12:13], off nt
	v_addc_co_u32_e32 v3, vcc, 0, v3, vcc
	global_load_dwordx4 v[16:19], v[20:21], off offset:-4096 nt
	s_nop 0
	global_load_dwordx4 v[20:23], v[20:21], off nt
	s_nop 0
	global_load_dwordx4 v[24:27], v[30:31], off offset:-4096 nt
	s_nop 0
	global_load_dwordx4 v[30:33], v[30:31], off nt
	s_nop 0
	global_load_dwordx4 v[34:37], v[2:3], off offset:-4096 nt
	global_load_dwordx4 v[38:41], v[2:3], off nt
	v_lshl_add_u64 v[4:5], v[42:43], 0, v[4:5]
	s_waitcnt vmcnt(6)
	v_cvt_pk_bf16_f32 v0, v8, v12
	s_waitcnt vmcnt(4)
	v_cvt_pk_bf16_f32 v1, v16, v20
	s_waitcnt vmcnt(2)
	v_cvt_pk_bf16_f32 v2, v24, v30
	s_waitcnt vmcnt(0)
	v_cvt_pk_bf16_f32 v3, v34, v38
	global_store_dwordx4 v[6:7], v[0:3], off offset:16
	s_nop 1
	v_cvt_pk_bf16_f32 v0, v9, v13
	v_cvt_pk_bf16_f32 v1, v17, v21
	v_cvt_pk_bf16_f32 v2, v25, v31
	v_cvt_pk_bf16_f32 v3, v35, v39
	global_store_dwordx4 v[6:7], v[0:3], off offset:2064
	s_nop 1
	v_cvt_pk_bf16_f32 v0, v10, v14
	v_cvt_pk_bf16_f32 v1, v18, v22
	v_cvt_pk_bf16_f32 v2, v26, v32
	v_cvt_pk_bf16_f32 v3, v36, v40
	global_store_dwordx4 v[4:5], v[0:3], off
	v_lshl_add_u64 v[4:5], v[42:43], 0, v[174:175]
	s_nop 0
	v_cvt_pk_bf16_f32 v0, v11, v15
	v_cvt_pk_bf16_f32 v1, v19, v23
	v_cvt_pk_bf16_f32 v2, v27, v33
	v_cvt_pk_bf16_f32 v3, v37, v41
	global_store_dwordx4 v[4:5], v[0:3], off

; __device__ __forceinline__ unsigned pk2(float lo, float hi) { f32x2 v = {lo, hi}; bf16x2_t b = __builtin_convertvector(v, bf16x2_t); return __builtin_bit_cast(unsigned, b); }
; __device__ __forceinline__ void p0_cvt_item(const float* W, int K, int N, bf16_t* WT, int row_off, const float* gain, int item, int lane) {
;     const int nblk = N / 256, kb = item / nblk, nb = item % nblk, k0 = 16 * kb, n0 = 256 * nb + 4 * lane;
; #pragma unroll
;     for (int kk = 0; kk < 16; kk += 8) {
;         f32x4 v[8];
; #pragma unroll
;         for (int j = 0; j < 8; ++j) { const float gk = gain ? gain[k0 + kk + j] : 1.f; v[j] = *(const f32x4*)(W + (size_t)(k0 + kk + j) * N + n0) * gk; }
; #pragma unroll
;         for (int c = 0; c < 4; ++c) { u32x4 o; o.x = pk2(v[0][c], v[1][c]); o.y = pk2(v[2][c], v[3][c]); o.z = pk2(v[4][c], v[5][c]); o.w = pk2(v[6][c], v[7][c]);
;             *(u32x4*)(WT + (size_t)(row_off + n0 + c) * K + k0 + kk) = o; }
; __device__ __forceinline__ void p0_phase(const Args& a, LAS unsigned char* lds, int G, int wg, int part, bool split) {
;     ...
;         if (r < I_QKV) { p0_cvt_item(a.in[8], DM, 3072, (bf16_t*)(ws + WS_BQKV), 0, norm_mix + 1 * DM, r, lane); continue; } r -= I_QKV;
.LBB0_1481:
	s_andn2_saveexec_b64 s[0:1], s[50:51]
	s_cbranch_execz .LBB0_1483
	v_add_u16_e32 v0, 0xf700, v0
	v_mul_u32_u24_e32 v1, 0xaaab, v0
	v_lshrrev_b32_e32 v4, 19, v1
	v_mul_lo_u16_e32 v1, 12, v4
	v_sub_u16_sdwa v0, v0, v1 dst_sel:BYTE_1 dst_unused:UNUSED_PAD src0_sel:DWORD src1_sel:DWORD
	v_readlane_b32 s52, v252, 16
	v_or_b32_e32 v9, v45, v0
	v_lshlrev_b32_e32 v174, 2, v9
	v_readlane_b32 s53, v252, 17
	v_readlane_b32 s38, v252, 42
	v_lshlrev_b32_e32 v8, 4, v4
	v_lshl_add_u64 v[2:3], s[52:53], 0, v[174:175]
	v_lshlrev_b32_e32 v174, 5, v4
	v_readlane_b32 s39, v252, 43
	v_readlane_b32 s40, v254, 10
	s_movk_i32 s16, 0x3000
	v_lshl_add_u64 v[0:1], s[38:39], 0, v[174:175]
	v_lshlrev_b32_e32 v10, 6, v4
	v_readlane_b32 s41, v254, 11
	v_mad_u64_u32 v[14:15], s[38:39], v8, s16, v[2:3]
	s_nop 3
	global_load_dwordx4 v[4:7], v10, s[40:41] offset:16
	s_nop 0
	global_load_dwordx4 v[10:13], v10, s[40:41]
	v_lshlrev_b32_e32 v174, 11, v9
	global_load_dwordx4 v[14:17], v[14:15], off nt
	v_or_b32_e32 v9, 8, v8
	v_readlane_b32 s64, v252, 28
	v_readlane_b32 s65, v252, 29
	v_readlane_b32 s63, v252, 27
	v_readlane_b32 s67, v252, 31
	v_readlane_b32 s64, v255, 6
	s_mov_b32 s63, 0x10000
	v_readlane_b32 s67, v255, 8
	v_readlane_b32 s65, v255, 7
	v_readlane_b32 s54, v252, 18
	v_readlane_b32 s55, v252, 19
	v_readlane_b32 s56, v252, 20
	v_readlane_b32 s57, v252, 21
	v_readlane_b32 s58, v252, 22
	v_readlane_b32 s59, v252, 23
	v_readlane_b32 s60, v252, 24
	v_readlane_b32 s61, v252, 25
	v_readlane_b32 s62, v252, 26
	v_readlane_b32 s66, v252, 30
	s_waitcnt vmcnt(0)
	v_pk_mul_f32 v[20:21], v[14:15], v[10:11] op_sel_hi:[1,0]
	v_or_b32_e32 v14, 1, v8
	v_mad_u64_u32 v[14:15], s[38:39], v14, s16, v[2:3]
	v_pk_mul_f32 v[18:19], v[16:17], v[10:11] op_sel_hi:[1,0]
	global_load_dwordx4 v[14:17], v[14:15], off nt
	s_waitcnt vmcnt(0)
	v_pk_mul_f32 v[22:23], v[16:17], v[10:11] op_sel:[0,1]
	v_pk_mul_f32 v[24:25], v[14:15], v[10:11] op_sel:[0,1]
	v_or_b32_e32 v10, 2, v8
	v_mad_u64_u32 v[10:11], s[38:39], v10, s16, v[2:3]
	global_load_dwordx4 v[14:17], v[10:11], off nt
	v_or_b32_e32 v10, 3, v8
	v_mad_u64_u32 v[10:11], s[38:39], v10, s16, v[2:3]
	s_waitcnt vmcnt(0)
	v_pk_mul_f32 v[26:27], v[16:17], v[12:13] op_sel_hi:[1,0]
	v_pk_mul_f32 v[30:31], v[14:15], v[12:13] op_sel_hi:[1,0]
	global_load_dwordx4 v[14:17], v[10:11], off nt
	v_mov_b32_e32 v10, v13
	s_waitcnt vmcnt(0)
	v_pk_mul_f32 v[16:17], v[16:17], v[10:11] op_sel_hi:[1,0]
	v_pk_mul_f32 v[14:15], v[14:15], v[10:11] op_sel_hi:[1,0]
	v_or_b32_e32 v10, 4, v8
	v_mad_u64_u32 v[10:11], s[38:39], v10, s16, v[2:3]
	global_load_dwordx4 v[10:13], v[10:11], off nt
	s_waitcnt vmcnt(0)
	v_pk_mul_f32 v[34:35], v[10:11], v[4:5] op_sel_hi:[1,0]
	v_or_b32_e32 v10, 5, v8
	v_mad_u64_u32 v[10:11], s[38:39], v10, s16, v[2:3]
	v_pk_mul_f32 v[32:33], v[12:13], v[4:5] op_sel_hi:[1,0]
	global_load_dwordx4 v[10:13], v[10:11], off nt
	s_waitcnt vmcnt(0)
	v_pk_mul_f32 v[36:37], v[12:13], v[4:5] op_sel:[0,1]
	v_pk_mul_f32 v[4:5], v[10:11], v[4:5] op_sel:[0,1]
	v_or_b32_e32 v10, 6, v8
	v_mad_u64_u32 v[10:11], s[38:39], v10, s16, v[2:3]
	global_load_dwordx4 v[10:13], v[10:11], off nt
	s_waitcnt vmcnt(0)
	v_pk_mul_f32 v[38:39], v[12:13], v[6:7] op_sel_hi:[1,0]
	v_pk_mul_f32 v[40:41], v[10:11], v[6:7] op_sel_hi:[1,0]
	v_or_b32_e32 v6, 7, v8
	v_mad_u64_u32 v[10:11], s[38:39], v6, s16, v[2:3]
	global_load_dwordx4 v[10:13], v[10:11], off nt
	v_mov_b32_e32 v6, v7
	s_waitcnt vmcnt(0)
; __device__ __forceinline__ unsigned pk2(float lo, float hi) { f32x2 v = {lo, hi}; bf16x2_t b = __builtin_convertvector(v, bf16x2_t); return __builtin_bit_cast(unsigned, b); }
; __device__ __forceinline__ void p0_cvt_item(const float* W, int K, int N, bf16_t* WT, int row_off, const float* gain, int item, int lane) {
;     const int nblk = N / 256, kb = item / nblk, nb = item % nblk, k0 = 16 * kb, n0 = 256 * nb + 4 * lane;
; #pragma unroll
;     for (int kk = 0; kk < 16; kk += 8) {
;         f32x4 v[8];
; #pragma unroll
;         for (int j = 0; j < 8; ++j) { const float gk = gain ? gain[k0 + kk + j] : 1.f; v[j] = *(const f32x4*)(W + (size_t)(k0 + kk + j) * N + n0) * gk; }
; #pragma unroll
;         for (int c = 0; c < 4; ++c) { u32x4 o; o.x = pk2(v[0][c], v[1][c]); o.y = pk2(v[2][c], v[3][c]); o.z = pk2(v[4][c], v[5][c]); o.w = pk2(v[6][c], v[7][c]);
;             *(u32x4*)(WT + (size_t)(row_off + n0 + c) * K + k0 + kk) = o; }
; __device__ __forceinline__ void p0_phase(const Args& a, LAS unsigned char* lds, int G, int wg, int part, bool split) {
;     ...
;         if (r < I_QKV) { p0_cvt_item(a.in[8], DM, 3072, (bf16_t*)(ws + WS_BQKV), 0, norm_mix + 1 * DM, r, lane); continue; } r -= I_QKV;
	v_pk_mul_f32 v[54:55], v[10:11], v[6:7] op_sel_hi:[1,0]
	v_pk_mul_f32 v[42:43], v[12:13], v[6:7] op_sel_hi:[1,0]
	v_cvt_pk_bf16_f32 v10, v20, v24
	v_cvt_pk_bf16_f32 v11, v30, v14
	v_cvt_pk_bf16_f32 v12, v34, v4
	v_cvt_pk_bf16_f32 v13, v40, v54
	v_lshl_add_u64 v[6:7], v[0:1], 0, v[174:175]
	global_store_dwordx4 v[6:7], v[10:13], off
	v_or_b32_e32 v4, 0x1000, v174
	v_or_b32_e32 v174, 0x1800, v174
	v_cvt_pk_bf16_f32 v10, v21, v25
	v_cvt_pk_bf16_f32 v11, v31, v15
	v_cvt_pk_bf16_f32 v12, v35, v5
	v_cvt_pk_bf16_f32 v13, v41, v55
	v_mov_b32_e32 v5, v175
	global_store_dwordx4 v[6:7], v[10:13], off offset:2048
	v_lshl_add_u64 v[14:15], v[0:1], 0, v[4:5]
	s_nop 0
	v_cvt_pk_bf16_f32 v10, v18, v22
	v_cvt_pk_bf16_f32 v11, v26, v16
	v_cvt_pk_bf16_f32 v12, v32, v36
	v_cvt_pk_bf16_f32 v13, v38, v42
	global_store_dwordx4 v[14:15], v[10:13], off
	v_lshl_add_u64 v[14:15], v[0:1], 0, v[174:175]
	s_nop 0
	v_cvt_pk_bf16_f32 v10, v19, v23
	v_cvt_pk_bf16_f32 v11, v27, v17
	v_cvt_pk_bf16_f32 v12, v33, v37
	v_cvt_pk_bf16_f32 v13, v39, v43
	global_store_dwordx4 v[14:15], v[10:13], off
	v_lshlrev_b32_e32 v14, 2, v9
	v_mad_u64_u32 v[18:19], s[38:39], v9, s16, v[2:3]
	v_or_b32_e32 v9, 9, v8
	v_mad_u64_u32 v[22:23], s[38:39], v9, s16, v[2:3]
	v_or_b32_e32 v9, 10, v8
	v_mad_u64_u32 v[26:27], s[38:39], v9, s16, v[2:3]
	v_or_b32_e32 v9, 11, v8
	global_load_dwordx4 v[10:13], v14, s[40:41] offset:16
	s_nop 0
	global_load_dwordx4 v[14:17], v14, s[40:41]
	s_nop 0
	global_load_dwordx4 v[22:25], v[22:23], off nt
	s_nop 0
	global_load_dwordx4 v[30:33], v[26:27], off nt
	v_mad_u64_u32 v[26:27], s[38:39], v9, s16, v[2:3]
	v_or_b32_e32 v9, 12, v8
	global_load_dwordx4 v[34:37], v[26:27], off nt
	v_mad_u64_u32 v[26:27], s[38:39], v9, s16, v[2:3]
	v_or_b32_e32 v9, 13, v8
	global_load_dwordx4 v[38:41], v[26:27], off nt
	v_mad_u64_u32 v[26:27], s[38:39], v9, s16, v[2:3]
	global_load_dwordx4 v[54:57], v[26:27], off nt
	v_or_b32_e32 v9, 14, v8
	v_mad_u64_u32 v[26:27], s[38:39], v9, s16, v[2:3]
	v_or_b32_e32 v9, 15, v8
	v_mad_u64_u32 v[2:3], s[38:39], v9, s16, v[2:3]
	global_load_dwordx4 v[18:21], v[18:19], off nt
	s_waitcnt vmcnt(6)
	v_mov_b32_e32 v8, v17
	global_load_dwordx4 v[58:61], v[26:27], off nt
	s_waitcnt vmcnt(6)
	v_pk_mul_f32 v[24:25], v[24:25], v[14:15] op_sel:[0,1]
	v_pk_mul_f32 v[22:23], v[22:23], v[14:15] op_sel:[0,1]
	s_waitcnt vmcnt(5)
	v_pk_mul_f32 v[32:33], v[32:33], v[16:17] op_sel_hi:[1,0]
	v_pk_mul_f32 v[16:17], v[30:31], v[16:17] op_sel_hi:[1,0]
	s_waitcnt vmcnt(4)
	v_pk_mul_f32 v[36:37], v[36:37], v[8:9] op_sel_hi:[1,0]
	v_pk_mul_f32 v[34:35], v[34:35], v[8:9] op_sel_hi:[1,0]
	s_waitcnt vmcnt(3)
	v_pk_mul_f32 v[40:41], v[40:41], v[10:11] op_sel_hi:[1,0]
	v_pk_mul_f32 v[38:39], v[38:39], v[10:11] op_sel_hi:[1,0]
	s_waitcnt vmcnt(2)
	v_pk_mul_f32 v[56:57], v[56:57], v[10:11] op_sel:[0,1]
	v_pk_mul_f32 v[54:55], v[54:55], v[10:11] op_sel:[0,1]
	global_load_dwordx4 v[8:11], v[2:3], off nt
	v_mov_b32_e32 v2, v13
	s_waitcnt vmcnt(2)
	v_pk_mul_f32 v[20:21], v[20:21], v[14:15] op_sel_hi:[1,0]
	v_pk_mul_f32 v[14:15], v[18:19], v[14:15] op_sel_hi:[1,0]
	s_waitcnt vmcnt(1)
	v_pk_mul_f32 v[42:43], v[58:59], v[12:13] op_sel_hi:[1,0]
	v_pk_mul_f32 v[26:27], v[60:61], v[12:13] op_sel_hi:[1,0]
	v_lshl_add_u64 v[12:13], v[0:1], 0, 16
	v_cvt_pk_bf16_f32 v0, v14, v22
	v_cvt_pk_bf16_f32 v1, v16, v34
	v_lshl_add_u64 v[4:5], v[12:13], 0, v[4:5]
	s_waitcnt vmcnt(0)
	v_pk_mul_f32 v[8:9], v[8:9], v[2:3] op_sel_hi:[1,0]
	v_pk_mul_f32 v[10:11], v[10:11], v[2:3] op_sel_hi:[1,0]
	v_cvt_pk_bf16_f32 v2, v38, v54
	v_cvt_pk_bf16_f32 v3, v42, v8
	global_store_dwordx4 v[6:7], v[0:3], off offset:16
	s_nop 1
	v_cvt_pk_bf16_f32 v0, v15, v23
	v_cvt_pk_bf16_f32 v1, v17, v35
	v_cvt_pk_bf16_f32 v2, v39, v55
	v_cvt_pk_bf16_f32 v3, v43, v9
	global_store_dwordx4 v[6:7], v[0:3], off offset:2064
	s_nop 1
	v_cvt_pk_bf16_f32 v0, v20, v24
	v_cvt_pk_bf16_f32 v1, v32, v36
	v_cvt_pk_bf16_f32 v2, v40, v56
	v_cvt_pk_bf16_f32 v3, v26, v10
	global_store_dwordx4 v[4:5], v[0:3], off
	v_lshl_add_u64 v[4:5], v[12:13], 0, v[174:175]
	s_nop 0
	v_cvt_pk_bf16_f32 v0, v21, v25
	v_cvt_pk_bf16_f32 v1, v33, v37
	v_cvt_pk_bf16_f32 v2, v41, v57
	v_cvt_pk_bf16_f32 v3, v27, v11
	global_store_dwordx4 v[4:5], v[0:3], off

; __device__ __forceinline__ unsigned pk2(float lo, float hi) { f32x2 v = {lo, hi}; bf16x2_t b = __builtin_convertvector(v, bf16x2_t); return __builtin_bit_cast(unsigned, b); }
; __device__ __forceinline__ void p0_cvt_item(const float* W, int K, int N, bf16_t* WT, int row_off, const float* gain, int item, int lane) {
;     const int nblk = N / 256, kb = item / nblk, nb = item % nblk, k0 = 16 * kb, n0 = 256 * nb + 4 * lane;
; #pragma unroll
;     for (int kk = 0; kk < 16; kk += 8) {
;         f32x4 v[8];
; #pragma unroll
;         for (int j = 0; j < 8; ++j) { const float gk = gain ? gain[k0 + kk + j] : 1.f; v[j] = *(const f32x4*)(W + (size_t)(k0 + kk + j) * N + n0) * gk; }
; #pragma unroll
;         for (int c = 0; c < 4; ++c) { u32x4 o; o.x = pk2(v[0][c], v[1][c]); o.y = pk2(v[2][c], v[3][c]); o.z = pk2(v[4][c], v[5][c]); o.w = pk2(v[6][c], v[7][c]);
;             *(u32x4*)(WT + (size_t)(row_off + n0 + c) * K + k0 + kk) = o; }
; __device__ __forceinline__ void p0_phase(const Args& a, LAS unsigned char* lds, int G, int wg, int part, bool split) {
;     ...
;         if (r < I_SQ) { p0_cvt_item(a.in[7], DM, DM, (bf16_t*)(ws + WS_AWOUT), 0, nullptr, r, lane); continue; } r -= I_SQ;
.LBB0_1484:
	s_andn2_saveexec_b64 s[0:1], s[48:49]
	s_cbranch_execz .LBB0_1486
	v_add_u32_e32 v0, s9, v47
	s_movk_i32 s16, 0x300
	v_add_u32_e32 v0, 0xfffff000, v0
	v_and_or_b32 v6, v49, s16, v45
	v_and_b32_e32 v4, 0x3f0, v0
	v_lshlrev_b32_e32 v174, 2, v6
	v_readlane_b32 s38, v254, 12
	v_lshl_add_u64 v[2:3], s[82:83], 0, v[174:175]
	v_lshlrev_b32_e32 v174, 1, v4
	v_readlane_b32 s39, v254, 13
	s_mov_b32 s16, 0x9000
	s_nop 0
	v_lshl_add_u64 v[0:1], s[38:39], 0, v[174:175]
	v_lshlrev_b32_e32 v174, 12, v4
	v_lshl_add_u64 v[2:3], v[2:3], 0, v[174:175]
	v_add_co_u32_e32 v4, vcc, 0x1000, v2
	global_load_dwordx4 v[8:11], v[2:3], off nt
	s_nop 0
	v_addc_co_u32_e32 v5, vcc, 0, v3, vcc
	global_load_dwordx4 v[12:15], v[4:5], off nt
	v_add_co_u32_e32 v4, vcc, s23, v2
	v_lshlrev_b32_e32 v174, 11, v6
	s_nop 0
	v_addc_co_u32_e32 v5, vcc, 0, v3, vcc
	global_load_dwordx4 v[16:19], v[4:5], off nt
	v_add_co_u32_e32 v4, vcc, 0x3000, v2
	v_lshl_add_u64 v[6:7], v[0:1], 0, v[174:175]
	s_nop 0
	v_addc_co_u32_e32 v5, vcc, 0, v3, vcc
	global_load_dwordx4 v[20:23], v[4:5], off nt
	v_add_co_u32_e32 v4, vcc, s31, v2
	v_lshl_add_u64 v[42:43], v[0:1], 0, 16
	s_nop 0
	v_addc_co_u32_e32 v5, vcc, 0, v3, vcc
	global_load_dwordx4 v[24:27], v[4:5], off nt
	v_add_co_u32_e32 v4, vcc, 0x5000, v2
	s_waitcnt vmcnt(3)
	v_cvt_pk_bf16_f32 v54, v8, v12
	v_addc_co_u32_e32 v5, vcc, 0, v3, vcc
	global_load_dwordx4 v[30:33], v[4:5], off nt
	v_add_co_u32_e32 v4, vcc, s33, v2
	s_waitcnt vmcnt(2)
	v_cvt_pk_bf16_f32 v55, v16, v20
	v_addc_co_u32_e32 v5, vcc, 0, v3, vcc
	global_load_dwordx4 v[34:37], v[4:5], off nt
	v_add_co_u32_e32 v4, vcc, 0x7000, v2
	s_waitcnt vmcnt(1)
	v_cvt_pk_bf16_f32 v56, v24, v30
	v_addc_co_u32_e32 v5, vcc, 0, v3, vcc
	global_load_dwordx4 v[38:41], v[4:5], off nt
	v_or_b32_e32 v4, 0x1000, v174
	v_mov_b32_e32 v5, v175
	v_or_b32_e32 v174, 0x1800, v174
	s_waitcnt vmcnt(0)
	v_cvt_pk_bf16_f32 v57, v34, v38
	global_store_dwordx4 v[6:7], v[54:57], off
	s_nop 1
	v_cvt_pk_bf16_f32 v54, v9, v13
	v_cvt_pk_bf16_f32 v55, v17, v21
	v_cvt_pk_bf16_f32 v56, v25, v31
	v_cvt_pk_bf16_f32 v57, v35, v39
	global_store_dwordx4 v[6:7], v[54:57], off offset:2048
	v_lshl_add_u64 v[8:9], v[0:1], 0, v[4:5]
	v_lshl_add_u64 v[12:13], v[0:1], 0, v[174:175]
	v_cvt_pk_bf16_f32 v54, v10, v14
	v_cvt_pk_bf16_f32 v55, v18, v22
	v_cvt_pk_bf16_f32 v56, v26, v32
	v_cvt_pk_bf16_f32 v57, v36, v40
	global_store_dwordx4 v[8:9], v[54:57], off
	v_cvt_pk_bf16_f32 v8, v11, v15
	v_cvt_pk_bf16_f32 v9, v19, v23
	v_cvt_pk_bf16_f32 v10, v27, v33
	v_cvt_pk_bf16_f32 v11, v37, v41
	global_store_dwordx4 v[12:13], v[8:11], off
	v_add_co_u32_e32 v12, vcc, s16, v2
	s_mov_b32 s16, 0xb000
	s_nop 0
	v_addc_co_u32_e32 v13, vcc, 0, v3, vcc
	v_add_co_u32_e32 v20, vcc, s16, v2
	s_mov_b32 s16, 0xd000
	s_nop 0
	v_addc_co_u32_e32 v21, vcc, 0, v3, vcc
	v_add_co_u32_e32 v30, vcc, s16, v2
	s_mov_b32 s16, 0xf000
	s_nop 0
	v_addc_co_u32_e32 v31, vcc, 0, v3, vcc
	v_add_co_u32_e32 v2, vcc, s16, v2
	global_load_dwordx4 v[8:11], v[12:13], off offset:-4096 nt
	s_nop 0
	global_load_dwordx4 v[12:15], v[12:13], off nt
	v_addc_co_u32_e32 v3, vcc, 0, v3, vcc
	global_load_dwordx4 v[16:19], v[20:21], off offset:-4096 nt
	s_nop 0
	global_load_dwordx4 v[20:23], v[20:21], off nt
	s_nop 0
	global_load_dwordx4 v[24:27], v[30:31], off offset:-4096 nt
	s_nop 0
	global_load_dwordx4 v[30:33], v[30:31], off nt
	s_nop 0
	global_load_dwordx4 v[34:37], v[2:3], off offset:-4096 nt
	global_load_dwordx4 v[38:41], v[2:3], off nt
	v_lshl_add_u64 v[4:5], v[42:43], 0, v[4:5]
	s_waitcnt vmcnt(6)
	v_cvt_pk_bf16_f32 v0, v8, v12
	s_waitcnt vmcnt(4)
	v_cvt_pk_bf16_f32 v1, v16, v20
	s_waitcnt vmcnt(2)
	v_cvt_pk_bf16_f32 v2, v24, v30
	s_waitcnt vmcnt(0)
	v_cvt_pk_bf16_f32 v3, v34, v38
	global_store_dwordx4 v[6:7], v[0:3], off offset:16
	s_nop 1
	v_cvt_pk_bf16_f32 v0, v9, v13
	v_cvt_pk_bf16_f32 v1, v17, v21
	v_cvt_pk_bf16_f32 v2, v25, v31
	v_cvt_pk_bf16_f32 v3, v35, v39
	global_store_dwordx4 v[6:7], v[0:3], off offset:2064
	s_nop 1
	v_cvt_pk_bf16_f32 v0, v10, v14
	v_cvt_pk_bf16_f32 v1, v18, v22
	v_cvt_pk_bf16_f32 v2, v26, v32
	v_cvt_pk_bf16_f32 v3, v36, v40
	global_store_dwordx4 v[4:5], v[0:3], off
	v_lshl_add_u64 v[4:5], v[42:43], 0, v[174:175]
	s_nop 0
	v_cvt_pk_bf16_f32 v0, v11, v15
	v_cvt_pk_bf16_f32 v1, v19, v23
	v_cvt_pk_bf16_f32 v2, v27, v33
	v_cvt_pk_bf16_f32 v3, v37, v41
	global_store_dwordx4 v[4:5], v[0:3], off

; __device__ __forceinline__ void p0_cvt_item(const float* W, int K, int N, bf16_t* WT, int row_off, const float* gain, int item, int lane) {
;     const int nblk = N / 256, kb = item / nblk, nb = item % nblk, k0 = 16 * kb, n0 = 256 * nb + 4 * lane;
; #pragma unroll
;     for (int kk = 0; kk < 16; kk += 8) {
;         f32x4 v[8];
; #pragma unroll
;         for (int j = 0; j < 8; ++j) { const float gk = gain ? gain[k0 + kk + j] : 1.f; v[j] = *(const f32x4*)(W + (size_t)(k0 + kk + j) * N + n0) * gk; }
; #pragma unroll
; __device__ __forceinline__ void p0_phase(const Args& a, LAS unsigned char* lds, int G, int wg, int part, bool split) {
;     ...
;         if (r < 2 * I_AIN) { const int j = r / I_AIN; r -= j * I_AIN;
;             p0_cvt_item(a.in[4] + (size_t)j * DM * 4096, DM, 4096, (bf16_t*)(ws + WS_AWIN) + (size_t)j * 4096 * DM, 0, norm_mix + (3 * j) * DM, r, lane); continue; } r -= 2 * I_AIN;
.LBB0_1490:
	v_ashrrev_i32_e32 v1, 4, v1
	v_lshlrev_b32_e32 v1, 4, v1
	v_ashrrev_i32_e32 v37, 31, v36
	v_sub_u32_e32 v0, v0, v1
	v_lshlrev_b64 v[2:3], 24, v[36:37]
	v_lshl_or_b32 v40, v0, 8, v45
	v_lshl_add_u64 v[2:3], s[76:77], 0, v[2:3]
	v_ashrrev_i32_e32 v41, 31, v40
	v_lshl_add_u64 v[30:31], v[40:41], 2, v[2:3]
	v_lshlrev_b64 v[0:1], 14, v[32:33]
	v_lshl_add_u64 v[0:1], v[30:31], 0, v[0:1]
	global_load_dwordx4 v[0:3], v[0:1], off nt
	s_and_b64 vcc, exec, s[40:41]
	s_cbranch_vccnz .LBB0_1492
	global_load_dword v38, v[34:35], off offset:4
.LBB0_1492:
	v_or_b32_e32 v4, 1, v32
	v_ashrrev_i32_e32 v5, 31, v4
	v_lshlrev_b64 v[4:5], 14, v[4:5]
	v_lshl_add_u64 v[4:5], v[30:31], 0, v[4:5]
	global_load_dwordx4 v[4:7], v[4:5], off nt
	v_mov_b32_e32 v46, 1.0
	s_and_b64 vcc, exec, s[40:41]
	v_mov_b32_e32 v48, 1.0
	s_cbranch_vccnz .LBB0_1494
	global_load_dword v48, v[34:35], off offset:8
.LBB0_1494:
	v_or_b32_e32 v8, 2, v32
	v_ashrrev_i32_e32 v9, 31, v8
	v_lshlrev_b64 v[8:9], 14, v[8:9]
	v_lshl_add_u64 v[8:9], v[30:31], 0, v[8:9]
	global_load_dwordx4 v[8:11], v[8:9], off nt
	s_and_b64 vcc, exec, s[40:41]
	s_cbranch_vccnz .LBB0_1496
	global_load_dword v46, v[34:35], off offset:12
.LBB0_1496:
	v_or_b32_e32 v12, 3, v32
	v_ashrrev_i32_e32 v13, 31, v12
	v_lshlrev_b64 v[12:13], 14, v[12:13]
	v_lshl_add_u64 v[12:13], v[30:31], 0, v[12:13]
	global_load_dwordx4 v[12:15], v[12:13], off nt
	v_mov_b32_e32 v50, 1.0
	s_and_b64 vcc, exec, s[40:41]
	v_mov_b32_e32 v52, 1.0
	s_cbranch_vccnz .LBB0_1498
	global_load_dword v52, v[34:35], off offset:16
.LBB0_1498:
	v_or_b32_e32 v16, 4, v32
	v_ashrrev_i32_e32 v17, 31, v16
	v_lshlrev_b64 v[16:17], 14, v[16:17]
	v_lshl_add_u64 v[16:17], v[30:31], 0, v[16:17]
	global_load_dwordx4 v[16:19], v[16:17], off nt
	s_and_b64 vcc, exec, s[40:41]
	s_cbranch_vccnz .LBB0_1500
	global_load_dword v50, v[34:35], off offset:20
.LBB0_1500:
	v_or_b32_e32 v20, 5, v32
	v_ashrrev_i32_e32 v21, 31, v20
	v_lshlrev_b64 v[20:21], 14, v[20:21]
	v_lshl_add_u64 v[20:21], v[30:31], 0, v[20:21]
	global_load_dwordx4 v[20:23], v[20:21], off nt
	v_mov_b32_e32 v44, 1.0
	s_and_b64 vcc, exec, s[40:41]
	v_mov_b32_e32 v54, 1.0
	s_cbranch_vccnz .LBB0_1502
	global_load_dword v54, v[34:35], off offset:24
.LBB0_1502:
	v_or_b32_e32 v24, 6, v32
	v_ashrrev_i32_e32 v25, 31, v24
	v_lshlrev_b64 v[24:25], 14, v[24:25]
	v_lshl_add_u64 v[24:25], v[30:31], 0, v[24:25]
	global_load_dwordx4 v[24:27], v[24:25], off nt
	s_and_b64 vcc, exec, s[40:41]
	s_cbranch_vccnz .LBB0_1504
	global_load_dword v44, v[34:35], off offset:28
; __device__ __forceinline__ unsigned pk2(float lo, float hi) { f32x2 v = {lo, hi}; bf16x2_t b = __builtin_convertvector(v, bf16x2_t); return __builtin_bit_cast(unsigned, b); }
; __device__ __forceinline__ void p0_cvt_item(const float* W, int K, int N, bf16_t* WT, int row_off, const float* gain, int item, int lane) {
;     const int nblk = N / 256, kb = item / nblk, nb = item % nblk, k0 = 16 * kb, n0 = 256 * nb + 4 * lane;
; #pragma unroll
;     for (int kk = 0; kk < 16; kk += 8) {
;         f32x4 v[8];
; #pragma unroll
;         for (int j = 0; j < 8; ++j) { const float gk = gain ? gain[k0 + kk + j] : 1.f; v[j] = *(const f32x4*)(W + (size_t)(k0 + kk + j) * N + n0) * gk; }
; #pragma unroll
;         for (int c = 0; c < 4; ++c) { u32x4 o; o.x = pk2(v[0][c], v[1][c]); o.y = pk2(v[2][c], v[3][c]); o.z = pk2(v[4][c], v[5][c]); o.w = pk2(v[6][c], v[7][c]);
;             *(u32x4*)(WT + (size_t)(row_off + n0 + c) * K + k0 + kk) = o; }
; __device__ __forceinline__ void p0_phase(const Args& a, LAS unsigned char* lds, int G, int wg, int part, bool split) {
;     ...
;         if (r < 2 * I_AIN) { const int j = r / I_AIN; r -= j * I_AIN;
;             p0_cvt_item(a.in[4] + (size_t)j * DM * 4096, DM, 4096, (bf16_t*)(ws + WS_AWIN) + (size_t)j * 4096 * DM, 0, norm_mix + (3 * j) * DM, r, lane); continue; } r -= 2 * I_AIN;
.LBB0_1504:
	s_waitcnt vmcnt(0)
	v_pk_mul_f32 v[26:27], v[26:27], v[54:55] op_sel_hi:[1,0]
	v_pk_mul_f32 v[24:25], v[24:25], v[54:55] op_sel_hi:[1,0]
	v_or_b32_e32 v54, 7, v32
	v_ashrrev_i32_e32 v55, 31, v54
	v_pk_mul_f32 v[2:3], v[2:3], v[42:43] op_sel_hi:[1,0]
	v_pk_mul_f32 v[42:43], v[0:1], v[42:43] op_sel_hi:[1,0]
	v_lshlrev_b64 v[0:1], 23, v[36:37]
	v_lshlrev_b64 v[36:37], 14, v[54:55]
	v_lshl_add_u64 v[36:37], v[30:31], 0, v[36:37]
	v_pk_mul_f32 v[6:7], v[6:7], v[38:39] op_sel_hi:[1,0]
	v_pk_mul_f32 v[4:5], v[4:5], v[38:39] op_sel_hi:[1,0]
	global_load_dwordx4 v[36:39], v[36:37], off nt
	v_readlane_b32 s38, v252, 38
	v_readlane_b32 s39, v252, 39
	v_pk_mul_f32 v[20:21], v[20:21], v[50:51] op_sel_hi:[1,0]
	v_pk_mul_f32 v[16:17], v[16:17], v[52:53] op_sel_hi:[1,0]
	v_lshl_add_u64 v[0:1], s[38:39], 0, v[0:1]
	v_pk_mul_f32 v[12:13], v[12:13], v[46:47] op_sel_hi:[1,0]
	v_pk_mul_f32 v[8:9], v[8:9], v[48:49] op_sel_hi:[1,0]
	v_lshl_add_u64 v[0:1], v[32:33], 1, v[0:1]
	v_cvt_pk_bf16_f32 v54, v42, v4
	v_cvt_pk_bf16_f32 v55, v8, v12
	v_cvt_pk_bf16_f32 v56, v16, v20
	v_or_b32_e32 v4, 1, v40
	v_pk_mul_f32 v[22:23], v[22:23], v[50:51] op_sel_hi:[1,0]
	v_pk_mul_f32 v[18:19], v[18:19], v[52:53] op_sel_hi:[1,0]
	v_pk_mul_f32 v[14:15], v[14:15], v[46:47] op_sel_hi:[1,0]
	v_pk_mul_f32 v[10:11], v[10:11], v[48:49] op_sel_hi:[1,0]
	s_and_b64 vcc, exec, s[40:41]
	v_mov_b32_e32 v46, 1.0
	s_waitcnt vmcnt(0)
	v_pk_mul_f32 v[58:59], v[38:39], v[44:45] op_sel_hi:[1,0]
	v_pk_mul_f32 v[38:39], v[36:37], v[44:45] op_sel_hi:[1,0]
	v_lshlrev_b64 v[36:37], 11, v[40:41]
	v_cvt_pk_bf16_f32 v57, v24, v38
	v_lshl_add_u64 v[36:37], v[0:1], 0, v[36:37]
	global_store_dwordx4 v[36:37], v[54:57], off
	v_mov_b32_e32 v44, 1.0
	s_nop 0
	v_cvt_pk_bf16_f32 v54, v43, v5
	v_ashrrev_i32_e32 v5, 31, v4
	v_lshlrev_b64 v[4:5], 11, v[4:5]
	v_cvt_pk_bf16_f32 v55, v9, v13
	v_cvt_pk_bf16_f32 v56, v17, v21
	v_cvt_pk_bf16_f32 v57, v25, v39
	v_lshl_add_u64 v[38:39], v[0:1], 0, v[4:5]
	global_store_dwordx4 v[38:39], v[54:57], off
	v_or_b32_e32 v4, 2, v40
	v_ashrrev_i32_e32 v5, 31, v4
	v_cvt_pk_bf16_f32 v54, v2, v6
	v_or_b32_e32 v6, 3, v40
	v_cvt_pk_bf16_f32 v2, v3, v7
	v_ashrrev_i32_e32 v7, 31, v6
	v_lshlrev_b64 v[4:5], 11, v[4:5]
	v_lshlrev_b64 v[6:7], 11, v[6:7]
	v_cvt_pk_bf16_f32 v55, v10, v14
	v_cvt_pk_bf16_f32 v56, v18, v22
	v_cvt_pk_bf16_f32 v57, v26, v58
	v_lshl_add_u64 v[42:43], v[0:1], 0, v[4:5]
	v_cvt_pk_bf16_f32 v3, v11, v15
	v_cvt_pk_bf16_f32 v4, v19, v23
	v_cvt_pk_bf16_f32 v5, v27, v59
	v_lshl_add_u64 v[40:41], v[0:1], 0, v[6:7]
	global_store_dwordx4 v[42:43], v[54:57], off
	global_store_dwordx4 v[40:41], v[2:5], off
	s_cbranch_vccnz .LBB0_1506
	global_load_dword v46, v[34:35], off offset:32
.LBB0_1506:
	v_or_b32_e32 v0, 8, v32
	v_ashrrev_i32_e32 v1, 31, v0
	v_lshlrev_b64 v[0:1], 14, v[0:1]
	v_lshl_add_u64 v[0:1], v[30:31], 0, v[0:1]
	global_load_dwordx4 v[0:3], v[0:1], off nt
	s_and_b64 vcc, exec, s[40:41]
	s_cbranch_vccnz .LBB0_1508
	global_load_dword v44, v[34:35], off offset:36
.LBB0_1508:
	v_or_b32_e32 v4, 9, v32
	v_ashrrev_i32_e32 v5, 31, v4
	v_lshlrev_b64 v[4:5], 14, v[4:5]
	v_lshl_add_u64 v[4:5], v[30:31], 0, v[4:5]
	global_load_dwordx4 v[4:7], v[4:5], off nt
	v_mov_b32_e32 v48, 1.0
	s_and_b64 vcc, exec, s[40:41]
	v_mov_b32_e32 v50, 1.0
	s_cbranch_vccnz .LBB0_1510
	global_load_dword v50, v[34:35], off offset:40
.LBB0_1510:
	v_or_b32_e32 v8, 10, v32
	v_ashrrev_i32_e32 v9, 31, v8
	v_lshlrev_b64 v[8:9], 14, v[8:9]
	v_lshl_add_u64 v[8:9], v[30:31], 0, v[8:9]
	global_load_dwordx4 v[8:11], v[8:9], off nt
	s_and_b64 vcc, exec, s[40:41]
	s_cbranch_vccnz .LBB0_1512
	global_load_dword v48, v[34:35], off offset:44
.LBB0_1512:
	v_or_b32_e32 v12, 11, v32
	v_ashrrev_i32_e32 v13, 31, v12
	v_lshlrev_b64 v[12:13], 14, v[12:13]
	v_lshl_add_u64 v[12:13], v[30:31], 0, v[12:13]
	global_load_dwordx4 v[12:15], v[12:13], off nt
	v_mov_b32_e32 v54, 1.0
	s_and_b64 vcc, exec, s[40:41]
	v_mov_b32_e32 v56, 1.0
	s_cbranch_vccnz .LBB0_1514
	global_load_dword v56, v[34:35], off offset:48
.LBB0_1514:
	v_or_b32_e32 v16, 12, v32
	v_ashrrev_i32_e32 v17, 31, v16
	v_lshlrev_b64 v[16:17], 14, v[16:17]
	v_lshl_add_u64 v[16:17], v[30:31], 0, v[16:17]
	global_load_dwordx4 v[16:19], v[16:17], off nt
	s_and_b64 vcc, exec, s[40:41]
	s_cbranch_vccnz .LBB0_1516
	global_load_dword v54, v[34:35], off offset:52
.LBB0_1516:
	v_or_b32_e32 v20, 13, v32
	v_ashrrev_i32_e32 v21, 31, v20
	v_lshlrev_b64 v[20:21], 14, v[20:21]
	v_lshl_add_u64 v[20:21], v[30:31], 0, v[20:21]
	global_load_dwordx4 v[20:23], v[20:21], off nt
	v_mov_b32_e32 v52, 1.0
	s_and_b64 vcc, exec, s[40:41]
	v_mov_b32_e32 v58, 1.0
	s_cbranch_vccnz .LBB0_1518
	global_load_dword v58, v[34:35], off offset:56
.LBB0_1518:
	v_or_b32_e32 v24, 14, v32
	v_ashrrev_i32_e32 v25, 31, v24
	v_lshlrev_b64 v[24:25], 14, v[24:25]
	v_lshl_add_u64 v[24:25], v[30:31], 0, v[24:25]
	global_load_dwordx4 v[24:27], v[24:25], off nt
	s_and_b64 vcc, exec, s[40:41]
	s_cbranch_vccnz .LBB0_1419
	global_load_dword v52, v[34:35], off offset:60
	s_branch .LBB0_1419
